# v44
# baseline (speedup 1.0000x reference)
; #define PG8_STAGE(bufoff, gbase, voff) do { _Pragma("unroll") for (int _i = 0; _i < 2; ++_i) \
;         __builtin_amdgcn_global_load_lds((const unsigned*)((const char*)(gbase) + (voff)[_i]), (PG8_LAS unsigned*)(lds + (bufoff) + ldsw + _i * 8192), 16, 0, 0); } while (0)
; #define PG8_LDA(dst, b, h) do { _Pragma("unroll") for (int m = 0; m < 4; ++m) _Pragma("unroll") for (int k = 0; k < 2; ++k) dst[m][k] = *(const PG8_LAS bf16x8*)(lds + PG8_SA(b, h) + aoff + m * 2048 + k * 1024); } while (0)
; #define PG8_LDB(dst, b, h) do { _Pragma("unroll") for (int n = 0; n < 2; ++n) _Pragma("unroll") for (int k = 0; k < 2; ++k) dst[n][k] = *(const PG8_LAS bf16x8*)(lds + PG8_SB(b, h) + boff + n * 2048 + k * 1024); } while (0)
; #define PG8_MMA(ai, bj, At, Bt) do { __builtin_amdgcn_s_setprio(1); _Pragma("unroll") for (int m = 0; m < 4; ++m) _Pragma("unroll") for (int n = 0; n < 2; ++n) _Pragma("unroll") for (int k = 0; k < 2; ++k) \
;         acc[ai][bj][m][n] = __builtin_amdgcn_mfma_f32_16x16x32_bf16(Bt[n][k], At[m][k], acc[ai][bj][m][n], 0, 0, 0); __builtin_amdgcn_s_setprio(0); } while (0)
; #define PG8_BAR __builtin_amdgcn_s_barrier()
; template <class Epi, class Sched, bool ALIGN_EPI = false, bool SP2 = false>
; __device__ __forceinline__ void gemm_phase(PG8_LAS unsigned char* lds, const Gemm g, const Sched& S, const Epi& E) {
;     ...
;         const bool has_next = S.next(ui + 1, nxt);
;         const char* nA = has_next ? (const char*)g.A + (size_t)nxt.pm * tstep : cA; const char* nB = has_next ? (const char*)g.Bt + (size_t)nxt.pn * tstep : cB;
;         for (int t = 0; t < nt; t += 2) {
;             const bool last = (t == nt - 2);
;             const char* a1 = cA + (size_t)(t + 1) * kstep;
;             const char* a2 = last ? nA : cA + (size_t)(t + 2) * kstep; const char* b2 = last ? nB : cB + (size_t)(t + 2) * kstep;
;             const char* a3 = a2 + kstep; const char* b3 = b2 + kstep;
;             if (last && has_next) S.a_ready(nxt);
;             if constexpr (SP2) {
;             PG8_LDB(B0, 0, 0); PG8_LDB(B1, 0, 1); PG8_SCHED; PG8_LDA(At, 0, 0); PG8_STAGE(PG8_SA(1, 1), a1 + hstep, voffA);
;             PG8_WAIT_V(8); PG8_WAIT_L(0); PG8_BAR; PG8_MMA(0, 0, At, B0); PG8_MMA(0, 1, At, B1); PG8_BAR; PG8_SCHED;
;             PG8_LDA(At, 0, 1); PG8_STAGE(PG8_SB(0, 0), b2, voffB); PG8_STAGE(PG8_SB(0, 1), b2 + hstep, voffB); PG8_STAGE(PG8_SA(0, 0), a2, voffA);
.LBB0_168:
	s_ashr_i32 s29, s28, 31
	v_cmp_lt_i64_e32 vcc, s[30:31], v[140:141]
	s_lshl_b64 s[30:31], s[28:29], 20
	s_add_u32 s30, s6, s30
	s_addc_u32 s31, s7, s31
	s_and_b64 s[34:35], vcc, exec
	s_cselect_b32 s29, s31, s39
	s_cselect_b32 s57, s30, s38
	s_ashr_i32 s27, s26, 31
	s_lshl_b64 s[34:35], s[26:27], 20
	s_add_u32 s34, s22, s34
	s_addc_u32 s35, s23, s35
	s_and_b64 s[42:43], vcc, exec
	s_cselect_b32 s27, s35, s41
	s_cselect_b32 s58, s34, s40
	s_add_u32 s38, s38, 0x80080
	s_addc_u32 s39, s39, 0
	s_add_u32 s59, s40, 0x100
	s_addc_u32 s60, s41, 0
	s_mov_b32 s61, -2
	ds_read_b128 v[152:155], v149
	ds_read_b128 v[156:159], v149 offset:1024
	ds_read_b128 v[160:163], v149 offset:2048
	ds_read_b128 v[164:167], v149 offset:3072
	ds_read_b128 v[168:171], v150
	ds_read_b128 v[172:175], v150 offset:1024
	ds_read_b128 v[176:179], v150 offset:2048
	ds_read_b128 v[180:183], v150 offset:3072
	s_add_u32 s40, s38, 0xfff80080
	s_addc_u32 s41, s39, -1
	s_cmp_eq_u32 s61, 28
	s_cselect_b32 s43, s29, s41
	s_cselect_b32 s42, s57, s40
	s_cselect_b32 s41, s27, s60
	s_cselect_b32 s40, s58, s59
	s_add_i32 m0, s37, 0xc000
	ds_read_b128 v[184:187], v151
	ds_read_b128 v[188:191], v151 offset:1024
	ds_read_b128 v[192:195], v151 offset:2048
	ds_read_b128 v[196:199], v151 offset:3072
	ds_read_b128 v[200:203], v151 offset:4096
	ds_read_b128 v[204:207], v151 offset:5120
	ds_read_b128 v[208:211], v151 offset:6144
	ds_read_b128 v[214:217], v151 offset:7168
	global_load_lds_dwordx4 v136, s[38:39]
	s_add_i32 m0, s37, 0xe000
	s_nop 0
	global_load_lds_dwordx4 v138, s[38:39]
	s_waitcnt vmcnt(8)
	s_waitcnt lgkmcnt(0)
	s_barrier
	v_mfma_f32_16x16x32_bf16 v[124:127], v[152:155], v[184:187], 0
	v_mfma_f32_16x16x32_bf16 v[120:123], v[160:163], v[184:187], 0
	v_mfma_f32_16x16x32_bf16 v[108:111], v[152:155], v[192:195], 0
	v_mfma_f32_16x16x32_bf16 v[104:107], v[160:163], v[192:195], 0
	v_mfma_f32_16x16x32_bf16 v[92:95], v[152:155], v[200:203], 0
	v_mfma_f32_16x16x32_bf16 v[88:91], v[160:163], v[200:203], 0
	v_mfma_f32_16x16x32_bf16 v[76:79], v[152:155], v[208:211], 0
	v_mfma_f32_16x16x32_bf16 v[72:75], v[160:163], v[208:211], 0
	v_mfma_f32_16x16x32_bf16 v[124:127], v[156:159], v[188:191], v[124:127]
	v_mfma_f32_16x16x32_bf16 v[120:123], v[164:167], v[188:191], v[120:123]
	v_mfma_f32_16x16x32_bf16 v[108:111], v[156:159], v[196:199], v[108:111]
	v_mfma_f32_16x16x32_bf16 v[104:107], v[164:167], v[196:199], v[104:107]
	v_mfma_f32_16x16x32_bf16 v[92:95], v[156:159], v[204:207], v[92:95]
	v_mfma_f32_16x16x32_bf16 v[88:91], v[164:167], v[204:207], v[88:91]
	v_mfma_f32_16x16x32_bf16 v[76:79], v[156:159], v[214:217], v[76:79]
	v_mfma_f32_16x16x32_bf16 v[72:75], v[164:167], v[214:217], v[72:75]
	v_mfma_f32_16x16x32_bf16 v[116:119], v[168:171], v[184:187], 0
	v_mfma_f32_16x16x32_bf16 v[112:115], v[176:179], v[184:187], 0
	v_mfma_f32_16x16x32_bf16 v[100:103], v[168:171], v[192:195], 0
	v_mfma_f32_16x16x32_bf16 v[96:99], v[176:179], v[192:195], 0
	v_mfma_f32_16x16x32_bf16 v[84:87], v[168:171], v[200:203], 0
	v_mfma_f32_16x16x32_bf16 v[80:83], v[176:179], v[200:203], 0
	v_mfma_f32_16x16x32_bf16 v[68:71], v[168:171], v[208:211], 0
	v_mfma_f32_16x16x32_bf16 v[64:67], v[176:179], v[208:211], 0
	v_mfma_f32_16x16x32_bf16 v[116:119], v[172:175], v[188:191], v[116:119]
	v_mfma_f32_16x16x32_bf16 v[112:115], v[180:183], v[188:191], v[112:115]
	v_mfma_f32_16x16x32_bf16 v[100:103], v[172:175], v[196:199], v[100:103]
	v_mfma_f32_16x16x32_bf16 v[96:99], v[180:183], v[196:199], v[96:99]
	v_mfma_f32_16x16x32_bf16 v[84:87], v[172:175], v[204:207], v[84:87]
	v_mfma_f32_16x16x32_bf16 v[80:83], v[180:183], v[204:207], v[80:83]
	v_mfma_f32_16x16x32_bf16 v[68:71], v[172:175], v[214:217], v[68:71]
	v_mfma_f32_16x16x32_bf16 v[64:67], v[180:183], v[214:217], v[64:67]
	s_barrier
	s_add_i32 s62, s53, s24
	s_mov_b32 m0, s62
	ds_read_b128 v[184:187], v151 offset:16384
	ds_read_b128 v[188:191], v151 offset:17408
	ds_read_b128 v[192:195], v151 offset:18432
	ds_read_b128 v[196:199], v151 offset:19456
	ds_read_b128 v[200:203], v151 offset:20480
	ds_read_b128 v[204:207], v151 offset:21504
	ds_read_b128 v[208:211], v151 offset:22528
	ds_read_b128 v[214:217], v151 offset:23552
	global_load_lds_dwordx4 v132, s[40:41]
	s_add_i32 m0, s62, 0x2000
	s_add_u32 s62, s40, 0x80000
	s_addc_u32 s63, s41, 0
	s_add_i32 s64, s54, s24
	global_load_lds_dwordx4 v128, s[40:41]
	s_mov_b32 m0, s64
	s_nop 0
	global_load_lds_dwordx4 v132, s[62:63]
	s_add_i32 m0, s64, 0x2000
	s_nop 0
	global_load_lds_dwordx4 v128, s[62:63]
	s_mov_b32 m0, s37
	s_nop 0
	global_load_lds_dwordx4 v134, s[42:43]
	s_mov_b32 m0, s45
	s_nop 0
	global_load_lds_dwordx4 v130, s[42:43]
	s_waitcnt vmcnt(8)
	s_waitcnt lgkmcnt(0)
	s_barrier
; #define PG8_STAGE(bufoff, gbase, voff) do { _Pragma("unroll") for (int _i = 0; _i < 2; ++_i) \
;         __builtin_amdgcn_global_load_lds((const unsigned*)((const char*)(gbase) + (voff)[_i]), (PG8_LAS unsigned*)(lds + (bufoff) + ldsw + _i * 8192), 16, 0, 0); } while (0)
; #define PG8_LDA(dst, b, h) do { _Pragma("unroll") for (int m = 0; m < 4; ++m) _Pragma("unroll") for (int k = 0; k < 2; ++k) dst[m][k] = *(const PG8_LAS bf16x8*)(lds + PG8_SA(b, h) + aoff + m * 2048 + k * 1024); } while (0)
; #define PG8_LDB(dst, b, h) do { _Pragma("unroll") for (int n = 0; n < 2; ++n) _Pragma("unroll") for (int k = 0; k < 2; ++k) dst[n][k] = *(const PG8_LAS bf16x8*)(lds + PG8_SB(b, h) + boff + n * 2048 + k * 1024); } while (0)
; #define PG8_MMA(ai, bj, At, Bt) do { __builtin_amdgcn_s_setprio(1); _Pragma("unroll") for (int m = 0; m < 4; ++m) _Pragma("unroll") for (int n = 0; n < 2; ++n) _Pragma("unroll") for (int k = 0; k < 2; ++k) \
;         acc[ai][bj][m][n] = __builtin_amdgcn_mfma_f32_16x16x32_bf16(Bt[n][k], At[m][k], acc[ai][bj][m][n], 0, 0, 0); __builtin_amdgcn_s_setprio(0); } while (0)
; #define PG8_WAIT_V(n) asm volatile("s_waitcnt vmcnt(" #n ")" ::: "memory")
; #define PG8_WAIT_L(n) asm volatile("s_waitcnt lgkmcnt(" #n ")" ::: "memory")
; #define PG8_BAR __builtin_amdgcn_s_barrier()
; #define PG8_SCHED __builtin_amdgcn_sched_barrier(0)
; template <class Epi, class Sched, bool ALIGN_EPI = false, bool SP2 = false>
; __device__ __forceinline__ void gemm_phase(PG8_LAS unsigned char* lds, const Gemm g, const Sched& S, const Epi& E) {
;     ...
;             PG8_WAIT_V(8); PG8_WAIT_L(0); PG8_BAR; PG8_MMA(1, 0, At, B0); PG8_MMA(1, 1, At, B1); PG8_BAR; PG8_SCHED;
;             PG8_LDB(B0, 1, 0); PG8_LDB(B1, 1, 1); PG8_SCHED; PG8_LDA(At, 1, 0); PG8_STAGE(PG8_SA(0, 1), a2 + hstep, voffA);
;             PG8_WAIT_V(8); PG8_WAIT_L(0); PG8_BAR; PG8_MMA(0, 0, At, B0); PG8_MMA(0, 1, At, B1); PG8_BAR; PG8_SCHED;
	v_mfma_f32_16x16x32_bf16 v[60:63], v[152:155], v[184:187], 0
	v_mfma_f32_16x16x32_bf16 v[56:59], v[160:163], v[184:187], 0
	v_mfma_f32_16x16x32_bf16 v[44:47], v[152:155], v[192:195], 0
	v_mfma_f32_16x16x32_bf16 v[40:43], v[160:163], v[192:195], 0
	v_mfma_f32_16x16x32_bf16 v[28:31], v[152:155], v[200:203], 0
	v_mfma_f32_16x16x32_bf16 v[24:27], v[160:163], v[200:203], 0
	v_mfma_f32_16x16x32_bf16 v[12:15], v[152:155], v[208:211], 0
	v_mfma_f32_16x16x32_bf16 v[8:11], v[160:163], v[208:211], 0
	v_mfma_f32_16x16x32_bf16 v[60:63], v[156:159], v[188:191], v[60:63]
	v_mfma_f32_16x16x32_bf16 v[56:59], v[164:167], v[188:191], v[56:59]
	v_mfma_f32_16x16x32_bf16 v[44:47], v[156:159], v[196:199], v[44:47]
	v_mfma_f32_16x16x32_bf16 v[40:43], v[164:167], v[196:199], v[40:43]
	v_mfma_f32_16x16x32_bf16 v[28:31], v[156:159], v[204:207], v[28:31]
	v_mfma_f32_16x16x32_bf16 v[24:27], v[164:167], v[204:207], v[24:27]
	v_mfma_f32_16x16x32_bf16 v[12:15], v[156:159], v[214:217], v[12:15]
	v_mfma_f32_16x16x32_bf16 v[8:11], v[164:167], v[214:217], v[8:11]
	v_mfma_f32_16x16x32_bf16 v[52:55], v[168:171], v[184:187], 0
	v_mfma_f32_16x16x32_bf16 v[48:51], v[176:179], v[184:187], 0
	v_mfma_f32_16x16x32_bf16 v[36:39], v[168:171], v[192:195], 0
	v_mfma_f32_16x16x32_bf16 v[32:35], v[176:179], v[192:195], 0
	v_mfma_f32_16x16x32_bf16 v[20:23], v[168:171], v[200:203], 0
	v_mfma_f32_16x16x32_bf16 v[16:19], v[176:179], v[200:203], 0
	v_mfma_f32_16x16x32_bf16 v[4:7], v[168:171], v[208:211], 0
	v_mfma_f32_16x16x32_bf16 v[0:3], v[176:179], v[208:211], 0
	v_mfma_f32_16x16x32_bf16 v[52:55], v[172:175], v[188:191], v[52:55]
	v_mfma_f32_16x16x32_bf16 v[48:51], v[180:183], v[188:191], v[48:51]
	v_mfma_f32_16x16x32_bf16 v[36:39], v[172:175], v[196:199], v[36:39]
	v_mfma_f32_16x16x32_bf16 v[32:35], v[180:183], v[196:199], v[32:35]
	v_mfma_f32_16x16x32_bf16 v[20:23], v[172:175], v[204:207], v[20:23]
	v_mfma_f32_16x16x32_bf16 v[16:19], v[180:183], v[204:207], v[16:19]
	v_mfma_f32_16x16x32_bf16 v[4:7], v[172:175], v[214:217], v[4:7]
	v_mfma_f32_16x16x32_bf16 v[0:3], v[180:183], v[214:217], v[0:3]
	s_barrier
	s_add_i32 s62, 0, 0x18000
	s_add_i32 s63, 0, 0x1c000
	v_add_u32_e32 v164, s62, v147
	v_add_u32_e32 v180, s63, v147
	ds_read_b128 v[152:155], v164
	ds_read_b128 v[156:159], v164 offset:1024
	ds_read_b128 v[160:163], v164 offset:2048
	ds_read_b128 v[164:167], v164 offset:3072
	ds_read_b128 v[168:171], v180
	ds_read_b128 v[172:175], v180 offset:1024
	ds_read_b128 v[176:179], v180 offset:2048
	ds_read_b128 v[180:183], v180 offset:3072
	s_add_u32 s84, s42, 0x80
	s_addc_u32 s85, s43, 0
	s_add_u32 s42, s42, 0x80000
	s_addc_u32 s43, s43, 0
	s_mov_b32 m0, s46
	ds_read_b128 v[184:187], v151 offset:32768
	ds_read_b128 v[188:191], v151 offset:33792
	ds_read_b128 v[192:195], v151 offset:34816
	ds_read_b128 v[196:199], v151 offset:35840
	ds_read_b128 v[200:203], v151 offset:36864
	ds_read_b128 v[204:207], v151 offset:37888
	ds_read_b128 v[208:211], v151 offset:38912
	ds_read_b128 v[214:217], v151 offset:39936
	global_load_lds_dwordx4 v134, s[42:43]
	s_mov_b32 m0, s47
	s_nop 0
	global_load_lds_dwordx4 v130, s[42:43]
	s_waitcnt vmcnt(8)
	s_waitcnt lgkmcnt(0)
	s_barrier
	v_mfma_f32_16x16x32_bf16 v[124:127], v[152:155], v[184:187], v[124:127]
	v_mfma_f32_16x16x32_bf16 v[120:123], v[160:163], v[184:187], v[120:123]
	v_mfma_f32_16x16x32_bf16 v[108:111], v[152:155], v[192:195], v[108:111]
	v_mfma_f32_16x16x32_bf16 v[104:107], v[160:163], v[192:195], v[104:107]
	v_mfma_f32_16x16x32_bf16 v[92:95], v[152:155], v[200:203], v[92:95]
	v_mfma_f32_16x16x32_bf16 v[88:91], v[160:163], v[200:203], v[88:91]
	v_mfma_f32_16x16x32_bf16 v[76:79], v[152:155], v[208:211], v[76:79]
	v_mfma_f32_16x16x32_bf16 v[72:75], v[160:163], v[208:211], v[72:75]
	v_mfma_f32_16x16x32_bf16 v[124:127], v[156:159], v[188:191], v[124:127]
	v_mfma_f32_16x16x32_bf16 v[120:123], v[164:167], v[188:191], v[120:123]
	v_mfma_f32_16x16x32_bf16 v[108:111], v[156:159], v[196:199], v[108:111]
	v_mfma_f32_16x16x32_bf16 v[104:107], v[164:167], v[196:199], v[104:107]
	v_mfma_f32_16x16x32_bf16 v[92:95], v[156:159], v[204:207], v[92:95]
	v_mfma_f32_16x16x32_bf16 v[88:91], v[164:167], v[204:207], v[88:91]
	v_mfma_f32_16x16x32_bf16 v[76:79], v[156:159], v[214:217], v[76:79]
	v_mfma_f32_16x16x32_bf16 v[72:75], v[164:167], v[214:217], v[72:75]
	v_mfma_f32_16x16x32_bf16 v[116:119], v[168:171], v[184:187], v[116:119]
	v_mfma_f32_16x16x32_bf16 v[112:115], v[176:179], v[184:187], v[112:115]
	v_mfma_f32_16x16x32_bf16 v[100:103], v[168:171], v[192:195], v[100:103]
	v_mfma_f32_16x16x32_bf16 v[96:99], v[176:179], v[192:195], v[96:99]
	v_mfma_f32_16x16x32_bf16 v[84:87], v[168:171], v[200:203], v[84:87]
	v_mfma_f32_16x16x32_bf16 v[80:83], v[176:179], v[200:203], v[80:83]
	v_mfma_f32_16x16x32_bf16 v[68:71], v[168:171], v[208:211], v[68:71]
	v_mfma_f32_16x16x32_bf16 v[64:67], v[176:179], v[208:211], v[64:67]
	v_mfma_f32_16x16x32_bf16 v[116:119], v[172:175], v[188:191], v[116:119]
	v_mfma_f32_16x16x32_bf16 v[112:115], v[180:183], v[188:191], v[112:115]
	v_mfma_f32_16x16x32_bf16 v[100:103], v[172:175], v[196:199], v[100:103]
	v_mfma_f32_16x16x32_bf16 v[96:99], v[180:183], v[196:199], v[96:99]
	v_mfma_f32_16x16x32_bf16 v[84:87], v[172:175], v[204:207], v[84:87]
	v_mfma_f32_16x16x32_bf16 v[80:83], v[180:183], v[204:207], v[80:83]
	v_mfma_f32_16x16x32_bf16 v[68:71], v[172:175], v[214:217], v[68:71]
	v_mfma_f32_16x16x32_bf16 v[64:67], v[180:183], v[214:217], v[64:67]
	s_barrier
; #define PG8_STAGE(bufoff, gbase, voff) do { _Pragma("unroll") for (int _i = 0; _i < 2; ++_i) \
;         __builtin_amdgcn_global_load_lds((const unsigned*)((const char*)(gbase) + (voff)[_i]), (PG8_LAS unsigned*)(lds + (bufoff) + ldsw + _i * 8192), 16, 0, 0); } while (0)
; #define PG8_LDA(dst, b, h) do { _Pragma("unroll") for (int m = 0; m < 4; ++m) _Pragma("unroll") for (int k = 0; k < 2; ++k) dst[m][k] = *(const PG8_LAS bf16x8*)(lds + PG8_SA(b, h) + aoff + m * 2048 + k * 1024); } while (0)
; #define PG8_MMA(ai, bj, At, Bt) do { __builtin_amdgcn_s_setprio(1); _Pragma("unroll") for (int m = 0; m < 4; ++m) _Pragma("unroll") for (int n = 0; n < 2; ++n) _Pragma("unroll") for (int k = 0; k < 2; ++k) \
;         acc[ai][bj][m][n] = __builtin_amdgcn_mfma_f32_16x16x32_bf16(Bt[n][k], At[m][k], acc[ai][bj][m][n], 0, 0, 0); __builtin_amdgcn_s_setprio(0); } while (0)
; #define PG8_WAIT_V(n) asm volatile("s_waitcnt vmcnt(" #n ")" ::: "memory")
; #define PG8_WAIT_L(n) asm volatile("s_waitcnt lgkmcnt(" #n ")" ::: "memory")
; #define PG8_BAR __builtin_amdgcn_s_barrier()
; #define PG8_SCHED __builtin_amdgcn_sched_barrier(0)
; template <class Epi, class Sched, bool ALIGN_EPI = false, bool SP2 = false>
; __device__ __forceinline__ void gemm_phase(PG8_LAS unsigned char* lds, const Gemm g, const Sched& S, const Epi& E) {
;     ...
;         for (int t = 0; t < nt; t += 2) {
;     ...
;             PG8_LDA(At, 1, 1); PG8_STAGE(PG8_SB(1, 0), b3, voffB); PG8_STAGE(PG8_SB(1, 1), b3 + hstep, voffB); PG8_STAGE(PG8_SA(1, 0), a3, voffA);
;             PG8_WAIT_V(8); PG8_WAIT_L(0); PG8_BAR; PG8_MMA(1, 0, At, B0); PG8_MMA(1, 1, At, B1); PG8_BAR; PG8_SCHED;
	s_add_i32 s42, s62, s24
	s_add_u32 s86, s40, 0x80
	s_addc_u32 s87, s41, 0
	s_mov_b32 m0, s42
	ds_read_b128 v[184:187], v151 offset:49152
	ds_read_b128 v[188:191], v151 offset:50176
	ds_read_b128 v[192:195], v151 offset:51200
	ds_read_b128 v[196:199], v151 offset:52224
	ds_read_b128 v[200:203], v151 offset:53248
	ds_read_b128 v[204:207], v151 offset:54272
	ds_read_b128 v[208:211], v151 offset:55296
	ds_read_b128 v[214:217], v151 offset:56320
	global_load_lds_dwordx4 v132, s[86:87]
	s_add_i32 m0, s42, 0x2000
	s_add_u32 s40, s40, 0x80080
	s_addc_u32 s41, s41, 0
	s_add_i32 s42, s63, s24
	global_load_lds_dwordx4 v128, s[86:87]
	s_mov_b32 m0, s42
	s_nop 0
	global_load_lds_dwordx4 v132, s[40:41]
	s_add_i32 m0, s42, 0x2000
	s_nop 0
	global_load_lds_dwordx4 v128, s[40:41]
	s_mov_b32 m0, s49
	s_nop 0
	global_load_lds_dwordx4 v134, s[84:85]
	s_mov_b32 m0, s50
	s_nop 0
	global_load_lds_dwordx4 v130, s[84:85]
	s_waitcnt vmcnt(8)
	s_waitcnt lgkmcnt(0)
	s_barrier
	v_mfma_f32_16x16x32_bf16 v[60:63], v[152:155], v[184:187], v[60:63]
	v_mfma_f32_16x16x32_bf16 v[56:59], v[160:163], v[184:187], v[56:59]
	v_mfma_f32_16x16x32_bf16 v[44:47], v[152:155], v[192:195], v[44:47]
	v_mfma_f32_16x16x32_bf16 v[40:43], v[160:163], v[192:195], v[40:43]
	v_mfma_f32_16x16x32_bf16 v[28:31], v[152:155], v[200:203], v[28:31]
	v_mfma_f32_16x16x32_bf16 v[24:27], v[160:163], v[200:203], v[24:27]
	v_mfma_f32_16x16x32_bf16 v[12:15], v[152:155], v[208:211], v[12:15]
	v_mfma_f32_16x16x32_bf16 v[8:11], v[160:163], v[208:211], v[8:11]
	v_mfma_f32_16x16x32_bf16 v[60:63], v[156:159], v[188:191], v[60:63]
	v_mfma_f32_16x16x32_bf16 v[56:59], v[164:167], v[188:191], v[56:59]
	v_mfma_f32_16x16x32_bf16 v[44:47], v[156:159], v[196:199], v[44:47]
	v_mfma_f32_16x16x32_bf16 v[40:43], v[164:167], v[196:199], v[40:43]
	v_mfma_f32_16x16x32_bf16 v[28:31], v[156:159], v[204:207], v[28:31]
	v_mfma_f32_16x16x32_bf16 v[24:27], v[164:167], v[204:207], v[24:27]
	v_mfma_f32_16x16x32_bf16 v[12:15], v[156:159], v[214:217], v[12:15]
	v_mfma_f32_16x16x32_bf16 v[8:11], v[164:167], v[214:217], v[8:11]
	v_mfma_f32_16x16x32_bf16 v[52:55], v[168:171], v[184:187], v[52:55]
	v_mfma_f32_16x16x32_bf16 v[48:51], v[176:179], v[184:187], v[48:51]
	v_mfma_f32_16x16x32_bf16 v[36:39], v[168:171], v[192:195], v[36:39]
	v_mfma_f32_16x16x32_bf16 v[32:35], v[176:179], v[192:195], v[32:35]
	v_mfma_f32_16x16x32_bf16 v[20:23], v[168:171], v[200:203], v[20:23]
	v_mfma_f32_16x16x32_bf16 v[16:19], v[176:179], v[200:203], v[16:19]
	v_mfma_f32_16x16x32_bf16 v[4:7], v[168:171], v[208:211], v[4:7]
	v_mfma_f32_16x16x32_bf16 v[0:3], v[176:179], v[208:211], v[0:3]
	v_mfma_f32_16x16x32_bf16 v[52:55], v[172:175], v[188:191], v[52:55]
	v_mfma_f32_16x16x32_bf16 v[48:51], v[180:183], v[188:191], v[48:51]
	v_mfma_f32_16x16x32_bf16 v[36:39], v[172:175], v[196:199], v[36:39]
	v_mfma_f32_16x16x32_bf16 v[32:35], v[180:183], v[196:199], v[32:35]
	v_mfma_f32_16x16x32_bf16 v[20:23], v[172:175], v[204:207], v[20:23]
	v_mfma_f32_16x16x32_bf16 v[16:19], v[180:183], v[204:207], v[16:19]
	v_mfma_f32_16x16x32_bf16 v[4:7], v[172:175], v[214:217], v[4:7]
	v_mfma_f32_16x16x32_bf16 v[0:3], v[180:183], v[214:217], v[0:3]
	s_barrier
	s_add_i32 s61, s61, 2
	s_add_u32 s38, s38, 0x100
	s_addc_u32 s39, s39, 0
	s_add_u32 s59, s59, 0x100
	s_addc_u32 s60, s60, 0
	s_cmp_gt_u32 s61, 29
	.p2align	6

; #define PG8_STAGE(bufoff, gbase, voff) do { _Pragma("unroll") for (int _i = 0; _i < 2; ++_i) \
;         __builtin_amdgcn_global_load_lds((const unsigned*)((const char*)(gbase) + (voff)[_i]), (PG8_LAS unsigned*)(lds + (bufoff) + ldsw + _i * 8192), 16, 0, 0); } while (0)
; #define PG8_LDA(dst, b, h) do { _Pragma("unroll") for (int m = 0; m < 4; ++m) _Pragma("unroll") for (int k = 0; k < 2; ++k) dst[m][k] = *(const PG8_LAS bf16x8*)(lds + PG8_SA(b, h) + aoff + m * 2048 + k * 1024); } while (0)
; #define PG8_LDB(dst, b, h) do { _Pragma("unroll") for (int n = 0; n < 2; ++n) _Pragma("unroll") for (int k = 0; k < 2; ++k) dst[n][k] = *(const PG8_LAS bf16x8*)(lds + PG8_SB(b, h) + boff + n * 2048 + k * 1024); } while (0)
; #define PG8_WAIT_V(n) asm volatile("s_waitcnt vmcnt(" #n ")" ::: "memory")
; #define PG8_WAIT_L(n) asm volatile("s_waitcnt lgkmcnt(" #n ")" ::: "memory")
; #define PG8_BAR __builtin_amdgcn_s_barrier()
; #define PG8_SCHED __builtin_amdgcn_sched_barrier(0)
; template <class Epi, class Sched, bool ALIGN_EPI = false, bool SP2 = false>
; __device__ __forceinline__ void gemm_phase(PG8_LAS unsigned char* lds, const Gemm g, const Sched& S, const Epi& E) {
;     ...
;         const bool has_next = S.next(ui + 1, nxt);
;         const char* nA = has_next ? (const char*)g.A + (size_t)nxt.pm * tstep : cA; const char* nB = has_next ? (const char*)g.Bt + (size_t)nxt.pn * tstep : cB;
;         for (int t = 0; t < nt; t += 2) {
;             const bool last = (t == nt - 2);
;             const char* a1 = cA + (size_t)(t + 1) * kstep;
;             const char* a2 = last ? nA : cA + (size_t)(t + 2) * kstep; const char* b2 = last ? nB : cB + (size_t)(t + 2) * kstep;
;             const char* a3 = a2 + kstep; const char* b3 = b2 + kstep;
;             if (last && has_next) S.a_ready(nxt);
;             if constexpr (SP2) {
;             PG8_LDB(B0, 0, 0); PG8_LDB(B1, 0, 1); PG8_SCHED; PG8_LDA(At, 0, 0); PG8_STAGE(PG8_SA(1, 1), a1 + hstep, voffA);
;             PG8_WAIT_V(8); PG8_WAIT_L(0); PG8_BAR; PG8_MMA(0, 0, At, B0); PG8_MMA(0, 1, At, B1); PG8_BAR; PG8_SCHED;
;             PG8_LDA(At, 0, 1); PG8_STAGE(PG8_SB(0, 0), b2, voffB); PG8_STAGE(PG8_SB(0, 1), b2 + hstep, voffB); PG8_STAGE(PG8_SA(0, 0), a2, voffA);
;             PG8_WAIT_V(8); PG8_WAIT_L(0); PG8_BAR; PG8_MMA(1, 0, At, B0); PG8_MMA(1, 1, At, B1); PG8_BAR; PG8_SCHED;
.LBB0_244:
	s_add_u32 s67, s46, 0x100
	v_mov_b32_e32 v220, v251
	s_addc_u32 s68, s47, 0
	s_mov_b32 s69, -2
	ds_read_b128 v[140:143], v169
	ds_read_b128 v[144:147], v169 offset:1024
	ds_read_b128 v[148:151], v169 offset:2048
	ds_read_b128 v[152:155], v169 offset:3072
	ds_read_b128 v[156:159], v170
	ds_read_b128 v[160:163], v170 offset:1024
	ds_read_b128 v[172:175], v170 offset:2048
	ds_read_b128 v[176:179], v170 offset:3072
	s_add_u32 s46, s44, 0x100
	s_addc_u32 s47, s45, 0
	s_cmpk_eq_i32 s69, 0x54
	s_cselect_b32 s51, s11, s47
	s_cselect_b32 s50, s10, s46
	s_cselect_b32 s49, s13, s68
	s_cselect_b32 s48, s12, s67
	s_add_i32 m0, s26, 0xc000
	ds_read_b128 v[180:183], v171
	ds_read_b128 v[184:187], v171 offset:1024
	ds_read_b128 v[188:191], v171 offset:2048
	ds_read_b128 v[192:195], v171 offset:3072
	ds_read_b128 v[196:199], v171 offset:4096
	ds_read_b128 v[200:203], v171 offset:5120
	ds_read_b128 v[204:207], v171 offset:6144
	ds_read_b128 v[208:211], v171 offset:7168
	global_load_lds_dwordx4 v136, s[44:45]
	s_add_i32 m0, s26, 0xe000
	s_nop 0
	global_load_lds_dwordx4 v138, s[44:45]
	s_waitcnt vmcnt(8)
	s_waitcnt lgkmcnt(0)
	s_barrier
	v_mfma_f32_16x16x32_bf16 v[124:127], v[140:143], v[180:183], 0
	v_mfma_f32_16x16x32_bf16 v[120:123], v[148:151], v[180:183], 0
	v_mfma_f32_16x16x32_bf16 v[116:119], v[140:143], v[188:191], 0
	v_mfma_f32_16x16x32_bf16 v[112:115], v[148:151], v[188:191], 0
	v_mfma_f32_16x16x32_bf16 v[108:111], v[140:143], v[196:199], 0
	v_mfma_f32_16x16x32_bf16 v[96:99], v[148:151], v[196:199], 0
	v_mfma_f32_16x16x32_bf16 v[84:87], v[140:143], v[204:207], 0
	v_mfma_f32_16x16x32_bf16 v[76:79], v[148:151], v[204:207], 0
	v_mfma_f32_16x16x32_bf16 v[124:127], v[144:147], v[184:187], v[124:127]
	v_mfma_f32_16x16x32_bf16 v[120:123], v[152:155], v[184:187], v[120:123]
	v_mfma_f32_16x16x32_bf16 v[116:119], v[144:147], v[192:195], v[116:119]
	v_mfma_f32_16x16x32_bf16 v[112:115], v[152:155], v[192:195], v[112:115]
	v_mfma_f32_16x16x32_bf16 v[108:111], v[144:147], v[200:203], v[108:111]
	v_mfma_f32_16x16x32_bf16 v[96:99], v[152:155], v[200:203], v[96:99]
	v_mfma_f32_16x16x32_bf16 v[84:87], v[144:147], v[208:211], v[84:87]
	v_mfma_f32_16x16x32_bf16 v[76:79], v[152:155], v[208:211], v[76:79]
	v_mfma_f32_16x16x32_bf16 v[104:107], v[156:159], v[180:183], 0
	v_mfma_f32_16x16x32_bf16 v[100:103], v[172:175], v[180:183], 0
	v_mfma_f32_16x16x32_bf16 v[92:95], v[156:159], v[188:191], 0
	v_mfma_f32_16x16x32_bf16 v[88:91], v[172:175], v[188:191], 0
	v_mfma_f32_16x16x32_bf16 v[80:83], v[156:159], v[196:199], 0
	v_mfma_f32_16x16x32_bf16 v[72:75], v[172:175], v[196:199], 0
	v_mfma_f32_16x16x32_bf16 v[68:71], v[156:159], v[204:207], 0
	v_mfma_f32_16x16x32_bf16 v[64:67], v[172:175], v[204:207], 0
	v_mfma_f32_16x16x32_bf16 v[104:107], v[160:163], v[184:187], v[104:107]
	v_mfma_f32_16x16x32_bf16 v[100:103], v[176:179], v[184:187], v[100:103]
	v_mfma_f32_16x16x32_bf16 v[92:95], v[160:163], v[192:195], v[92:95]
	v_mfma_f32_16x16x32_bf16 v[88:91], v[176:179], v[192:195], v[88:91]
	v_mfma_f32_16x16x32_bf16 v[80:83], v[160:163], v[200:203], v[80:83]
	v_mfma_f32_16x16x32_bf16 v[72:75], v[176:179], v[200:203], v[72:75]
	v_mfma_f32_16x16x32_bf16 v[68:71], v[160:163], v[208:211], v[68:71]
	v_mfma_f32_16x16x32_bf16 v[64:67], v[176:179], v[208:211], v[64:67]
	s_barrier
	s_add_i32 s44, s61, s25
	s_mov_b32 m0, s44
	ds_read_b128 v[180:183], v171 offset:16384
	ds_read_b128 v[184:187], v171 offset:17408
	ds_read_b128 v[188:191], v171 offset:18432
	ds_read_b128 v[192:195], v171 offset:19456
	ds_read_b128 v[196:199], v171 offset:20480
	ds_read_b128 v[200:203], v171 offset:21504
	ds_read_b128 v[204:207], v171 offset:22528
	ds_read_b128 v[208:211], v171 offset:23552
	global_load_lds_dwordx4 v130, s[48:49]
	s_add_i32 m0, s44, 0x2000
	s_add_u32 s44, s48, 0x160000
	s_addc_u32 s45, s49, 0
	s_add_i32 s70, s62, s25
	global_load_lds_dwordx4 v134, s[48:49]
	s_mov_b32 m0, s70
	s_nop 0
	global_load_lds_dwordx4 v130, s[44:45]
	s_add_i32 m0, s70, 0x2000
	s_nop 0
	global_load_lds_dwordx4 v134, s[44:45]
	s_mov_b32 m0, s26
	s_nop 0
	global_load_lds_dwordx4 v128, s[50:51]
	s_mov_b32 m0, s27
	s_nop 0
	global_load_lds_dwordx4 v132, s[50:51]
	s_waitcnt vmcnt(8)
	s_waitcnt lgkmcnt(0)
	s_barrier
	v_mfma_f32_16x16x32_bf16 v[60:63], v[140:143], v[180:183], 0
	v_mfma_f32_16x16x32_bf16 v[56:59], v[148:151], v[180:183], 0
	v_mfma_f32_16x16x32_bf16 v[52:55], v[140:143], v[188:191], 0
	v_mfma_f32_16x16x32_bf16 v[48:51], v[148:151], v[188:191], 0
	v_mfma_f32_16x16x32_bf16 v[44:47], v[140:143], v[196:199], 0
	v_mfma_f32_16x16x32_bf16 v[32:35], v[148:151], v[196:199], 0
	v_mfma_f32_16x16x32_bf16 v[20:23], v[140:143], v[204:207], 0
	v_mfma_f32_16x16x32_bf16 v[12:15], v[148:151], v[204:207], 0
	v_mfma_f32_16x16x32_bf16 v[60:63], v[144:147], v[184:187], v[60:63]
	v_mfma_f32_16x16x32_bf16 v[56:59], v[152:155], v[184:187], v[56:59]
	v_mfma_f32_16x16x32_bf16 v[52:55], v[144:147], v[192:195], v[52:55]
	v_mfma_f32_16x16x32_bf16 v[48:51], v[152:155], v[192:195], v[48:51]
	v_mfma_f32_16x16x32_bf16 v[44:47], v[144:147], v[200:203], v[44:47]
	v_mfma_f32_16x16x32_bf16 v[32:35], v[152:155], v[200:203], v[32:35]
	v_mfma_f32_16x16x32_bf16 v[20:23], v[144:147], v[208:211], v[20:23]
	v_mfma_f32_16x16x32_bf16 v[12:15], v[152:155], v[208:211], v[12:15]
	v_mfma_f32_16x16x32_bf16 v[40:43], v[156:159], v[180:183], 0
	v_mfma_f32_16x16x32_bf16 v[36:39], v[172:175], v[180:183], 0
	v_mfma_f32_16x16x32_bf16 v[28:31], v[156:159], v[188:191], 0
	v_mfma_f32_16x16x32_bf16 v[24:27], v[172:175], v[188:191], 0
	v_mfma_f32_16x16x32_bf16 v[16:19], v[156:159], v[196:199], 0
	v_mfma_f32_16x16x32_bf16 v[8:11], v[172:175], v[196:199], 0
	v_mfma_f32_16x16x32_bf16 v[4:7], v[156:159], v[204:207], 0
	v_mfma_f32_16x16x32_bf16 v[0:3], v[172:175], v[204:207], 0
	v_mfma_f32_16x16x32_bf16 v[40:43], v[160:163], v[184:187], v[40:43]
	v_mfma_f32_16x16x32_bf16 v[36:39], v[176:179], v[184:187], v[36:39]
	v_mfma_f32_16x16x32_bf16 v[28:31], v[160:163], v[192:195], v[28:31]
	v_mfma_f32_16x16x32_bf16 v[24:27], v[176:179], v[192:195], v[24:27]
	v_mfma_f32_16x16x32_bf16 v[16:19], v[160:163], v[200:203], v[16:19]
	v_mfma_f32_16x16x32_bf16 v[8:11], v[176:179], v[200:203], v[8:11]
	v_mfma_f32_16x16x32_bf16 v[4:7], v[160:163], v[208:211], v[4:7]
	v_mfma_f32_16x16x32_bf16 v[0:3], v[176:179], v[208:211], v[0:3]
	s_barrier
; #define PG8_STAGE(bufoff, gbase, voff) do { _Pragma("unroll") for (int _i = 0; _i < 2; ++_i) \
;         __builtin_amdgcn_global_load_lds((const unsigned*)((const char*)(gbase) + (voff)[_i]), (PG8_LAS unsigned*)(lds + (bufoff) + ldsw + _i * 8192), 16, 0, 0); } while (0)
; #define PG8_LDA(dst, b, h) do { _Pragma("unroll") for (int m = 0; m < 4; ++m) _Pragma("unroll") for (int k = 0; k < 2; ++k) dst[m][k] = *(const PG8_LAS bf16x8*)(lds + PG8_SA(b, h) + aoff + m * 2048 + k * 1024); } while (0)
; #define PG8_LDB(dst, b, h) do { _Pragma("unroll") for (int n = 0; n < 2; ++n) _Pragma("unroll") for (int k = 0; k < 2; ++k) dst[n][k] = *(const PG8_LAS bf16x8*)(lds + PG8_SB(b, h) + boff + n * 2048 + k * 1024); } while (0)
; #define PG8_MMA(ai, bj, At, Bt) do { __builtin_amdgcn_s_setprio(1); _Pragma("unroll") for (int m = 0; m < 4; ++m) _Pragma("unroll") for (int n = 0; n < 2; ++n) _Pragma("unroll") for (int k = 0; k < 2; ++k) \
;         acc[ai][bj][m][n] = __builtin_amdgcn_mfma_f32_16x16x32_bf16(Bt[n][k], At[m][k], acc[ai][bj][m][n], 0, 0, 0); __builtin_amdgcn_s_setprio(0); } while (0)
; #define PG8_WAIT_V(n) asm volatile("s_waitcnt vmcnt(" #n ")" ::: "memory")
; #define PG8_WAIT_L(n) asm volatile("s_waitcnt lgkmcnt(" #n ")" ::: "memory")
; #define PG8_BAR __builtin_amdgcn_s_barrier()
; #define PG8_SCHED __builtin_amdgcn_sched_barrier(0)
; template <class Epi, class Sched, bool ALIGN_EPI = false, bool SP2 = false>
; __device__ __forceinline__ void gemm_phase(PG8_LAS unsigned char* lds, const Gemm g, const Sched& S, const Epi& E) {
;     ...
;             PG8_LDB(B0, 1, 0); PG8_LDB(B1, 1, 1); PG8_SCHED; PG8_LDA(At, 1, 0); PG8_STAGE(PG8_SA(0, 1), a2 + hstep, voffA);
;             PG8_WAIT_V(8); PG8_WAIT_L(0); PG8_BAR; PG8_MMA(0, 0, At, B0); PG8_MMA(0, 1, At, B1); PG8_BAR; PG8_SCHED;
;             PG8_LDA(At, 1, 1); PG8_STAGE(PG8_SB(1, 0), b3, voffB); PG8_STAGE(PG8_SB(1, 1), b3 + hstep, voffB); PG8_STAGE(PG8_SA(1, 0), a3, voffA);
;             PG8_WAIT_V(8); PG8_WAIT_L(0); PG8_BAR; PG8_MMA(1, 0, At, B0); PG8_MMA(1, 1, At, B1); PG8_BAR; PG8_SCHED;
	s_add_i32 s70, 0, 0x18000
	s_add_i32 s71, 0, 0x1c000
	v_add_u32_e32 v152, s70, v167
	v_add_u32_e32 v176, s71, v167
	ds_read_b128 v[140:143], v152
	ds_read_b128 v[144:147], v152 offset:1024
	ds_read_b128 v[148:151], v152 offset:2048
	ds_read_b128 v[152:155], v152 offset:3072
	ds_read_b128 v[156:159], v176
	ds_read_b128 v[160:163], v176 offset:1024
	ds_read_b128 v[172:175], v176 offset:2048
	ds_read_b128 v[176:179], v176 offset:3072
	s_add_u32 s44, s50, 0x160000
	s_addc_u32 s45, s51, 0
	s_mov_b32 m0, s52
	ds_read_b128 v[180:183], v171 offset:32768
	ds_read_b128 v[184:187], v171 offset:33792
	ds_read_b128 v[188:191], v171 offset:34816
	ds_read_b128 v[192:195], v171 offset:35840
	ds_read_b128 v[196:199], v171 offset:36864
	ds_read_b128 v[200:203], v171 offset:37888
	ds_read_b128 v[204:207], v171 offset:38912
	ds_read_b128 v[208:211], v171 offset:39936
	global_load_lds_dwordx4 v128, s[44:45]
	s_mov_b32 m0, s53
	s_nop 0
	global_load_lds_dwordx4 v132, s[44:45]
	s_waitcnt vmcnt(8)
	s_waitcnt lgkmcnt(0)
	s_barrier
	v_mfma_f32_16x16x32_bf16 v[124:127], v[140:143], v[180:183], v[124:127]
	v_mfma_f32_16x16x32_bf16 v[120:123], v[148:151], v[180:183], v[120:123]
	v_mfma_f32_16x16x32_bf16 v[116:119], v[140:143], v[188:191], v[116:119]
	v_mfma_f32_16x16x32_bf16 v[112:115], v[148:151], v[188:191], v[112:115]
	v_mfma_f32_16x16x32_bf16 v[108:111], v[140:143], v[196:199], v[108:111]
	v_mfma_f32_16x16x32_bf16 v[96:99], v[148:151], v[196:199], v[96:99]
	v_mfma_f32_16x16x32_bf16 v[84:87], v[140:143], v[204:207], v[84:87]
	v_mfma_f32_16x16x32_bf16 v[76:79], v[148:151], v[204:207], v[76:79]
	v_mfma_f32_16x16x32_bf16 v[124:127], v[144:147], v[184:187], v[124:127]
	v_mfma_f32_16x16x32_bf16 v[120:123], v[152:155], v[184:187], v[120:123]
	v_mfma_f32_16x16x32_bf16 v[116:119], v[144:147], v[192:195], v[116:119]
	v_mfma_f32_16x16x32_bf16 v[112:115], v[152:155], v[192:195], v[112:115]
	v_mfma_f32_16x16x32_bf16 v[108:111], v[144:147], v[200:203], v[108:111]
	v_mfma_f32_16x16x32_bf16 v[96:99], v[152:155], v[200:203], v[96:99]
	v_mfma_f32_16x16x32_bf16 v[84:87], v[144:147], v[208:211], v[84:87]
	v_mfma_f32_16x16x32_bf16 v[76:79], v[152:155], v[208:211], v[76:79]
	v_mfma_f32_16x16x32_bf16 v[104:107], v[156:159], v[180:183], v[104:107]
	v_mfma_f32_16x16x32_bf16 v[100:103], v[172:175], v[180:183], v[100:103]
	v_mfma_f32_16x16x32_bf16 v[92:95], v[156:159], v[188:191], v[92:95]
	v_mfma_f32_16x16x32_bf16 v[88:91], v[172:175], v[188:191], v[88:91]
	v_mfma_f32_16x16x32_bf16 v[80:83], v[156:159], v[196:199], v[80:83]
	v_mfma_f32_16x16x32_bf16 v[72:75], v[172:175], v[196:199], v[72:75]
	v_mfma_f32_16x16x32_bf16 v[68:71], v[156:159], v[204:207], v[68:71]
	v_mfma_f32_16x16x32_bf16 v[64:67], v[172:175], v[204:207], v[64:67]
	v_mfma_f32_16x16x32_bf16 v[104:107], v[160:163], v[184:187], v[104:107]
	v_mfma_f32_16x16x32_bf16 v[100:103], v[176:179], v[184:187], v[100:103]
	v_mfma_f32_16x16x32_bf16 v[92:95], v[160:163], v[192:195], v[92:95]
	v_mfma_f32_16x16x32_bf16 v[88:91], v[176:179], v[192:195], v[88:91]
	v_mfma_f32_16x16x32_bf16 v[80:83], v[160:163], v[200:203], v[80:83]
	v_mfma_f32_16x16x32_bf16 v[72:75], v[176:179], v[200:203], v[72:75]
	v_mfma_f32_16x16x32_bf16 v[68:71], v[160:163], v[208:211], v[68:71]
	v_mfma_f32_16x16x32_bf16 v[64:67], v[176:179], v[208:211], v[64:67]
	s_barrier
	s_add_i32 s44, s70, s25
	s_add_u32 s86, s48, 0x80
	s_addc_u32 s87, s49, 0
	s_mov_b32 m0, s44
	ds_read_b128 v[180:183], v171 offset:49152
	ds_read_b128 v[184:187], v171 offset:50176
	ds_read_b128 v[188:191], v171 offset:51200
	ds_read_b128 v[192:195], v171 offset:52224
	ds_read_b128 v[196:199], v171 offset:53248
	ds_read_b128 v[200:203], v171 offset:54272
	ds_read_b128 v[204:207], v171 offset:55296
	ds_read_b128 v[208:211], v171 offset:56320
	global_load_lds_dwordx4 v130, s[86:87]
	s_add_i32 m0, s44, 0x2000
	s_add_u32 s44, s48, 0x160080
	s_addc_u32 s45, s49, 0
	s_add_i32 s48, s71, s25
	global_load_lds_dwordx4 v134, s[86:87]
	s_mov_b32 m0, s48
	s_nop 0
	global_load_lds_dwordx4 v130, s[44:45]
	s_add_i32 m0, s48, 0x2000
	s_nop 0
	global_load_lds_dwordx4 v134, s[44:45]
	s_add_u32 s84, s50, 0x80
	s_addc_u32 s85, s51, 0
	s_mov_b32 m0, s57
	s_nop 0
	global_load_lds_dwordx4 v128, s[84:85]
	s_mov_b32 m0, s58
	s_nop 0
	global_load_lds_dwordx4 v132, s[84:85]
	s_waitcnt vmcnt(8)
	s_waitcnt lgkmcnt(0)
	s_barrier
	v_mfma_f32_16x16x32_bf16 v[60:63], v[140:143], v[180:183], v[60:63]
	v_mfma_f32_16x16x32_bf16 v[56:59], v[148:151], v[180:183], v[56:59]
	v_mfma_f32_16x16x32_bf16 v[52:55], v[140:143], v[188:191], v[52:55]
	v_mfma_f32_16x16x32_bf16 v[48:51], v[148:151], v[188:191], v[48:51]
	v_mfma_f32_16x16x32_bf16 v[44:47], v[140:143], v[196:199], v[44:47]
	v_mfma_f32_16x16x32_bf16 v[32:35], v[148:151], v[196:199], v[32:35]
	v_mfma_f32_16x16x32_bf16 v[20:23], v[140:143], v[204:207], v[20:23]
	v_mfma_f32_16x16x32_bf16 v[12:15], v[148:151], v[204:207], v[12:15]
	v_mfma_f32_16x16x32_bf16 v[60:63], v[144:147], v[184:187], v[60:63]
	v_mfma_f32_16x16x32_bf16 v[56:59], v[152:155], v[184:187], v[56:59]
	v_mfma_f32_16x16x32_bf16 v[52:55], v[144:147], v[192:195], v[52:55]
	v_mfma_f32_16x16x32_bf16 v[48:51], v[152:155], v[192:195], v[48:51]
	v_mfma_f32_16x16x32_bf16 v[44:47], v[144:147], v[200:203], v[44:47]
	v_mfma_f32_16x16x32_bf16 v[32:35], v[152:155], v[200:203], v[32:35]
	v_mfma_f32_16x16x32_bf16 v[20:23], v[144:147], v[208:211], v[20:23]
	v_mfma_f32_16x16x32_bf16 v[12:15], v[152:155], v[208:211], v[12:15]
	v_mfma_f32_16x16x32_bf16 v[40:43], v[156:159], v[180:183], v[40:43]
	v_mfma_f32_16x16x32_bf16 v[36:39], v[172:175], v[180:183], v[36:39]
	v_mfma_f32_16x16x32_bf16 v[28:31], v[156:159], v[188:191], v[28:31]
	v_mfma_f32_16x16x32_bf16 v[24:27], v[172:175], v[188:191], v[24:27]
	v_mfma_f32_16x16x32_bf16 v[16:19], v[156:159], v[196:199], v[16:19]
	v_mfma_f32_16x16x32_bf16 v[8:11], v[172:175], v[196:199], v[8:11]
	v_mfma_f32_16x16x32_bf16 v[4:7], v[156:159], v[204:207], v[4:7]
	v_mfma_f32_16x16x32_bf16 v[0:3], v[172:175], v[204:207], v[0:3]
	v_mfma_f32_16x16x32_bf16 v[40:43], v[160:163], v[184:187], v[40:43]
	v_mfma_f32_16x16x32_bf16 v[36:39], v[176:179], v[184:187], v[36:39]
	v_mfma_f32_16x16x32_bf16 v[28:31], v[160:163], v[192:195], v[28:31]
	v_mfma_f32_16x16x32_bf16 v[24:27], v[176:179], v[192:195], v[24:27]
	v_mfma_f32_16x16x32_bf16 v[16:19], v[160:163], v[200:203], v[16:19]
	v_mfma_f32_16x16x32_bf16 v[8:11], v[176:179], v[200:203], v[8:11]
	v_mfma_f32_16x16x32_bf16 v[4:7], v[160:163], v[208:211], v[4:7]
	v_mfma_f32_16x16x32_bf16 v[0:3], v[176:179], v[208:211], v[0:3]
	s_barrier
	s_add_i32 s69, s69, 2
	s_add_u32 s67, s67, 0x100
	s_addc_u32 s68, s68, 0
	s_cmpk_gt_u32 s69, 0x55
	s_mov_b64 s[44:45], s[46:47]
	.p2align	6

; #define PG8_STAGE(bufoff, gbase, voff) do { _Pragma("unroll") for (int _i = 0; _i < 2; ++_i) \
;         __builtin_amdgcn_global_load_lds((const unsigned*)((const char*)(gbase) + (voff)[_i]), (PG8_LAS unsigned*)(lds + (bufoff) + ldsw + _i * 8192), 16, 0, 0); } while (0)
; #define PG8_LDA(dst, b, h) do { _Pragma("unroll") for (int m = 0; m < 4; ++m) _Pragma("unroll") for (int k = 0; k < 2; ++k) dst[m][k] = *(const PG8_LAS bf16x8*)(lds + PG8_SA(b, h) + aoff + m * 2048 + k * 1024); } while (0)
; #define PG8_LDB(dst, b, h) do { _Pragma("unroll") for (int n = 0; n < 2; ++n) _Pragma("unroll") for (int k = 0; k < 2; ++k) dst[n][k] = *(const PG8_LAS bf16x8*)(lds + PG8_SB(b, h) + boff + n * 2048 + k * 1024); } while (0)
; #define PG8_MMA(ai, bj, At, Bt) do { __builtin_amdgcn_s_setprio(1); _Pragma("unroll") for (int m = 0; m < 4; ++m) _Pragma("unroll") for (int n = 0; n < 2; ++n) _Pragma("unroll") for (int k = 0; k < 2; ++k) \
;         acc[ai][bj][m][n] = __builtin_amdgcn_mfma_f32_16x16x32_bf16(Bt[n][k], At[m][k], acc[ai][bj][m][n], 0, 0, 0); __builtin_amdgcn_s_setprio(0); } while (0)
; #define PG8_BAR __builtin_amdgcn_s_barrier()
; template <class Epi, class Sched, bool ALIGN_EPI = false, bool SP2 = false>
; __device__ __forceinline__ void gemm_phase(PG8_LAS unsigned char* lds, const Gemm g, const Sched& S, const Epi& E) {
;     ...
;         const bool has_next = S.next(ui + 1, nxt);
;         const char* nA = has_next ? (const char*)g.A + (size_t)nxt.pm * tstep : cA; const char* nB = has_next ? (const char*)g.Bt + (size_t)nxt.pn * tstep : cB;
;         for (int t = 0; t < nt; t += 2) {
;             const bool last = (t == nt - 2);
;             const char* a1 = cA + (size_t)(t + 1) * kstep;
;             const char* a2 = last ? nA : cA + (size_t)(t + 2) * kstep; const char* b2 = last ? nB : cB + (size_t)(t + 2) * kstep;
;             const char* a3 = a2 + kstep; const char* b3 = b2 + kstep;
;             if (last && has_next) S.a_ready(nxt);
;             if constexpr (SP2) {
;             PG8_LDB(B0, 0, 0); PG8_LDB(B1, 0, 1); PG8_SCHED; PG8_LDA(At, 0, 0); PG8_STAGE(PG8_SA(1, 1), a1 + hstep, voffA);
;             PG8_WAIT_V(8); PG8_WAIT_L(0); PG8_BAR; PG8_MMA(0, 0, At, B0); PG8_MMA(0, 1, At, B1); PG8_BAR; PG8_SCHED;
;             PG8_LDA(At, 0, 1); PG8_STAGE(PG8_SB(0, 0), b2, voffB); PG8_STAGE(PG8_SB(0, 1), b2 + hstep, voffB); PG8_STAGE(PG8_SA(0, 0), a2, voffA);
.LBB0_363:
	s_ashr_i32 s77, s76, 31
	s_lshl_b64 s[38:39], s[76:77], 20
	v_cmp_lt_i64_e32 vcc, s[78:79], v[178:179]
	s_add_u32 s78, s73, s38
	s_addc_u32 s79, s96, s39
	s_and_b64 s[38:39], vcc, exec
	s_cselect_b32 s77, s79, s85
	s_cselect_b32 s83, s78, s84
	s_ashr_i32 s75, s74, 31
	s_lshl_b64 s[38:39], s[74:75], 20
	s_add_u32 s80, s97, s38
	s_addc_u32 s81, s90, s39
	s_and_b64 s[38:39], vcc, exec
	s_cselect_b32 s75, s81, s87
	s_cselect_b32 vcc_lo, s80, s86
	s_add_u32 s84, s84, 0x80080
	s_addc_u32 s85, s85, 0
	s_add_u32 vcc_hi, s86, 0x100
	s_addc_u32 s38, s87, 0
	s_mov_b32 s39, -2
	ds_read_b128 v[128:131], v214
	ds_read_b128 v[132:135], v214 offset:1024
	ds_read_b128 v[136:139], v214 offset:2048
	ds_read_b128 v[140:143], v214 offset:3072
	ds_read_b128 v[144:147], v215
	ds_read_b128 v[148:151], v215 offset:1024
	ds_read_b128 v[152:155], v215 offset:2048
	ds_read_b128 v[156:159], v215 offset:3072
	s_add_u32 s58, s84, 0xfff80080
	s_addc_u32 s59, s85, -1
	s_cmp_eq_u32 s39, 28
	s_cselect_b32 s89, s77, s59
	s_cselect_b32 s88, s83, s58
	s_cselect_b32 s87, s75, s38
	s_cselect_b32 s86, vcc_lo, vcc_hi
	s_add_i32 m0, s7, 0xc000
	ds_read_b128 v[160:163], v216
	ds_read_b128 v[182:185], v216 offset:1024
	ds_read_b128 v[186:189], v216 offset:2048
	ds_read_b128 v[190:193], v216 offset:3072
	ds_read_b128 v[222:225], v216 offset:4096
	ds_read_b128 v[232:235], v216 offset:5120
	ds_read_b128 v[236:239], v216 offset:6144
	ds_read_b128 v[240:243], v216 offset:7168
	global_load_lds_dwordx4 v174, s[84:85]
	s_add_i32 m0, s7, 0xe000
	s_nop 0
	global_load_lds_dwordx4 v176, s[84:85]
	s_waitcnt vmcnt(8)
	s_waitcnt lgkmcnt(0)
	s_barrier
	v_mfma_f32_16x16x32_bf16 v[124:127], v[128:131], v[160:163], 0
	v_mfma_f32_16x16x32_bf16 v[120:123], v[136:139], v[160:163], 0
	v_mfma_f32_16x16x32_bf16 v[116:119], v[128:131], v[186:189], 0
	v_mfma_f32_16x16x32_bf16 v[112:115], v[136:139], v[186:189], 0
	v_mfma_f32_16x16x32_bf16 v[100:103], v[128:131], v[222:225], 0
	v_mfma_f32_16x16x32_bf16 v[96:99], v[136:139], v[222:225], 0
	v_mfma_f32_16x16x32_bf16 v[84:87], v[128:131], v[236:239], 0
	v_mfma_f32_16x16x32_bf16 v[80:83], v[136:139], v[236:239], 0
	v_mfma_f32_16x16x32_bf16 v[124:127], v[132:135], v[182:185], v[124:127]
	v_mfma_f32_16x16x32_bf16 v[120:123], v[140:143], v[182:185], v[120:123]
	v_mfma_f32_16x16x32_bf16 v[116:119], v[132:135], v[190:193], v[116:119]
	v_mfma_f32_16x16x32_bf16 v[112:115], v[140:143], v[190:193], v[112:115]
	v_mfma_f32_16x16x32_bf16 v[100:103], v[132:135], v[232:235], v[100:103]
	v_mfma_f32_16x16x32_bf16 v[96:99], v[140:143], v[232:235], v[96:99]
	v_mfma_f32_16x16x32_bf16 v[84:87], v[132:135], v[240:243], v[84:87]
	v_mfma_f32_16x16x32_bf16 v[80:83], v[140:143], v[240:243], v[80:83]
	v_mfma_f32_16x16x32_bf16 v[108:111], v[144:147], v[160:163], 0
	v_mfma_f32_16x16x32_bf16 v[104:107], v[152:155], v[160:163], 0
	v_mfma_f32_16x16x32_bf16 v[92:95], v[144:147], v[186:189], 0
	v_mfma_f32_16x16x32_bf16 v[88:91], v[152:155], v[186:189], 0
	v_mfma_f32_16x16x32_bf16 v[76:79], v[144:147], v[222:225], 0
	v_mfma_f32_16x16x32_bf16 v[72:75], v[152:155], v[222:225], 0
	v_mfma_f32_16x16x32_bf16 v[68:71], v[144:147], v[236:239], 0
	v_mfma_f32_16x16x32_bf16 v[64:67], v[152:155], v[236:239], 0
	v_mfma_f32_16x16x32_bf16 v[108:111], v[148:151], v[182:185], v[108:111]
	v_mfma_f32_16x16x32_bf16 v[104:107], v[156:159], v[182:185], v[104:107]
	v_mfma_f32_16x16x32_bf16 v[92:95], v[148:151], v[190:193], v[92:95]
	v_mfma_f32_16x16x32_bf16 v[88:91], v[156:159], v[190:193], v[88:91]
	v_mfma_f32_16x16x32_bf16 v[76:79], v[148:151], v[232:235], v[76:79]
	v_mfma_f32_16x16x32_bf16 v[72:75], v[156:159], v[232:235], v[72:75]
	v_mfma_f32_16x16x32_bf16 v[68:71], v[148:151], v[240:243], v[68:71]
	v_mfma_f32_16x16x32_bf16 v[64:67], v[156:159], v[240:243], v[64:67]
	s_barrier
	s_add_i32 s58, s34, s24
	v_lshl_add_u64 v[194:195], s[86:87], 0, v[168:169]
	s_mov_b32 m0, s58
	ds_read_b128 v[160:163], v216 offset:16384
	ds_read_b128 v[182:185], v216 offset:17408
	ds_read_b128 v[186:189], v216 offset:18432
	ds_read_b128 v[190:193], v216 offset:19456
	ds_read_b128 v[222:225], v216 offset:20480
	ds_read_b128 v[232:235], v216 offset:21504
	ds_read_b128 v[236:239], v216 offset:22528
	ds_read_b128 v[240:243], v216 offset:23552
	global_load_lds_dwordx4 v168, s[86:87]
	s_add_i32 m0, s58, 0x2000
	s_add_u32 s58, s86, 0x80000
	v_lshl_add_u64 v[230:231], s[86:87], 0, v[164:165]
	s_addc_u32 s59, s87, 0
	s_add_i32 s48, s35, s24
	global_load_lds_dwordx4 v164, s[86:87]
	s_mov_b32 m0, s48
	v_lshl_add_u64 v[246:247], s[88:89], 0, v[166:167]
	global_load_lds_dwordx4 v168, s[58:59]
	s_add_i32 m0, s48, 0x2000
	s_nop 0
	global_load_lds_dwordx4 v164, s[58:59]
	v_lshl_add_u64 v[244:245], s[88:89], 0, v[170:171]
	s_mov_b32 m0, s7
	s_nop 0
	global_load_lds_dwordx4 v170, s[88:89]
	s_mov_b32 m0, s8
	s_nop 0
	global_load_lds_dwordx4 v166, s[88:89]
	s_waitcnt vmcnt(8)
	s_waitcnt lgkmcnt(0)
	s_barrier
; #define PG8_STAGE(bufoff, gbase, voff) do { _Pragma("unroll") for (int _i = 0; _i < 2; ++_i) \
;         __builtin_amdgcn_global_load_lds((const unsigned*)((const char*)(gbase) + (voff)[_i]), (PG8_LAS unsigned*)(lds + (bufoff) + ldsw + _i * 8192), 16, 0, 0); } while (0)
; #define PG8_LDA(dst, b, h) do { _Pragma("unroll") for (int m = 0; m < 4; ++m) _Pragma("unroll") for (int k = 0; k < 2; ++k) dst[m][k] = *(const PG8_LAS bf16x8*)(lds + PG8_SA(b, h) + aoff + m * 2048 + k * 1024); } while (0)
; #define PG8_LDB(dst, b, h) do { _Pragma("unroll") for (int n = 0; n < 2; ++n) _Pragma("unroll") for (int k = 0; k < 2; ++k) dst[n][k] = *(const PG8_LAS bf16x8*)(lds + PG8_SB(b, h) + boff + n * 2048 + k * 1024); } while (0)
; #define PG8_MMA(ai, bj, At, Bt) do { __builtin_amdgcn_s_setprio(1); _Pragma("unroll") for (int m = 0; m < 4; ++m) _Pragma("unroll") for (int n = 0; n < 2; ++n) _Pragma("unroll") for (int k = 0; k < 2; ++k) \
;         acc[ai][bj][m][n] = __builtin_amdgcn_mfma_f32_16x16x32_bf16(Bt[n][k], At[m][k], acc[ai][bj][m][n], 0, 0, 0); __builtin_amdgcn_s_setprio(0); } while (0)
; #define PG8_WAIT_V(n) asm volatile("s_waitcnt vmcnt(" #n ")" ::: "memory")
; #define PG8_WAIT_L(n) asm volatile("s_waitcnt lgkmcnt(" #n ")" ::: "memory")
; #define PG8_BAR __builtin_amdgcn_s_barrier()
; #define PG8_SCHED __builtin_amdgcn_sched_barrier(0)
; template <class Epi, class Sched, bool ALIGN_EPI = false, bool SP2 = false>
; __device__ __forceinline__ void gemm_phase(PG8_LAS unsigned char* lds, const Gemm g, const Sched& S, const Epi& E) {
;     ...
;             PG8_WAIT_V(8); PG8_WAIT_L(0); PG8_BAR; PG8_MMA(1, 0, At, B0); PG8_MMA(1, 1, At, B1); PG8_BAR; PG8_SCHED;
;             PG8_LDB(B0, 1, 0); PG8_LDB(B1, 1, 1); PG8_SCHED; PG8_LDA(At, 1, 0); PG8_STAGE(PG8_SA(0, 1), a2 + hstep, voffA);
;             PG8_WAIT_V(8); PG8_WAIT_L(0); PG8_BAR; PG8_MMA(0, 0, At, B0); PG8_MMA(0, 1, At, B1); PG8_BAR; PG8_SCHED;
	v_mfma_f32_16x16x32_bf16 v[60:63], v[128:131], v[160:163], 0
	v_mfma_f32_16x16x32_bf16 v[56:59], v[136:139], v[160:163], 0
	v_mfma_f32_16x16x32_bf16 v[52:55], v[128:131], v[186:189], 0
	v_mfma_f32_16x16x32_bf16 v[48:51], v[136:139], v[186:189], 0
	v_mfma_f32_16x16x32_bf16 v[36:39], v[128:131], v[222:225], 0
	v_mfma_f32_16x16x32_bf16 v[32:35], v[136:139], v[222:225], 0
	v_mfma_f32_16x16x32_bf16 v[20:23], v[128:131], v[236:239], 0
	v_mfma_f32_16x16x32_bf16 v[16:19], v[136:139], v[236:239], 0
	v_mfma_f32_16x16x32_bf16 v[60:63], v[132:135], v[182:185], v[60:63]
	v_mfma_f32_16x16x32_bf16 v[56:59], v[140:143], v[182:185], v[56:59]
	v_mfma_f32_16x16x32_bf16 v[52:55], v[132:135], v[190:193], v[52:55]
	v_mfma_f32_16x16x32_bf16 v[48:51], v[140:143], v[190:193], v[48:51]
	v_mfma_f32_16x16x32_bf16 v[36:39], v[132:135], v[232:235], v[36:39]
	v_mfma_f32_16x16x32_bf16 v[32:35], v[140:143], v[232:235], v[32:35]
	v_mfma_f32_16x16x32_bf16 v[20:23], v[132:135], v[240:243], v[20:23]
	v_mfma_f32_16x16x32_bf16 v[16:19], v[140:143], v[240:243], v[16:19]
	v_mfma_f32_16x16x32_bf16 v[44:47], v[144:147], v[160:163], 0
	v_mfma_f32_16x16x32_bf16 v[40:43], v[152:155], v[160:163], 0
	v_mfma_f32_16x16x32_bf16 v[28:31], v[144:147], v[186:189], 0
	v_mfma_f32_16x16x32_bf16 v[24:27], v[152:155], v[186:189], 0
	v_mfma_f32_16x16x32_bf16 v[12:15], v[144:147], v[222:225], 0
	v_mfma_f32_16x16x32_bf16 v[8:11], v[152:155], v[222:225], 0
	v_mfma_f32_16x16x32_bf16 v[4:7], v[144:147], v[236:239], 0
	v_mfma_f32_16x16x32_bf16 v[0:3], v[152:155], v[236:239], 0
	v_mfma_f32_16x16x32_bf16 v[44:47], v[148:151], v[182:185], v[44:47]
	v_mfma_f32_16x16x32_bf16 v[40:43], v[156:159], v[182:185], v[40:43]
	v_mfma_f32_16x16x32_bf16 v[28:31], v[148:151], v[190:193], v[28:31]
	v_mfma_f32_16x16x32_bf16 v[24:27], v[156:159], v[190:193], v[24:27]
	v_mfma_f32_16x16x32_bf16 v[12:15], v[148:151], v[232:235], v[12:15]
	v_mfma_f32_16x16x32_bf16 v[8:11], v[156:159], v[232:235], v[8:11]
	v_mfma_f32_16x16x32_bf16 v[4:7], v[148:151], v[240:243], v[4:7]
	v_mfma_f32_16x16x32_bf16 v[0:3], v[156:159], v[240:243], v[0:3]
	s_barrier
	s_add_i32 s48, 0, 0x18000
	s_add_i32 s60, 0, 0x1c000
	v_add_u32_e32 v140, s48, v197
	v_add_u32_e32 v156, s60, v197
	ds_read_b128 v[128:131], v140
	ds_read_b128 v[132:135], v140 offset:1024
	ds_read_b128 v[136:139], v140 offset:2048
	ds_read_b128 v[140:143], v140 offset:3072
	ds_read_b128 v[144:147], v156
	ds_read_b128 v[148:151], v156 offset:1024
	ds_read_b128 v[152:155], v156 offset:2048
	ds_read_b128 v[156:159], v156 offset:3072
	s_add_u32 s58, s88, 0x80000
	s_addc_u32 s59, s89, 0
	s_mov_b32 m0, s9
	ds_read_b128 v[160:163], v216 offset:32768
	ds_read_b128 v[182:185], v216 offset:33792
	ds_read_b128 v[186:189], v216 offset:34816
	ds_read_b128 v[190:193], v216 offset:35840
	ds_read_b128 v[222:225], v216 offset:36864
	ds_read_b128 v[232:235], v216 offset:37888
	ds_read_b128 v[236:239], v216 offset:38912
	ds_read_b128 v[240:243], v216 offset:39936
	global_load_lds_dwordx4 v170, s[58:59]
	s_mov_b32 m0, s26
	s_nop 0
	global_load_lds_dwordx4 v166, s[58:59]
	s_waitcnt vmcnt(8)
	s_waitcnt lgkmcnt(0)
	s_barrier
	v_mfma_f32_16x16x32_bf16 v[124:127], v[128:131], v[160:163], v[124:127]
	v_mfma_f32_16x16x32_bf16 v[120:123], v[136:139], v[160:163], v[120:123]
	v_mfma_f32_16x16x32_bf16 v[116:119], v[128:131], v[186:189], v[116:119]
	v_mfma_f32_16x16x32_bf16 v[112:115], v[136:139], v[186:189], v[112:115]
	v_mfma_f32_16x16x32_bf16 v[100:103], v[128:131], v[222:225], v[100:103]
	v_mfma_f32_16x16x32_bf16 v[96:99], v[136:139], v[222:225], v[96:99]
	v_mfma_f32_16x16x32_bf16 v[84:87], v[128:131], v[236:239], v[84:87]
	v_mfma_f32_16x16x32_bf16 v[80:83], v[136:139], v[236:239], v[80:83]
	v_mfma_f32_16x16x32_bf16 v[124:127], v[132:135], v[182:185], v[124:127]
	v_mfma_f32_16x16x32_bf16 v[120:123], v[140:143], v[182:185], v[120:123]
	v_mfma_f32_16x16x32_bf16 v[116:119], v[132:135], v[190:193], v[116:119]
	v_mfma_f32_16x16x32_bf16 v[112:115], v[140:143], v[190:193], v[112:115]
	v_mfma_f32_16x16x32_bf16 v[100:103], v[132:135], v[232:235], v[100:103]
	v_mfma_f32_16x16x32_bf16 v[96:99], v[140:143], v[232:235], v[96:99]
	v_mfma_f32_16x16x32_bf16 v[84:87], v[132:135], v[240:243], v[84:87]
	v_mfma_f32_16x16x32_bf16 v[80:83], v[140:143], v[240:243], v[80:83]
	v_mfma_f32_16x16x32_bf16 v[108:111], v[144:147], v[160:163], v[108:111]
	v_mfma_f32_16x16x32_bf16 v[104:107], v[152:155], v[160:163], v[104:107]
	v_mfma_f32_16x16x32_bf16 v[92:95], v[144:147], v[186:189], v[92:95]
	v_mfma_f32_16x16x32_bf16 v[88:91], v[152:155], v[186:189], v[88:91]
	v_mfma_f32_16x16x32_bf16 v[76:79], v[144:147], v[222:225], v[76:79]
	v_mfma_f32_16x16x32_bf16 v[72:75], v[152:155], v[222:225], v[72:75]
	v_mfma_f32_16x16x32_bf16 v[68:71], v[144:147], v[236:239], v[68:71]
	v_mfma_f32_16x16x32_bf16 v[64:67], v[152:155], v[236:239], v[64:67]
	v_mfma_f32_16x16x32_bf16 v[108:111], v[148:151], v[182:185], v[108:111]
	v_mfma_f32_16x16x32_bf16 v[104:107], v[156:159], v[182:185], v[104:107]
	v_mfma_f32_16x16x32_bf16 v[92:95], v[148:151], v[190:193], v[92:95]
	v_mfma_f32_16x16x32_bf16 v[88:91], v[156:159], v[190:193], v[88:91]
	v_mfma_f32_16x16x32_bf16 v[76:79], v[148:151], v[232:235], v[76:79]
	v_mfma_f32_16x16x32_bf16 v[72:75], v[156:159], v[232:235], v[72:75]
	v_mfma_f32_16x16x32_bf16 v[68:71], v[148:151], v[240:243], v[68:71]
	v_mfma_f32_16x16x32_bf16 v[64:67], v[156:159], v[240:243], v[64:67]
	s_barrier
; #define PG8_STAGE(bufoff, gbase, voff) do { _Pragma("unroll") for (int _i = 0; _i < 2; ++_i) \
;         __builtin_amdgcn_global_load_lds((const unsigned*)((const char*)(gbase) + (voff)[_i]), (PG8_LAS unsigned*)(lds + (bufoff) + ldsw + _i * 8192), 16, 0, 0); } while (0)
; #define PG8_LDA(dst, b, h) do { _Pragma("unroll") for (int m = 0; m < 4; ++m) _Pragma("unroll") for (int k = 0; k < 2; ++k) dst[m][k] = *(const PG8_LAS bf16x8*)(lds + PG8_SA(b, h) + aoff + m * 2048 + k * 1024); } while (0)
; #define PG8_MMA(ai, bj, At, Bt) do { __builtin_amdgcn_s_setprio(1); _Pragma("unroll") for (int m = 0; m < 4; ++m) _Pragma("unroll") for (int n = 0; n < 2; ++n) _Pragma("unroll") for (int k = 0; k < 2; ++k) \
;         acc[ai][bj][m][n] = __builtin_amdgcn_mfma_f32_16x16x32_bf16(Bt[n][k], At[m][k], acc[ai][bj][m][n], 0, 0, 0); __builtin_amdgcn_s_setprio(0); } while (0)
; #define PG8_WAIT_V(n) asm volatile("s_waitcnt vmcnt(" #n ")" ::: "memory")
; #define PG8_WAIT_L(n) asm volatile("s_waitcnt lgkmcnt(" #n ")" ::: "memory")
; #define PG8_BAR __builtin_amdgcn_s_barrier()
; #define PG8_SCHED __builtin_amdgcn_sched_barrier(0)
; template <class Epi, class Sched, bool ALIGN_EPI = false, bool SP2 = false>
; __device__ __forceinline__ void gemm_phase(PG8_LAS unsigned char* lds, const Gemm g, const Sched& S, const Epi& E) {
;     ...
;         for (int t = 0; t < nt; t += 2) {
;     ...
;             PG8_LDA(At, 1, 1); PG8_STAGE(PG8_SB(1, 0), b3, voffB); PG8_STAGE(PG8_SB(1, 1), b3 + hstep, voffB); PG8_STAGE(PG8_SA(1, 0), a3, voffA);
;             PG8_WAIT_V(8); PG8_WAIT_L(0); PG8_BAR; PG8_MMA(1, 0, At, B0); PG8_MMA(1, 1, At, B1); PG8_BAR; PG8_SCHED;
	s_add_i32 s48, s48, s24
	v_lshl_add_u64 v[194:195], v[194:195], 0, s[54:55]
	s_mov_b32 m0, s48
	ds_read_b128 v[160:163], v216 offset:49152
	ds_read_b128 v[182:185], v216 offset:50176
	ds_read_b128 v[186:189], v216 offset:51200
	ds_read_b128 v[190:193], v216 offset:52224
	ds_read_b128 v[222:225], v216 offset:53248
	ds_read_b128 v[232:235], v216 offset:54272
	ds_read_b128 v[236:239], v216 offset:55296
	ds_read_b128 v[240:243], v216 offset:56320
	global_load_lds_dwordx4 v[194:195], off
	s_add_i32 m0, s48, 0x2000
	s_add_u32 s58, s86, 0x80080
	v_lshl_add_u64 v[194:195], v[230:231], 0, s[54:55]
	s_addc_u32 s59, s87, 0
	s_add_i32 s48, s60, s24
	global_load_lds_dwordx4 v[194:195], off
	s_mov_b32 m0, s48
	s_nop 0
	global_load_lds_dwordx4 v168, s[58:59]
	s_add_i32 m0, s48, 0x2000
	s_nop 0
	global_load_lds_dwordx4 v164, s[58:59]
	v_lshl_add_u64 v[194:195], v[244:245], 0, s[54:55]
	s_mov_b32 m0, s36
	s_nop 0
	global_load_lds_dwordx4 v[194:195], off
	v_lshl_add_u64 v[194:195], v[246:247], 0, s[54:55]
	s_mov_b32 m0, s37
	s_nop 0
	global_load_lds_dwordx4 v[194:195], off
	s_waitcnt vmcnt(8)
	s_waitcnt lgkmcnt(0)
	s_barrier
	v_mfma_f32_16x16x32_bf16 v[60:63], v[128:131], v[160:163], v[60:63]
	v_mfma_f32_16x16x32_bf16 v[56:59], v[136:139], v[160:163], v[56:59]
	v_mfma_f32_16x16x32_bf16 v[52:55], v[128:131], v[186:189], v[52:55]
	v_mfma_f32_16x16x32_bf16 v[48:51], v[136:139], v[186:189], v[48:51]
	v_mfma_f32_16x16x32_bf16 v[36:39], v[128:131], v[222:225], v[36:39]
	v_mfma_f32_16x16x32_bf16 v[32:35], v[136:139], v[222:225], v[32:35]
	v_mfma_f32_16x16x32_bf16 v[20:23], v[128:131], v[236:239], v[20:23]
	v_mfma_f32_16x16x32_bf16 v[16:19], v[136:139], v[236:239], v[16:19]
	v_mfma_f32_16x16x32_bf16 v[60:63], v[132:135], v[182:185], v[60:63]
	v_mfma_f32_16x16x32_bf16 v[56:59], v[140:143], v[182:185], v[56:59]
	v_mfma_f32_16x16x32_bf16 v[52:55], v[132:135], v[190:193], v[52:55]
	v_mfma_f32_16x16x32_bf16 v[48:51], v[140:143], v[190:193], v[48:51]
	v_mfma_f32_16x16x32_bf16 v[36:39], v[132:135], v[232:235], v[36:39]
	v_mfma_f32_16x16x32_bf16 v[32:35], v[140:143], v[232:235], v[32:35]
	v_mfma_f32_16x16x32_bf16 v[20:23], v[132:135], v[240:243], v[20:23]
	v_mfma_f32_16x16x32_bf16 v[16:19], v[140:143], v[240:243], v[16:19]
	v_mfma_f32_16x16x32_bf16 v[44:47], v[144:147], v[160:163], v[44:47]
	v_mfma_f32_16x16x32_bf16 v[40:43], v[152:155], v[160:163], v[40:43]
	v_mfma_f32_16x16x32_bf16 v[28:31], v[144:147], v[186:189], v[28:31]
	v_mfma_f32_16x16x32_bf16 v[24:27], v[152:155], v[186:189], v[24:27]
	v_mfma_f32_16x16x32_bf16 v[12:15], v[144:147], v[222:225], v[12:15]
	v_mfma_f32_16x16x32_bf16 v[8:11], v[152:155], v[222:225], v[8:11]
	v_mfma_f32_16x16x32_bf16 v[4:7], v[144:147], v[236:239], v[4:7]
	v_mfma_f32_16x16x32_bf16 v[0:3], v[152:155], v[236:239], v[0:3]
	v_mfma_f32_16x16x32_bf16 v[44:47], v[148:151], v[182:185], v[44:47]
	v_mfma_f32_16x16x32_bf16 v[40:43], v[156:159], v[182:185], v[40:43]
	v_mfma_f32_16x16x32_bf16 v[28:31], v[148:151], v[190:193], v[28:31]
	v_mfma_f32_16x16x32_bf16 v[24:27], v[156:159], v[190:193], v[24:27]
	v_mfma_f32_16x16x32_bf16 v[12:15], v[148:151], v[232:235], v[12:15]
	v_mfma_f32_16x16x32_bf16 v[8:11], v[156:159], v[232:235], v[8:11]
	v_mfma_f32_16x16x32_bf16 v[4:7], v[148:151], v[240:243], v[4:7]
	v_mfma_f32_16x16x32_bf16 v[0:3], v[156:159], v[240:243], v[0:3]
	s_barrier
	s_add_i32 s39, s39, 2
	s_add_u32 s84, s84, 0x100
	s_addc_u32 s85, s85, 0
	s_add_u32 vcc_hi, vcc_hi, 0x100
	s_addc_u32 s38, s38, 0
	s_cmp_gt_u32 s39, 29
	.p2align	6

; #define PG8_STAGE(bufoff, gbase, voff) do { _Pragma("unroll") for (int _i = 0; _i < 2; ++_i) \
;         __builtin_amdgcn_global_load_lds((const unsigned*)((const char*)(gbase) + (voff)[_i]), (PG8_LAS unsigned*)(lds + (bufoff) + ldsw + _i * 8192), 16, 0, 0); } while (0)
; #define PG8_LDA(dst, b, h) do { _Pragma("unroll") for (int m = 0; m < 4; ++m) _Pragma("unroll") for (int k = 0; k < 2; ++k) dst[m][k] = *(const PG8_LAS bf16x8*)(lds + PG8_SA(b, h) + aoff + m * 2048 + k * 1024); } while (0)
; #define PG8_LDB(dst, b, h) do { _Pragma("unroll") for (int n = 0; n < 2; ++n) _Pragma("unroll") for (int k = 0; k < 2; ++k) dst[n][k] = *(const PG8_LAS bf16x8*)(lds + PG8_SB(b, h) + boff + n * 2048 + k * 1024); } while (0)
; #define PG8_MMA(ai, bj, At, Bt) do { __builtin_amdgcn_s_setprio(1); _Pragma("unroll") for (int m = 0; m < 4; ++m) _Pragma("unroll") for (int n = 0; n < 2; ++n) _Pragma("unroll") for (int k = 0; k < 2; ++k) \
;         acc[ai][bj][m][n] = __builtin_amdgcn_mfma_f32_16x16x32_bf16(Bt[n][k], At[m][k], acc[ai][bj][m][n], 0, 0, 0); __builtin_amdgcn_s_setprio(0); } while (0)
; #define PG8_BAR __builtin_amdgcn_s_barrier()
; template <class Epi, class Sched, bool ALIGN_EPI = false, bool SP2 = false>
; __device__ __forceinline__ void gemm_phase(PG8_LAS unsigned char* lds, const Gemm g, const Sched& S, const Epi& E) {
;     ...
;         const bool has_next = S.next(ui + 1, nxt);
;         const char* nA = has_next ? (const char*)g.A + (size_t)nxt.pm * tstep : cA; const char* nB = has_next ? (const char*)g.Bt + (size_t)nxt.pn * tstep : cB;
;         for (int t = 0; t < nt; t += 2) {
;             const bool last = (t == nt - 2);
;             const char* a1 = cA + (size_t)(t + 1) * kstep;
;             const char* a2 = last ? nA : cA + (size_t)(t + 2) * kstep; const char* b2 = last ? nB : cB + (size_t)(t + 2) * kstep;
;             const char* a3 = a2 + kstep; const char* b3 = b2 + kstep;
;             if (last && has_next) S.a_ready(nxt);
;             if constexpr (SP2) {
;             PG8_LDB(B0, 0, 0); PG8_LDB(B1, 0, 1); PG8_SCHED; PG8_LDA(At, 0, 0); PG8_STAGE(PG8_SA(1, 1), a1 + hstep, voffA);
;             PG8_WAIT_V(8); PG8_WAIT_L(0); PG8_BAR; PG8_MMA(0, 0, At, B0); PG8_MMA(0, 1, At, B1); PG8_BAR; PG8_SCHED;
;             PG8_LDA(At, 0, 1); PG8_STAGE(PG8_SB(0, 0), b2, voffB); PG8_STAGE(PG8_SB(0, 1), b2 + hstep, voffB); PG8_STAGE(PG8_SA(0, 0), a2, voffA);
.LBB0_734:
	s_ashr_i32 s39, s38, 31
	v_cmp_lt_i64_e32 vcc, s[40:41], v[140:141]
	s_lshl_b64 s[40:41], s[38:39], 19
	s_add_u32 s40, s9, s40
	s_addc_u32 s41, s22, s41
	s_and_b64 s[42:43], vcc, exec
	s_cselect_b32 s39, s41, s47
	s_cselect_b32 s65, s40, s46
	s_ashr_i32 s37, s36, 31
	s_lshl_b64 s[42:43], s[36:37], 19
	s_add_u32 s42, s23, s42
	s_addc_u32 s43, s52, s43
	s_and_b64 s[50:51], vcc, exec
	s_cselect_b32 s37, s43, s49
	s_cselect_b32 s66, s42, s48
	s_add_u32 s46, s46, 0x40080
	s_addc_u32 s47, s47, 0
	s_add_u32 s67, s48, 0x100
	s_addc_u32 s68, s49, 0
	s_mov_b32 s69, -2
	ds_read_b128 v[144:147], v155
	ds_read_b128 v[148:151], v155 offset:1024
	ds_read_b128 v[158:161], v155 offset:2048
	ds_read_b128 v[162:165], v155 offset:3072
	ds_read_b128 v[166:169], v156
	ds_read_b128 v[170:173], v156 offset:1024
	ds_read_b128 v[174:177], v156 offset:2048
	ds_read_b128 v[178:181], v156 offset:3072
	s_add_u32 s48, s46, 0xfffc0080
	s_addc_u32 s49, s47, -1
	s_cmp_eq_u32 s69, 12
	s_cselect_b32 s51, s39, s49
	s_cselect_b32 s50, s65, s48
	s_cselect_b32 s49, s37, s68
	s_cselect_b32 s48, s66, s67
	s_add_i32 m0, s45, 0xc000
	ds_read_b128 v[182:185], v157
	ds_read_b128 v[186:189], v157 offset:1024
	ds_read_b128 v[190:193], v157 offset:2048
	ds_read_b128 v[194:197], v157 offset:3072
	ds_read_b128 v[198:201], v157 offset:4096
	ds_read_b128 v[202:205], v157 offset:5120
	ds_read_b128 v[206:209], v157 offset:6144
	ds_read_b128 v[214:217], v157 offset:7168
	global_load_lds_dwordx4 v136, s[46:47]
	s_add_i32 m0, s45, 0xe000
	s_nop 0
	global_load_lds_dwordx4 v138, s[46:47]
	s_waitcnt vmcnt(8)
	s_waitcnt lgkmcnt(0)
	s_barrier
	v_mfma_f32_16x16x32_bf16 v[124:127], v[144:147], v[182:185], 0
	v_mfma_f32_16x16x32_bf16 v[120:123], v[158:161], v[182:185], 0
	v_mfma_f32_16x16x32_bf16 v[116:119], v[144:147], v[190:193], 0
	v_mfma_f32_16x16x32_bf16 v[112:115], v[158:161], v[190:193], 0
	v_mfma_f32_16x16x32_bf16 v[96:99], v[144:147], v[198:201], 0
	v_mfma_f32_16x16x32_bf16 v[88:91], v[158:161], v[198:201], 0
	v_mfma_f32_16x16x32_bf16 v[80:83], v[144:147], v[206:209], 0
	v_mfma_f32_16x16x32_bf16 v[72:75], v[158:161], v[206:209], 0
	v_mfma_f32_16x16x32_bf16 v[124:127], v[148:151], v[186:189], v[124:127]
	v_mfma_f32_16x16x32_bf16 v[120:123], v[162:165], v[186:189], v[120:123]
	v_mfma_f32_16x16x32_bf16 v[116:119], v[148:151], v[194:197], v[116:119]
	v_mfma_f32_16x16x32_bf16 v[112:115], v[162:165], v[194:197], v[112:115]
	v_mfma_f32_16x16x32_bf16 v[96:99], v[148:151], v[202:205], v[96:99]
	v_mfma_f32_16x16x32_bf16 v[88:91], v[162:165], v[202:205], v[88:91]
	v_mfma_f32_16x16x32_bf16 v[80:83], v[148:151], v[214:217], v[80:83]
	v_mfma_f32_16x16x32_bf16 v[72:75], v[162:165], v[214:217], v[72:75]
	v_mfma_f32_16x16x32_bf16 v[108:111], v[166:169], v[182:185], 0
	v_mfma_f32_16x16x32_bf16 v[104:107], v[174:177], v[182:185], 0
	v_mfma_f32_16x16x32_bf16 v[100:103], v[166:169], v[190:193], 0
	v_mfma_f32_16x16x32_bf16 v[92:95], v[174:177], v[190:193], 0
	v_mfma_f32_16x16x32_bf16 v[84:87], v[166:169], v[198:201], 0
	v_mfma_f32_16x16x32_bf16 v[76:79], v[174:177], v[198:201], 0
	v_mfma_f32_16x16x32_bf16 v[68:71], v[166:169], v[206:209], 0
	v_mfma_f32_16x16x32_bf16 v[64:67], v[174:177], v[206:209], 0
	v_mfma_f32_16x16x32_bf16 v[108:111], v[170:173], v[186:189], v[108:111]
	v_mfma_f32_16x16x32_bf16 v[104:107], v[178:181], v[186:189], v[104:107]
	v_mfma_f32_16x16x32_bf16 v[100:103], v[170:173], v[194:197], v[100:103]
	v_mfma_f32_16x16x32_bf16 v[92:95], v[178:181], v[194:197], v[92:95]
	v_mfma_f32_16x16x32_bf16 v[84:87], v[170:173], v[202:205], v[84:87]
	v_mfma_f32_16x16x32_bf16 v[76:79], v[178:181], v[202:205], v[76:79]
	v_mfma_f32_16x16x32_bf16 v[68:71], v[170:173], v[214:217], v[68:71]
	v_mfma_f32_16x16x32_bf16 v[64:67], v[178:181], v[214:217], v[64:67]
	s_barrier
	s_add_i32 s70, s62, s53
	s_mov_b32 m0, s70
	ds_read_b128 v[182:185], v157 offset:16384
	ds_read_b128 v[186:189], v157 offset:17408
	ds_read_b128 v[190:193], v157 offset:18432
	ds_read_b128 v[194:197], v157 offset:19456
	ds_read_b128 v[198:201], v157 offset:20480
	ds_read_b128 v[202:205], v157 offset:21504
	ds_read_b128 v[206:209], v157 offset:22528
	ds_read_b128 v[214:217], v157 offset:23552
	global_load_lds_dwordx4 v130, s[48:49]
	s_add_i32 m0, s70, 0x2000
	s_add_u32 s70, s48, 0x40000
	s_addc_u32 s71, s49, 0
	s_add_i32 s72, s63, s53
	global_load_lds_dwordx4 v134, s[48:49]
	s_mov_b32 m0, s72
	s_nop 0
	global_load_lds_dwordx4 v130, s[70:71]
	s_add_i32 m0, s72, 0x2000
	s_nop 0
	global_load_lds_dwordx4 v134, s[70:71]
	s_mov_b32 m0, s45
	s_nop 0
	global_load_lds_dwordx4 v128, s[50:51]
	s_mov_b32 m0, s54
	s_nop 0
	global_load_lds_dwordx4 v132, s[50:51]
	s_waitcnt vmcnt(8)
	s_waitcnt lgkmcnt(0)
	s_barrier
; #define PG8_STAGE(bufoff, gbase, voff) do { _Pragma("unroll") for (int _i = 0; _i < 2; ++_i) \
;         __builtin_amdgcn_global_load_lds((const unsigned*)((const char*)(gbase) + (voff)[_i]), (PG8_LAS unsigned*)(lds + (bufoff) + ldsw + _i * 8192), 16, 0, 0); } while (0)
; #define PG8_LDA(dst, b, h) do { _Pragma("unroll") for (int m = 0; m < 4; ++m) _Pragma("unroll") for (int k = 0; k < 2; ++k) dst[m][k] = *(const PG8_LAS bf16x8*)(lds + PG8_SA(b, h) + aoff + m * 2048 + k * 1024); } while (0)
; #define PG8_LDB(dst, b, h) do { _Pragma("unroll") for (int n = 0; n < 2; ++n) _Pragma("unroll") for (int k = 0; k < 2; ++k) dst[n][k] = *(const PG8_LAS bf16x8*)(lds + PG8_SB(b, h) + boff + n * 2048 + k * 1024); } while (0)
; #define PG8_MMA(ai, bj, At, Bt) do { __builtin_amdgcn_s_setprio(1); _Pragma("unroll") for (int m = 0; m < 4; ++m) _Pragma("unroll") for (int n = 0; n < 2; ++n) _Pragma("unroll") for (int k = 0; k < 2; ++k) \
;         acc[ai][bj][m][n] = __builtin_amdgcn_mfma_f32_16x16x32_bf16(Bt[n][k], At[m][k], acc[ai][bj][m][n], 0, 0, 0); __builtin_amdgcn_s_setprio(0); } while (0)
; #define PG8_WAIT_V(n) asm volatile("s_waitcnt vmcnt(" #n ")" ::: "memory")
; #define PG8_WAIT_L(n) asm volatile("s_waitcnt lgkmcnt(" #n ")" ::: "memory")
; #define PG8_BAR __builtin_amdgcn_s_barrier()
; #define PG8_SCHED __builtin_amdgcn_sched_barrier(0)
; template <class Epi, class Sched, bool ALIGN_EPI = false, bool SP2 = false>
; __device__ __forceinline__ void gemm_phase(PG8_LAS unsigned char* lds, const Gemm g, const Sched& S, const Epi& E) {
;     ...
;             PG8_WAIT_V(8); PG8_WAIT_L(0); PG8_BAR; PG8_MMA(1, 0, At, B0); PG8_MMA(1, 1, At, B1); PG8_BAR; PG8_SCHED;
;             PG8_LDB(B0, 1, 0); PG8_LDB(B1, 1, 1); PG8_SCHED; PG8_LDA(At, 1, 0); PG8_STAGE(PG8_SA(0, 1), a2 + hstep, voffA);
;             PG8_WAIT_V(8); PG8_WAIT_L(0); PG8_BAR; PG8_MMA(0, 0, At, B0); PG8_MMA(0, 1, At, B1); PG8_BAR; PG8_SCHED;
	v_mfma_f32_16x16x32_bf16 v[60:63], v[144:147], v[182:185], 0
	v_mfma_f32_16x16x32_bf16 v[56:59], v[158:161], v[182:185], 0
	v_mfma_f32_16x16x32_bf16 v[48:51], v[144:147], v[190:193], 0
	v_mfma_f32_16x16x32_bf16 v[40:43], v[158:161], v[190:193], 0
	v_mfma_f32_16x16x32_bf16 v[32:35], v[144:147], v[198:201], 0
	v_mfma_f32_16x16x32_bf16 v[24:27], v[158:161], v[198:201], 0
	v_mfma_f32_16x16x32_bf16 v[16:19], v[144:147], v[206:209], 0
	v_mfma_f32_16x16x32_bf16 v[8:11], v[158:161], v[206:209], 0
	v_mfma_f32_16x16x32_bf16 v[60:63], v[148:151], v[186:189], v[60:63]
	v_mfma_f32_16x16x32_bf16 v[56:59], v[162:165], v[186:189], v[56:59]
	v_mfma_f32_16x16x32_bf16 v[48:51], v[148:151], v[194:197], v[48:51]
	v_mfma_f32_16x16x32_bf16 v[40:43], v[162:165], v[194:197], v[40:43]
	v_mfma_f32_16x16x32_bf16 v[32:35], v[148:151], v[202:205], v[32:35]
	v_mfma_f32_16x16x32_bf16 v[24:27], v[162:165], v[202:205], v[24:27]
	v_mfma_f32_16x16x32_bf16 v[16:19], v[148:151], v[214:217], v[16:19]
	v_mfma_f32_16x16x32_bf16 v[8:11], v[162:165], v[214:217], v[8:11]
	v_mfma_f32_16x16x32_bf16 v[52:55], v[166:169], v[182:185], 0
	v_mfma_f32_16x16x32_bf16 v[44:47], v[174:177], v[182:185], 0
	v_mfma_f32_16x16x32_bf16 v[36:39], v[166:169], v[190:193], 0
	v_mfma_f32_16x16x32_bf16 v[28:31], v[174:177], v[190:193], 0
	v_mfma_f32_16x16x32_bf16 v[20:23], v[166:169], v[198:201], 0
	v_mfma_f32_16x16x32_bf16 v[12:15], v[174:177], v[198:201], 0
	v_mfma_f32_16x16x32_bf16 v[4:7], v[166:169], v[206:209], 0
	v_mfma_f32_16x16x32_bf16 v[0:3], v[174:177], v[206:209], 0
	v_mfma_f32_16x16x32_bf16 v[52:55], v[170:173], v[186:189], v[52:55]
	v_mfma_f32_16x16x32_bf16 v[44:47], v[178:181], v[186:189], v[44:47]
	v_mfma_f32_16x16x32_bf16 v[36:39], v[170:173], v[194:197], v[36:39]
	v_mfma_f32_16x16x32_bf16 v[28:31], v[178:181], v[194:197], v[28:31]
	v_mfma_f32_16x16x32_bf16 v[20:23], v[170:173], v[202:205], v[20:23]
	v_mfma_f32_16x16x32_bf16 v[12:15], v[178:181], v[202:205], v[12:15]
	v_mfma_f32_16x16x32_bf16 v[4:7], v[170:173], v[214:217], v[4:7]
	v_mfma_f32_16x16x32_bf16 v[0:3], v[178:181], v[214:217], v[0:3]
	s_barrier
	s_add_i32 s70, 0, 0x18000
	s_add_i32 s71, 0, 0x1c000
	v_add_u32_e32 v162, s70, v153
	v_add_u32_e32 v178, s71, v153
	ds_read_b128 v[144:147], v162
	ds_read_b128 v[148:151], v162 offset:1024
	ds_read_b128 v[158:161], v162 offset:2048
	ds_read_b128 v[162:165], v162 offset:3072
	ds_read_b128 v[166:169], v178
	ds_read_b128 v[170:173], v178 offset:1024
	ds_read_b128 v[174:177], v178 offset:2048
	ds_read_b128 v[178:181], v178 offset:3072
	s_add_u32 s80, s50, 0x80
	s_addc_u32 s81, s51, 0
	s_add_u32 s50, s50, 0x40000
	s_addc_u32 s51, s51, 0
	s_mov_b32 m0, s55
	ds_read_b128 v[182:185], v157 offset:32768
	ds_read_b128 v[186:189], v157 offset:33792
	ds_read_b128 v[190:193], v157 offset:34816
	ds_read_b128 v[194:197], v157 offset:35840
	ds_read_b128 v[198:201], v157 offset:36864
	ds_read_b128 v[202:205], v157 offset:37888
	ds_read_b128 v[206:209], v157 offset:38912
	ds_read_b128 v[214:217], v157 offset:39936
	global_load_lds_dwordx4 v128, s[50:51]
	s_mov_b32 m0, s56
	s_nop 0
	global_load_lds_dwordx4 v132, s[50:51]
	s_waitcnt vmcnt(8)
	s_waitcnt lgkmcnt(0)
	s_barrier
	v_mfma_f32_16x16x32_bf16 v[124:127], v[144:147], v[182:185], v[124:127]
	v_mfma_f32_16x16x32_bf16 v[120:123], v[158:161], v[182:185], v[120:123]
	v_mfma_f32_16x16x32_bf16 v[116:119], v[144:147], v[190:193], v[116:119]
	v_mfma_f32_16x16x32_bf16 v[112:115], v[158:161], v[190:193], v[112:115]
	v_mfma_f32_16x16x32_bf16 v[96:99], v[144:147], v[198:201], v[96:99]
	v_mfma_f32_16x16x32_bf16 v[88:91], v[158:161], v[198:201], v[88:91]
	v_mfma_f32_16x16x32_bf16 v[80:83], v[144:147], v[206:209], v[80:83]
	v_mfma_f32_16x16x32_bf16 v[72:75], v[158:161], v[206:209], v[72:75]
	v_mfma_f32_16x16x32_bf16 v[124:127], v[148:151], v[186:189], v[124:127]
	v_mfma_f32_16x16x32_bf16 v[120:123], v[162:165], v[186:189], v[120:123]
	v_mfma_f32_16x16x32_bf16 v[116:119], v[148:151], v[194:197], v[116:119]
	v_mfma_f32_16x16x32_bf16 v[112:115], v[162:165], v[194:197], v[112:115]
	v_mfma_f32_16x16x32_bf16 v[96:99], v[148:151], v[202:205], v[96:99]
	v_mfma_f32_16x16x32_bf16 v[88:91], v[162:165], v[202:205], v[88:91]
	v_mfma_f32_16x16x32_bf16 v[80:83], v[148:151], v[214:217], v[80:83]
	v_mfma_f32_16x16x32_bf16 v[72:75], v[162:165], v[214:217], v[72:75]
	v_mfma_f32_16x16x32_bf16 v[108:111], v[166:169], v[182:185], v[108:111]
	v_mfma_f32_16x16x32_bf16 v[104:107], v[174:177], v[182:185], v[104:107]
	v_mfma_f32_16x16x32_bf16 v[100:103], v[166:169], v[190:193], v[100:103]
	v_mfma_f32_16x16x32_bf16 v[92:95], v[174:177], v[190:193], v[92:95]
	v_mfma_f32_16x16x32_bf16 v[84:87], v[166:169], v[198:201], v[84:87]
	v_mfma_f32_16x16x32_bf16 v[76:79], v[174:177], v[198:201], v[76:79]
	v_mfma_f32_16x16x32_bf16 v[68:71], v[166:169], v[206:209], v[68:71]
	v_mfma_f32_16x16x32_bf16 v[64:67], v[174:177], v[206:209], v[64:67]
	v_mfma_f32_16x16x32_bf16 v[108:111], v[170:173], v[186:189], v[108:111]
	v_mfma_f32_16x16x32_bf16 v[104:107], v[178:181], v[186:189], v[104:107]
	v_mfma_f32_16x16x32_bf16 v[100:103], v[170:173], v[194:197], v[100:103]
	v_mfma_f32_16x16x32_bf16 v[92:95], v[178:181], v[194:197], v[92:95]
	v_mfma_f32_16x16x32_bf16 v[84:87], v[170:173], v[202:205], v[84:87]
	v_mfma_f32_16x16x32_bf16 v[76:79], v[178:181], v[202:205], v[76:79]
	v_mfma_f32_16x16x32_bf16 v[68:71], v[170:173], v[214:217], v[68:71]
	v_mfma_f32_16x16x32_bf16 v[64:67], v[178:181], v[214:217], v[64:67]
	s_barrier
; #define PG8_STAGE(bufoff, gbase, voff) do { _Pragma("unroll") for (int _i = 0; _i < 2; ++_i) \
;         __builtin_amdgcn_global_load_lds((const unsigned*)((const char*)(gbase) + (voff)[_i]), (PG8_LAS unsigned*)(lds + (bufoff) + ldsw + _i * 8192), 16, 0, 0); } while (0)
; #define PG8_LDA(dst, b, h) do { _Pragma("unroll") for (int m = 0; m < 4; ++m) _Pragma("unroll") for (int k = 0; k < 2; ++k) dst[m][k] = *(const PG8_LAS bf16x8*)(lds + PG8_SA(b, h) + aoff + m * 2048 + k * 1024); } while (0)
; #define PG8_MMA(ai, bj, At, Bt) do { __builtin_amdgcn_s_setprio(1); _Pragma("unroll") for (int m = 0; m < 4; ++m) _Pragma("unroll") for (int n = 0; n < 2; ++n) _Pragma("unroll") for (int k = 0; k < 2; ++k) \
;         acc[ai][bj][m][n] = __builtin_amdgcn_mfma_f32_16x16x32_bf16(Bt[n][k], At[m][k], acc[ai][bj][m][n], 0, 0, 0); __builtin_amdgcn_s_setprio(0); } while (0)
; #define PG8_WAIT_V(n) asm volatile("s_waitcnt vmcnt(" #n ")" ::: "memory")
; #define PG8_WAIT_L(n) asm volatile("s_waitcnt lgkmcnt(" #n ")" ::: "memory")
; #define PG8_BAR __builtin_amdgcn_s_barrier()
; #define PG8_SCHED __builtin_amdgcn_sched_barrier(0)
; template <class Epi, class Sched, bool ALIGN_EPI = false, bool SP2 = false>
; __device__ __forceinline__ void gemm_phase(PG8_LAS unsigned char* lds, const Gemm g, const Sched& S, const Epi& E) {
;     ...
;         for (int t = 0; t < nt; t += 2) {
;     ...
;             PG8_LDA(At, 1, 1); PG8_STAGE(PG8_SB(1, 0), b3, voffB); PG8_STAGE(PG8_SB(1, 1), b3 + hstep, voffB); PG8_STAGE(PG8_SA(1, 0), a3, voffA);
;             PG8_WAIT_V(8); PG8_WAIT_L(0); PG8_BAR; PG8_MMA(1, 0, At, B0); PG8_MMA(1, 1, At, B1); PG8_BAR; PG8_SCHED;
	s_add_i32 s50, s70, s53
	s_add_u32 s82, s48, 0x80
	s_addc_u32 s83, s49, 0
	s_mov_b32 m0, s50
	ds_read_b128 v[182:185], v157 offset:49152
	ds_read_b128 v[186:189], v157 offset:50176
	ds_read_b128 v[190:193], v157 offset:51200
	ds_read_b128 v[194:197], v157 offset:52224
	ds_read_b128 v[198:201], v157 offset:53248
	ds_read_b128 v[202:205], v157 offset:54272
	ds_read_b128 v[206:209], v157 offset:55296
	ds_read_b128 v[214:217], v157 offset:56320
	global_load_lds_dwordx4 v130, s[82:83]
	s_add_i32 m0, s50, 0x2000
	s_add_u32 s48, s48, 0x40080
	s_addc_u32 s49, s49, 0
	s_add_i32 s50, s71, s53
	global_load_lds_dwordx4 v134, s[82:83]
	s_mov_b32 m0, s50
	s_nop 0
	global_load_lds_dwordx4 v130, s[48:49]
	s_add_i32 m0, s50, 0x2000
	s_nop 0
	global_load_lds_dwordx4 v134, s[48:49]
	s_mov_b32 m0, s58
	s_nop 0
	global_load_lds_dwordx4 v128, s[80:81]
	s_mov_b32 m0, s59
	s_nop 0
	global_load_lds_dwordx4 v132, s[80:81]
	s_waitcnt vmcnt(8)
	s_waitcnt lgkmcnt(0)
	s_barrier
	v_mfma_f32_16x16x32_bf16 v[60:63], v[144:147], v[182:185], v[60:63]
	v_mfma_f32_16x16x32_bf16 v[56:59], v[158:161], v[182:185], v[56:59]
	v_mfma_f32_16x16x32_bf16 v[48:51], v[144:147], v[190:193], v[48:51]
	v_mfma_f32_16x16x32_bf16 v[40:43], v[158:161], v[190:193], v[40:43]
	v_mfma_f32_16x16x32_bf16 v[32:35], v[144:147], v[198:201], v[32:35]
	v_mfma_f32_16x16x32_bf16 v[24:27], v[158:161], v[198:201], v[24:27]
	v_mfma_f32_16x16x32_bf16 v[16:19], v[144:147], v[206:209], v[16:19]
	v_mfma_f32_16x16x32_bf16 v[8:11], v[158:161], v[206:209], v[8:11]
	v_mfma_f32_16x16x32_bf16 v[60:63], v[148:151], v[186:189], v[60:63]
	v_mfma_f32_16x16x32_bf16 v[56:59], v[162:165], v[186:189], v[56:59]
	v_mfma_f32_16x16x32_bf16 v[48:51], v[148:151], v[194:197], v[48:51]
	v_mfma_f32_16x16x32_bf16 v[40:43], v[162:165], v[194:197], v[40:43]
	v_mfma_f32_16x16x32_bf16 v[32:35], v[148:151], v[202:205], v[32:35]
	v_mfma_f32_16x16x32_bf16 v[24:27], v[162:165], v[202:205], v[24:27]
	v_mfma_f32_16x16x32_bf16 v[16:19], v[148:151], v[214:217], v[16:19]
	v_mfma_f32_16x16x32_bf16 v[8:11], v[162:165], v[214:217], v[8:11]
	v_mfma_f32_16x16x32_bf16 v[52:55], v[166:169], v[182:185], v[52:55]
	v_mfma_f32_16x16x32_bf16 v[44:47], v[174:177], v[182:185], v[44:47]
	v_mfma_f32_16x16x32_bf16 v[36:39], v[166:169], v[190:193], v[36:39]
	v_mfma_f32_16x16x32_bf16 v[28:31], v[174:177], v[190:193], v[28:31]
	v_mfma_f32_16x16x32_bf16 v[20:23], v[166:169], v[198:201], v[20:23]
	v_mfma_f32_16x16x32_bf16 v[12:15], v[174:177], v[198:201], v[12:15]
	v_mfma_f32_16x16x32_bf16 v[4:7], v[166:169], v[206:209], v[4:7]
	v_mfma_f32_16x16x32_bf16 v[0:3], v[174:177], v[206:209], v[0:3]
	v_mfma_f32_16x16x32_bf16 v[52:55], v[170:173], v[186:189], v[52:55]
	v_mfma_f32_16x16x32_bf16 v[44:47], v[178:181], v[186:189], v[44:47]
	v_mfma_f32_16x16x32_bf16 v[36:39], v[170:173], v[194:197], v[36:39]
	v_mfma_f32_16x16x32_bf16 v[28:31], v[178:181], v[194:197], v[28:31]
	v_mfma_f32_16x16x32_bf16 v[20:23], v[170:173], v[202:205], v[20:23]
	v_mfma_f32_16x16x32_bf16 v[12:15], v[178:181], v[202:205], v[12:15]
	v_mfma_f32_16x16x32_bf16 v[4:7], v[170:173], v[214:217], v[4:7]
	v_mfma_f32_16x16x32_bf16 v[0:3], v[178:181], v[214:217], v[0:3]
	s_barrier
	s_add_i32 s69, s69, 2
	s_add_u32 s46, s46, 0x100
	s_addc_u32 s47, s47, 0
	s_add_u32 s67, s67, 0x100
	s_addc_u32 s68, s68, 0
	s_cmp_gt_u32 s69, 13
	.p2align	6

; #define PG8_STAGE(bufoff, gbase, voff) do { _Pragma("unroll") for (int _i = 0; _i < 2; ++_i) \
;         __builtin_amdgcn_global_load_lds((const unsigned*)((const char*)(gbase) + (voff)[_i]), (PG8_LAS unsigned*)(lds + (bufoff) + ldsw + _i * 8192), 16, 0, 0); } while (0)
; #define PG8_LDA(dst, b, h) do { _Pragma("unroll") for (int m = 0; m < 4; ++m) _Pragma("unroll") for (int k = 0; k < 2; ++k) dst[m][k] = *(const PG8_LAS bf16x8*)(lds + PG8_SA(b, h) + aoff + m * 2048 + k * 1024); } while (0)
; #define PG8_LDB(dst, b, h) do { _Pragma("unroll") for (int n = 0; n < 2; ++n) _Pragma("unroll") for (int k = 0; k < 2; ++k) dst[n][k] = *(const PG8_LAS bf16x8*)(lds + PG8_SB(b, h) + boff + n * 2048 + k * 1024); } while (0)
; #define PG8_MMA(ai, bj, At, Bt) do { __builtin_amdgcn_s_setprio(1); _Pragma("unroll") for (int m = 0; m < 4; ++m) _Pragma("unroll") for (int n = 0; n < 2; ++n) _Pragma("unroll") for (int k = 0; k < 2; ++k) \
;         acc[ai][bj][m][n] = __builtin_amdgcn_mfma_f32_16x16x32_bf16(Bt[n][k], At[m][k], acc[ai][bj][m][n], 0, 0, 0); __builtin_amdgcn_s_setprio(0); } while (0)
; #define PG8_BAR __builtin_amdgcn_s_barrier()
; template <class Epi, class Sched, bool ALIGN_EPI = false, bool SP2 = false>
; __device__ __forceinline__ void gemm_phase(PG8_LAS unsigned char* lds, const Gemm g, const Sched& S, const Epi& E) {
;     ...
;         const bool has_next = S.next(ui + 1, nxt);
;         const char* nA = has_next ? (const char*)g.A + (size_t)nxt.pm * tstep : cA; const char* nB = has_next ? (const char*)g.Bt + (size_t)nxt.pn * tstep : cB;
;         for (int t = 0; t < nt; t += 2) {
;             const bool last = (t == nt - 2);
;             const char* a1 = cA + (size_t)(t + 1) * kstep;
;             const char* a2 = last ? nA : cA + (size_t)(t + 2) * kstep; const char* b2 = last ? nB : cB + (size_t)(t + 2) * kstep;
;             const char* a3 = a2 + kstep; const char* b3 = b2 + kstep;
;             if (last && has_next) S.a_ready(nxt);
;             if constexpr (SP2) {
;             PG8_LDB(B0, 0, 0); PG8_LDB(B1, 0, 1); PG8_SCHED; PG8_LDA(At, 0, 0); PG8_STAGE(PG8_SA(1, 1), a1 + hstep, voffA);
;             PG8_WAIT_V(8); PG8_WAIT_L(0); PG8_BAR; PG8_MMA(0, 0, At, B0); PG8_MMA(0, 1, At, B1); PG8_BAR; PG8_SCHED;
;             PG8_LDA(At, 0, 1); PG8_STAGE(PG8_SB(0, 0), b2, voffB); PG8_STAGE(PG8_SB(0, 1), b2 + hstep, voffB); PG8_STAGE(PG8_SA(0, 0), a2, voffA);
.LBB0_754:
	s_ashr_i32 s29, s28, 31
	v_cmp_lt_i64_e32 vcc, s[30:31], v[160:161]
	s_lshl_b64 s[30:31], s[28:29], 19
	s_add_u32 s30, s9, s30
	s_addc_u32 s31, s22, s31
	s_and_b64 s[34:35], vcc, exec
	s_cselect_b32 s29, s31, s39
	s_cselect_b32 s57, s30, s38
	s_ashr_i32 s27, s26, 31
	s_lshl_b64 s[34:35], s[26:27], 19
	s_add_u32 s34, s23, s34
	s_addc_u32 s35, s44, s35
	s_and_b64 s[42:43], vcc, exec
	s_cselect_b32 s27, s35, s41
	s_cselect_b32 s58, s34, s40
	s_add_u32 s38, s38, 0x40080
	s_addc_u32 s39, s39, 0
	s_add_u32 s59, s40, 0x100
	s_addc_u32 s60, s41, 0
	s_mov_b32 s61, -2
	ds_read_b128 v[128:131], v177
	ds_read_b128 v[132:135], v177 offset:1024
	ds_read_b128 v[136:139], v177 offset:2048
	ds_read_b128 v[140:143], v177 offset:3072
	ds_read_b128 v[144:147], v178
	ds_read_b128 v[164:167], v178 offset:1024
	ds_read_b128 v[168:171], v178 offset:2048
	ds_read_b128 v[180:183], v178 offset:3072
	s_add_u32 s40, s38, 0xfffc0080
	s_addc_u32 s41, s39, -1
	s_cmp_eq_u32 s61, 12
	s_cselect_b32 s43, s29, s41
	s_cselect_b32 s42, s57, s40
	s_cselect_b32 s41, s27, s60
	s_cselect_b32 s40, s58, s59
	s_add_i32 m0, s37, 0xc000
	ds_read_b128 v[184:187], v179
	ds_read_b128 v[188:191], v179 offset:1024
	ds_read_b128 v[192:195], v179 offset:2048
	ds_read_b128 v[196:199], v179 offset:3072
	ds_read_b128 v[200:203], v179 offset:4096
	ds_read_b128 v[204:207], v179 offset:5120
	ds_read_b128 v[208:211], v179 offset:6144
	ds_read_b128 v[214:217], v179 offset:7168
	global_load_lds_dwordx4 v156, s[38:39]
	s_add_i32 m0, s37, 0xe000
	s_nop 0
	global_load_lds_dwordx4 v158, s[38:39]
	s_waitcnt vmcnt(8)
	s_waitcnt lgkmcnt(0)
	s_barrier
	v_mfma_f32_16x16x32_bf16 v[124:127], v[128:131], v[184:187], 0
	v_mfma_f32_16x16x32_bf16 v[120:123], v[136:139], v[184:187], 0
	v_mfma_f32_16x16x32_bf16 v[108:111], v[128:131], v[192:195], 0
	v_mfma_f32_16x16x32_bf16 v[104:107], v[136:139], v[192:195], 0
	v_mfma_f32_16x16x32_bf16 v[92:95], v[128:131], v[200:203], 0
	v_mfma_f32_16x16x32_bf16 v[88:91], v[136:139], v[200:203], 0
	v_mfma_f32_16x16x32_bf16 v[76:79], v[128:131], v[208:211], 0
	v_mfma_f32_16x16x32_bf16 v[72:75], v[136:139], v[208:211], 0
	v_mfma_f32_16x16x32_bf16 v[124:127], v[132:135], v[188:191], v[124:127]
	v_mfma_f32_16x16x32_bf16 v[120:123], v[140:143], v[188:191], v[120:123]
	v_mfma_f32_16x16x32_bf16 v[108:111], v[132:135], v[196:199], v[108:111]
	v_mfma_f32_16x16x32_bf16 v[104:107], v[140:143], v[196:199], v[104:107]
	v_mfma_f32_16x16x32_bf16 v[92:95], v[132:135], v[204:207], v[92:95]
	v_mfma_f32_16x16x32_bf16 v[88:91], v[140:143], v[204:207], v[88:91]
	v_mfma_f32_16x16x32_bf16 v[76:79], v[132:135], v[214:217], v[76:79]
	v_mfma_f32_16x16x32_bf16 v[72:75], v[140:143], v[214:217], v[72:75]
	v_mfma_f32_16x16x32_bf16 v[116:119], v[144:147], v[184:187], 0
	v_mfma_f32_16x16x32_bf16 v[112:115], v[168:171], v[184:187], 0
	v_mfma_f32_16x16x32_bf16 v[100:103], v[144:147], v[192:195], 0
	v_mfma_f32_16x16x32_bf16 v[96:99], v[168:171], v[192:195], 0
	v_mfma_f32_16x16x32_bf16 v[84:87], v[144:147], v[200:203], 0
	v_mfma_f32_16x16x32_bf16 v[80:83], v[168:171], v[200:203], 0
	v_mfma_f32_16x16x32_bf16 v[68:71], v[144:147], v[208:211], 0
	v_mfma_f32_16x16x32_bf16 v[64:67], v[168:171], v[208:211], 0
	v_mfma_f32_16x16x32_bf16 v[116:119], v[164:167], v[188:191], v[116:119]
	v_mfma_f32_16x16x32_bf16 v[112:115], v[180:183], v[188:191], v[112:115]
	v_mfma_f32_16x16x32_bf16 v[100:103], v[164:167], v[196:199], v[100:103]
	v_mfma_f32_16x16x32_bf16 v[96:99], v[180:183], v[196:199], v[96:99]
	v_mfma_f32_16x16x32_bf16 v[84:87], v[164:167], v[204:207], v[84:87]
	v_mfma_f32_16x16x32_bf16 v[80:83], v[180:183], v[204:207], v[80:83]
	v_mfma_f32_16x16x32_bf16 v[68:71], v[164:167], v[214:217], v[68:71]
	v_mfma_f32_16x16x32_bf16 v[64:67], v[180:183], v[214:217], v[64:67]
	s_barrier
	s_add_i32 s62, s54, s45
	s_mov_b32 m0, s62
	ds_read_b128 v[184:187], v179 offset:16384
	ds_read_b128 v[188:191], v179 offset:17408
	ds_read_b128 v[192:195], v179 offset:18432
	ds_read_b128 v[196:199], v179 offset:19456
	ds_read_b128 v[200:203], v179 offset:20480
	ds_read_b128 v[204:207], v179 offset:21504
	ds_read_b128 v[208:211], v179 offset:22528
	ds_read_b128 v[214:217], v179 offset:23552
	global_load_lds_dwordx4 v150, s[40:41]
	s_add_i32 m0, s62, 0x2000
	s_add_u32 s62, s40, 0x40000
	s_addc_u32 s63, s41, 0
	s_add_i32 s64, s55, s45
	global_load_lds_dwordx4 v154, s[40:41]
	s_mov_b32 m0, s64
	s_nop 0
	global_load_lds_dwordx4 v150, s[62:63]
	s_add_i32 m0, s64, 0x2000
	s_nop 0
	global_load_lds_dwordx4 v154, s[62:63]
	s_mov_b32 m0, s37
	s_nop 0
	global_load_lds_dwordx4 v148, s[42:43]
	s_mov_b32 m0, s46
	s_nop 0
	global_load_lds_dwordx4 v152, s[42:43]
	s_waitcnt vmcnt(8)
	s_waitcnt lgkmcnt(0)
	s_barrier
; #define PG8_STAGE(bufoff, gbase, voff) do { _Pragma("unroll") for (int _i = 0; _i < 2; ++_i) \
;         __builtin_amdgcn_global_load_lds((const unsigned*)((const char*)(gbase) + (voff)[_i]), (PG8_LAS unsigned*)(lds + (bufoff) + ldsw + _i * 8192), 16, 0, 0); } while (0)
; #define PG8_LDA(dst, b, h) do { _Pragma("unroll") for (int m = 0; m < 4; ++m) _Pragma("unroll") for (int k = 0; k < 2; ++k) dst[m][k] = *(const PG8_LAS bf16x8*)(lds + PG8_SA(b, h) + aoff + m * 2048 + k * 1024); } while (0)
; #define PG8_LDB(dst, b, h) do { _Pragma("unroll") for (int n = 0; n < 2; ++n) _Pragma("unroll") for (int k = 0; k < 2; ++k) dst[n][k] = *(const PG8_LAS bf16x8*)(lds + PG8_SB(b, h) + boff + n * 2048 + k * 1024); } while (0)
; #define PG8_MMA(ai, bj, At, Bt) do { __builtin_amdgcn_s_setprio(1); _Pragma("unroll") for (int m = 0; m < 4; ++m) _Pragma("unroll") for (int n = 0; n < 2; ++n) _Pragma("unroll") for (int k = 0; k < 2; ++k) \
;         acc[ai][bj][m][n] = __builtin_amdgcn_mfma_f32_16x16x32_bf16(Bt[n][k], At[m][k], acc[ai][bj][m][n], 0, 0, 0); __builtin_amdgcn_s_setprio(0); } while (0)
; #define PG8_WAIT_V(n) asm volatile("s_waitcnt vmcnt(" #n ")" ::: "memory")
; #define PG8_WAIT_L(n) asm volatile("s_waitcnt lgkmcnt(" #n ")" ::: "memory")
; #define PG8_BAR __builtin_amdgcn_s_barrier()
; #define PG8_SCHED __builtin_amdgcn_sched_barrier(0)
; template <class Epi, class Sched, bool ALIGN_EPI = false, bool SP2 = false>
; __device__ __forceinline__ void gemm_phase(PG8_LAS unsigned char* lds, const Gemm g, const Sched& S, const Epi& E) {
;     ...
;             PG8_WAIT_V(8); PG8_WAIT_L(0); PG8_BAR; PG8_MMA(1, 0, At, B0); PG8_MMA(1, 1, At, B1); PG8_BAR; PG8_SCHED;
;             PG8_LDB(B0, 1, 0); PG8_LDB(B1, 1, 1); PG8_SCHED; PG8_LDA(At, 1, 0); PG8_STAGE(PG8_SA(0, 1), a2 + hstep, voffA);
;             PG8_WAIT_V(8); PG8_WAIT_L(0); PG8_BAR; PG8_MMA(0, 0, At, B0); PG8_MMA(0, 1, At, B1); PG8_BAR; PG8_SCHED;
	v_mfma_f32_16x16x32_bf16 v[60:63], v[128:131], v[184:187], 0
	v_mfma_f32_16x16x32_bf16 v[56:59], v[136:139], v[184:187], 0
	v_mfma_f32_16x16x32_bf16 v[44:47], v[128:131], v[192:195], 0
	v_mfma_f32_16x16x32_bf16 v[40:43], v[136:139], v[192:195], 0
	v_mfma_f32_16x16x32_bf16 v[28:31], v[128:131], v[200:203], 0
	v_mfma_f32_16x16x32_bf16 v[24:27], v[136:139], v[200:203], 0
	v_mfma_f32_16x16x32_bf16 v[12:15], v[128:131], v[208:211], 0
	v_mfma_f32_16x16x32_bf16 v[8:11], v[136:139], v[208:211], 0
	v_mfma_f32_16x16x32_bf16 v[60:63], v[132:135], v[188:191], v[60:63]
	v_mfma_f32_16x16x32_bf16 v[56:59], v[140:143], v[188:191], v[56:59]
	v_mfma_f32_16x16x32_bf16 v[44:47], v[132:135], v[196:199], v[44:47]
	v_mfma_f32_16x16x32_bf16 v[40:43], v[140:143], v[196:199], v[40:43]
	v_mfma_f32_16x16x32_bf16 v[28:31], v[132:135], v[204:207], v[28:31]
	v_mfma_f32_16x16x32_bf16 v[24:27], v[140:143], v[204:207], v[24:27]
	v_mfma_f32_16x16x32_bf16 v[12:15], v[132:135], v[214:217], v[12:15]
	v_mfma_f32_16x16x32_bf16 v[8:11], v[140:143], v[214:217], v[8:11]
	v_mfma_f32_16x16x32_bf16 v[52:55], v[144:147], v[184:187], 0
	v_mfma_f32_16x16x32_bf16 v[48:51], v[168:171], v[184:187], 0
	v_mfma_f32_16x16x32_bf16 v[36:39], v[144:147], v[192:195], 0
	v_mfma_f32_16x16x32_bf16 v[32:35], v[168:171], v[192:195], 0
	v_mfma_f32_16x16x32_bf16 v[20:23], v[144:147], v[200:203], 0
	v_mfma_f32_16x16x32_bf16 v[16:19], v[168:171], v[200:203], 0
	v_mfma_f32_16x16x32_bf16 v[4:7], v[144:147], v[208:211], 0
	v_mfma_f32_16x16x32_bf16 v[0:3], v[168:171], v[208:211], 0
	v_mfma_f32_16x16x32_bf16 v[52:55], v[164:167], v[188:191], v[52:55]
	v_mfma_f32_16x16x32_bf16 v[48:51], v[180:183], v[188:191], v[48:51]
	v_mfma_f32_16x16x32_bf16 v[36:39], v[164:167], v[196:199], v[36:39]
	v_mfma_f32_16x16x32_bf16 v[32:35], v[180:183], v[196:199], v[32:35]
	v_mfma_f32_16x16x32_bf16 v[20:23], v[164:167], v[204:207], v[20:23]
	v_mfma_f32_16x16x32_bf16 v[16:19], v[180:183], v[204:207], v[16:19]
	v_mfma_f32_16x16x32_bf16 v[4:7], v[164:167], v[214:217], v[4:7]
	v_mfma_f32_16x16x32_bf16 v[0:3], v[180:183], v[214:217], v[0:3]
	s_barrier
	s_add_i32 s62, 0, 0x18000
	s_add_i32 s63, 0, 0x1c000
	v_add_u32_e32 v140, s62, v175
	v_add_u32_e32 v180, s63, v175
	ds_read_b128 v[128:131], v140
	ds_read_b128 v[132:135], v140 offset:1024
	ds_read_b128 v[136:139], v140 offset:2048
	ds_read_b128 v[140:143], v140 offset:3072
	ds_read_b128 v[144:147], v180
	ds_read_b128 v[164:167], v180 offset:1024
	ds_read_b128 v[168:171], v180 offset:2048
	ds_read_b128 v[180:183], v180 offset:3072
	s_add_u32 s84, s42, 0x80
	s_addc_u32 s85, s43, 0
	s_add_u32 s42, s42, 0x40000
	s_addc_u32 s43, s43, 0
	s_mov_b32 m0, s47
	ds_read_b128 v[184:187], v179 offset:32768
	ds_read_b128 v[188:191], v179 offset:33792
	ds_read_b128 v[192:195], v179 offset:34816
	ds_read_b128 v[196:199], v179 offset:35840
	ds_read_b128 v[200:203], v179 offset:36864
	ds_read_b128 v[204:207], v179 offset:37888
	ds_read_b128 v[208:211], v179 offset:38912
	ds_read_b128 v[214:217], v179 offset:39936
	global_load_lds_dwordx4 v148, s[42:43]
	s_mov_b32 m0, s48
	s_nop 0
	global_load_lds_dwordx4 v152, s[42:43]
	s_waitcnt vmcnt(8)
	s_waitcnt lgkmcnt(0)
	s_barrier
	v_mfma_f32_16x16x32_bf16 v[124:127], v[128:131], v[184:187], v[124:127]
	v_mfma_f32_16x16x32_bf16 v[120:123], v[136:139], v[184:187], v[120:123]
	v_mfma_f32_16x16x32_bf16 v[108:111], v[128:131], v[192:195], v[108:111]
	v_mfma_f32_16x16x32_bf16 v[104:107], v[136:139], v[192:195], v[104:107]
	v_mfma_f32_16x16x32_bf16 v[92:95], v[128:131], v[200:203], v[92:95]
	v_mfma_f32_16x16x32_bf16 v[88:91], v[136:139], v[200:203], v[88:91]
	v_mfma_f32_16x16x32_bf16 v[76:79], v[128:131], v[208:211], v[76:79]
	v_mfma_f32_16x16x32_bf16 v[72:75], v[136:139], v[208:211], v[72:75]
	v_mfma_f32_16x16x32_bf16 v[124:127], v[132:135], v[188:191], v[124:127]
	v_mfma_f32_16x16x32_bf16 v[120:123], v[140:143], v[188:191], v[120:123]
	v_mfma_f32_16x16x32_bf16 v[108:111], v[132:135], v[196:199], v[108:111]
	v_mfma_f32_16x16x32_bf16 v[104:107], v[140:143], v[196:199], v[104:107]
	v_mfma_f32_16x16x32_bf16 v[92:95], v[132:135], v[204:207], v[92:95]
	v_mfma_f32_16x16x32_bf16 v[88:91], v[140:143], v[204:207], v[88:91]
	v_mfma_f32_16x16x32_bf16 v[76:79], v[132:135], v[214:217], v[76:79]
	v_mfma_f32_16x16x32_bf16 v[72:75], v[140:143], v[214:217], v[72:75]
	v_mfma_f32_16x16x32_bf16 v[116:119], v[144:147], v[184:187], v[116:119]
	v_mfma_f32_16x16x32_bf16 v[112:115], v[168:171], v[184:187], v[112:115]
	v_mfma_f32_16x16x32_bf16 v[100:103], v[144:147], v[192:195], v[100:103]
	v_mfma_f32_16x16x32_bf16 v[96:99], v[168:171], v[192:195], v[96:99]
	v_mfma_f32_16x16x32_bf16 v[84:87], v[144:147], v[200:203], v[84:87]
	v_mfma_f32_16x16x32_bf16 v[80:83], v[168:171], v[200:203], v[80:83]
	v_mfma_f32_16x16x32_bf16 v[68:71], v[144:147], v[208:211], v[68:71]
	v_mfma_f32_16x16x32_bf16 v[64:67], v[168:171], v[208:211], v[64:67]
	v_mfma_f32_16x16x32_bf16 v[116:119], v[164:167], v[188:191], v[116:119]
	v_mfma_f32_16x16x32_bf16 v[112:115], v[180:183], v[188:191], v[112:115]
	v_mfma_f32_16x16x32_bf16 v[100:103], v[164:167], v[196:199], v[100:103]
	v_mfma_f32_16x16x32_bf16 v[96:99], v[180:183], v[196:199], v[96:99]
	v_mfma_f32_16x16x32_bf16 v[84:87], v[164:167], v[204:207], v[84:87]
	v_mfma_f32_16x16x32_bf16 v[80:83], v[180:183], v[204:207], v[80:83]
	v_mfma_f32_16x16x32_bf16 v[68:71], v[164:167], v[214:217], v[68:71]
	v_mfma_f32_16x16x32_bf16 v[64:67], v[180:183], v[214:217], v[64:67]
	s_barrier
; #define PG8_STAGE(bufoff, gbase, voff) do { _Pragma("unroll") for (int _i = 0; _i < 2; ++_i) \
;         __builtin_amdgcn_global_load_lds((const unsigned*)((const char*)(gbase) + (voff)[_i]), (PG8_LAS unsigned*)(lds + (bufoff) + ldsw + _i * 8192), 16, 0, 0); } while (0)
; #define PG8_LDA(dst, b, h) do { _Pragma("unroll") for (int m = 0; m < 4; ++m) _Pragma("unroll") for (int k = 0; k < 2; ++k) dst[m][k] = *(const PG8_LAS bf16x8*)(lds + PG8_SA(b, h) + aoff + m * 2048 + k * 1024); } while (0)
; #define PG8_MMA(ai, bj, At, Bt) do { __builtin_amdgcn_s_setprio(1); _Pragma("unroll") for (int m = 0; m < 4; ++m) _Pragma("unroll") for (int n = 0; n < 2; ++n) _Pragma("unroll") for (int k = 0; k < 2; ++k) \
;         acc[ai][bj][m][n] = __builtin_amdgcn_mfma_f32_16x16x32_bf16(Bt[n][k], At[m][k], acc[ai][bj][m][n], 0, 0, 0); __builtin_amdgcn_s_setprio(0); } while (0)
; #define PG8_WAIT_V(n) asm volatile("s_waitcnt vmcnt(" #n ")" ::: "memory")
; #define PG8_WAIT_L(n) asm volatile("s_waitcnt lgkmcnt(" #n ")" ::: "memory")
; #define PG8_BAR __builtin_amdgcn_s_barrier()
; #define PG8_SCHED __builtin_amdgcn_sched_barrier(0)
; template <class Epi, class Sched, bool ALIGN_EPI = false, bool SP2 = false>
; __device__ __forceinline__ void gemm_phase(PG8_LAS unsigned char* lds, const Gemm g, const Sched& S, const Epi& E) {
;     ...
;         for (int t = 0; t < nt; t += 2) {
;     ...
;             PG8_LDA(At, 1, 1); PG8_STAGE(PG8_SB(1, 0), b3, voffB); PG8_STAGE(PG8_SB(1, 1), b3 + hstep, voffB); PG8_STAGE(PG8_SA(1, 0), a3, voffA);
;             PG8_WAIT_V(8); PG8_WAIT_L(0); PG8_BAR; PG8_MMA(1, 0, At, B0); PG8_MMA(1, 1, At, B1); PG8_BAR; PG8_SCHED;
	s_add_i32 s42, s62, s45
	s_add_u32 s86, s40, 0x80
	s_addc_u32 s87, s41, 0
	s_mov_b32 m0, s42
	ds_read_b128 v[184:187], v179 offset:49152
	ds_read_b128 v[188:191], v179 offset:50176
	ds_read_b128 v[192:195], v179 offset:51200
	ds_read_b128 v[196:199], v179 offset:52224
	ds_read_b128 v[200:203], v179 offset:53248
	ds_read_b128 v[204:207], v179 offset:54272
	ds_read_b128 v[208:211], v179 offset:55296
	ds_read_b128 v[214:217], v179 offset:56320
	global_load_lds_dwordx4 v150, s[86:87]
	s_add_i32 m0, s42, 0x2000
	s_add_u32 s40, s40, 0x40080
	s_addc_u32 s41, s41, 0
	s_add_i32 s42, s63, s45
	global_load_lds_dwordx4 v154, s[86:87]
	s_mov_b32 m0, s42
	s_nop 0
	global_load_lds_dwordx4 v150, s[40:41]
	s_add_i32 m0, s42, 0x2000
	s_nop 0
	global_load_lds_dwordx4 v154, s[40:41]
	s_mov_b32 m0, s50
	s_nop 0
	global_load_lds_dwordx4 v148, s[84:85]
	s_mov_b32 m0, s51
	s_nop 0
	global_load_lds_dwordx4 v152, s[84:85]
	s_waitcnt vmcnt(8)
	s_waitcnt lgkmcnt(0)
	s_barrier
	v_mfma_f32_16x16x32_bf16 v[60:63], v[128:131], v[184:187], v[60:63]
	v_mfma_f32_16x16x32_bf16 v[56:59], v[136:139], v[184:187], v[56:59]
	v_mfma_f32_16x16x32_bf16 v[44:47], v[128:131], v[192:195], v[44:47]
	v_mfma_f32_16x16x32_bf16 v[40:43], v[136:139], v[192:195], v[40:43]
	v_mfma_f32_16x16x32_bf16 v[28:31], v[128:131], v[200:203], v[28:31]
	v_mfma_f32_16x16x32_bf16 v[24:27], v[136:139], v[200:203], v[24:27]
	v_mfma_f32_16x16x32_bf16 v[12:15], v[128:131], v[208:211], v[12:15]
	v_mfma_f32_16x16x32_bf16 v[8:11], v[136:139], v[208:211], v[8:11]
	v_mfma_f32_16x16x32_bf16 v[60:63], v[132:135], v[188:191], v[60:63]
	v_mfma_f32_16x16x32_bf16 v[56:59], v[140:143], v[188:191], v[56:59]
	v_mfma_f32_16x16x32_bf16 v[44:47], v[132:135], v[196:199], v[44:47]
	v_mfma_f32_16x16x32_bf16 v[40:43], v[140:143], v[196:199], v[40:43]
	v_mfma_f32_16x16x32_bf16 v[28:31], v[132:135], v[204:207], v[28:31]
	v_mfma_f32_16x16x32_bf16 v[24:27], v[140:143], v[204:207], v[24:27]
	v_mfma_f32_16x16x32_bf16 v[12:15], v[132:135], v[214:217], v[12:15]
	v_mfma_f32_16x16x32_bf16 v[8:11], v[140:143], v[214:217], v[8:11]
	v_mfma_f32_16x16x32_bf16 v[52:55], v[144:147], v[184:187], v[52:55]
	v_mfma_f32_16x16x32_bf16 v[48:51], v[168:171], v[184:187], v[48:51]
	v_mfma_f32_16x16x32_bf16 v[36:39], v[144:147], v[192:195], v[36:39]
	v_mfma_f32_16x16x32_bf16 v[32:35], v[168:171], v[192:195], v[32:35]
	v_mfma_f32_16x16x32_bf16 v[20:23], v[144:147], v[200:203], v[20:23]
	v_mfma_f32_16x16x32_bf16 v[16:19], v[168:171], v[200:203], v[16:19]
	v_mfma_f32_16x16x32_bf16 v[4:7], v[144:147], v[208:211], v[4:7]
	v_mfma_f32_16x16x32_bf16 v[0:3], v[168:171], v[208:211], v[0:3]
	v_mfma_f32_16x16x32_bf16 v[52:55], v[164:167], v[188:191], v[52:55]
	v_mfma_f32_16x16x32_bf16 v[48:51], v[180:183], v[188:191], v[48:51]
	v_mfma_f32_16x16x32_bf16 v[36:39], v[164:167], v[196:199], v[36:39]
	v_mfma_f32_16x16x32_bf16 v[32:35], v[180:183], v[196:199], v[32:35]
	v_mfma_f32_16x16x32_bf16 v[20:23], v[164:167], v[204:207], v[20:23]
	v_mfma_f32_16x16x32_bf16 v[16:19], v[180:183], v[204:207], v[16:19]
	v_mfma_f32_16x16x32_bf16 v[4:7], v[164:167], v[214:217], v[4:7]
	v_mfma_f32_16x16x32_bf16 v[0:3], v[180:183], v[214:217], v[0:3]
	s_barrier
	s_add_i32 s61, s61, 2
	s_add_u32 s38, s38, 0x100
	s_addc_u32 s39, s39, 0
	s_add_u32 s59, s59, 0x100
	s_addc_u32 s60, s60, 0
	s_cmp_gt_u32 s61, 13
	.p2align	6

; #define PG8_STAGE(bufoff, gbase, voff) do { _Pragma("unroll") for (int _i = 0; _i < 2; ++_i) \
;         __builtin_amdgcn_global_load_lds((const unsigned*)((const char*)(gbase) + (voff)[_i]), (PG8_LAS unsigned*)(lds + (bufoff) + ldsw + _i * 8192), 16, 0, 0); } while (0)
; #define PG8_LDA(dst, b, h) do { _Pragma("unroll") for (int m = 0; m < 4; ++m) _Pragma("unroll") for (int k = 0; k < 2; ++k) dst[m][k] = *(const PG8_LAS bf16x8*)(lds + PG8_SA(b, h) + aoff + m * 2048 + k * 1024); } while (0)
; #define PG8_LDB(dst, b, h) do { _Pragma("unroll") for (int n = 0; n < 2; ++n) _Pragma("unroll") for (int k = 0; k < 2; ++k) dst[n][k] = *(const PG8_LAS bf16x8*)(lds + PG8_SB(b, h) + boff + n * 2048 + k * 1024); } while (0)
; #define PG8_MMA(ai, bj, At, Bt) do { __builtin_amdgcn_s_setprio(1); _Pragma("unroll") for (int m = 0; m < 4; ++m) _Pragma("unroll") for (int n = 0; n < 2; ++n) _Pragma("unroll") for (int k = 0; k < 2; ++k) \
;         acc[ai][bj][m][n] = __builtin_amdgcn_mfma_f32_16x16x32_bf16(Bt[n][k], At[m][k], acc[ai][bj][m][n], 0, 0, 0); __builtin_amdgcn_s_setprio(0); } while (0)
; #define PG8_BAR __builtin_amdgcn_s_barrier()
; template <class Epi, class Sched, bool ALIGN_EPI = false, bool SP2 = false>
; __device__ __forceinline__ void gemm_phase(PG8_LAS unsigned char* lds, const Gemm g, const Sched& S, const Epi& E) {
;     ...
;         const bool has_next = S.next(ui + 1, nxt);
;         const char* nA = has_next ? (const char*)g.A + (size_t)nxt.pm * tstep : cA; const char* nB = has_next ? (const char*)g.Bt + (size_t)nxt.pn * tstep : cB;
;         for (int t = 0; t < nt; t += 2) {
;             const bool last = (t == nt - 2);
;             const char* a1 = cA + (size_t)(t + 1) * kstep;
;             const char* a2 = last ? nA : cA + (size_t)(t + 2) * kstep; const char* b2 = last ? nB : cB + (size_t)(t + 2) * kstep;
;             const char* a3 = a2 + kstep; const char* b3 = b2 + kstep;
;             if (last && has_next) S.a_ready(nxt);
;             if constexpr (SP2) {
;             PG8_LDB(B0, 0, 0); PG8_LDB(B1, 0, 1); PG8_SCHED; PG8_LDA(At, 0, 0); PG8_STAGE(PG8_SA(1, 1), a1 + hstep, voffA);
;             PG8_WAIT_V(8); PG8_WAIT_L(0); PG8_BAR; PG8_MMA(0, 0, At, B0); PG8_MMA(0, 1, At, B1); PG8_BAR; PG8_SCHED;
;             PG8_LDA(At, 0, 1); PG8_STAGE(PG8_SB(0, 0), b2, voffB); PG8_STAGE(PG8_SB(0, 1), b2 + hstep, voffB); PG8_STAGE(PG8_SA(0, 0), a2, voffA);
.LBB0_826:
	s_ashr_i32 s39, s38, 31
	v_cmp_lt_i64_e32 vcc, s[40:41], v[156:157]
	s_lshl_b64 s[40:41], s[38:39], 20
	s_add_u32 s40, s9, s40
	s_addc_u32 s41, s22, s41
	s_and_b64 s[42:43], vcc, exec
	s_cselect_b32 s39, s41, s47
	s_cselect_b32 s67, s40, s46
	s_ashr_i32 s37, s36, 31
	s_lshl_b64 s[42:43], s[36:37], 20
	s_add_u32 s42, s23, s42
	s_addc_u32 s43, s52, s43
	s_and_b64 s[50:51], vcc, exec
	s_cselect_b32 s37, s43, s49
	s_cselect_b32 s68, s42, s48
	s_add_u32 s46, s46, 0x80080
	s_addc_u32 s47, s47, 0
	s_add_u32 s69, s48, 0x100
	s_addc_u32 s70, s49, 0
	s_mov_b32 s71, -2
	ds_read_b128 v[128:131], v169
	ds_read_b128 v[132:135], v169 offset:1024
	ds_read_b128 v[136:139], v169 offset:2048
	ds_read_b128 v[140:143], v169 offset:3072
	ds_read_b128 v[160:163], v170
	ds_read_b128 v[172:175], v170 offset:1024
	ds_read_b128 v[176:179], v170 offset:2048
	ds_read_b128 v[180:183], v170 offset:3072
	s_add_u32 s48, s46, 0xfff80080
	s_addc_u32 s49, s47, -1
	s_cmp_eq_u32 s71, 28
	s_cselect_b32 s51, s39, s49
	s_cselect_b32 s50, s67, s48
	s_cselect_b32 s49, s37, s70
	s_cselect_b32 s48, s68, s69
	s_add_i32 m0, s45, 0xc000
	ds_read_b128 v[184:187], v171
	ds_read_b128 v[188:191], v171 offset:1024
	ds_read_b128 v[192:195], v171 offset:2048
	ds_read_b128 v[196:199], v171 offset:3072
	ds_read_b128 v[200:203], v171 offset:4096
	ds_read_b128 v[204:207], v171 offset:5120
	ds_read_b128 v[208:211], v171 offset:6144
	ds_read_b128 v[214:217], v171 offset:7168
	global_load_lds_dwordx4 v152, s[46:47]
	s_add_i32 m0, s45, 0xe000
	s_nop 0
	global_load_lds_dwordx4 v154, s[46:47]
	s_waitcnt vmcnt(8)
	s_waitcnt lgkmcnt(0)
	s_barrier
	v_mfma_f32_16x16x32_bf16 v[124:127], v[128:131], v[184:187], 0
	v_mfma_f32_16x16x32_bf16 v[120:123], v[136:139], v[184:187], 0
	v_mfma_f32_16x16x32_bf16 v[116:119], v[128:131], v[192:195], 0
	v_mfma_f32_16x16x32_bf16 v[112:115], v[136:139], v[192:195], 0
	v_mfma_f32_16x16x32_bf16 v[108:111], v[128:131], v[200:203], 0
	v_mfma_f32_16x16x32_bf16 v[96:99], v[136:139], v[200:203], 0
	v_mfma_f32_16x16x32_bf16 v[80:83], v[128:131], v[208:211], 0
	v_mfma_f32_16x16x32_bf16 v[72:75], v[136:139], v[208:211], 0
	v_mfma_f32_16x16x32_bf16 v[124:127], v[132:135], v[188:191], v[124:127]
	v_mfma_f32_16x16x32_bf16 v[120:123], v[140:143], v[188:191], v[120:123]
	v_mfma_f32_16x16x32_bf16 v[116:119], v[132:135], v[196:199], v[116:119]
	v_mfma_f32_16x16x32_bf16 v[112:115], v[140:143], v[196:199], v[112:115]
	v_mfma_f32_16x16x32_bf16 v[108:111], v[132:135], v[204:207], v[108:111]
	v_mfma_f32_16x16x32_bf16 v[96:99], v[140:143], v[204:207], v[96:99]
	v_mfma_f32_16x16x32_bf16 v[80:83], v[132:135], v[214:217], v[80:83]
	v_mfma_f32_16x16x32_bf16 v[72:75], v[140:143], v[214:217], v[72:75]
	v_mfma_f32_16x16x32_bf16 v[104:107], v[160:163], v[184:187], 0
	v_mfma_f32_16x16x32_bf16 v[100:103], v[176:179], v[184:187], 0
	v_mfma_f32_16x16x32_bf16 v[92:95], v[160:163], v[192:195], 0
	v_mfma_f32_16x16x32_bf16 v[88:91], v[176:179], v[192:195], 0
	v_mfma_f32_16x16x32_bf16 v[84:87], v[160:163], v[200:203], 0
	v_mfma_f32_16x16x32_bf16 v[76:79], v[176:179], v[200:203], 0
	v_mfma_f32_16x16x32_bf16 v[68:71], v[160:163], v[208:211], 0
	v_mfma_f32_16x16x32_bf16 v[64:67], v[176:179], v[208:211], 0
	v_mfma_f32_16x16x32_bf16 v[104:107], v[172:175], v[188:191], v[104:107]
	v_mfma_f32_16x16x32_bf16 v[100:103], v[180:183], v[188:191], v[100:103]
	v_mfma_f32_16x16x32_bf16 v[92:95], v[172:175], v[196:199], v[92:95]
	v_mfma_f32_16x16x32_bf16 v[88:91], v[180:183], v[196:199], v[88:91]
	v_mfma_f32_16x16x32_bf16 v[84:87], v[172:175], v[204:207], v[84:87]
	v_mfma_f32_16x16x32_bf16 v[76:79], v[180:183], v[204:207], v[76:79]
	v_mfma_f32_16x16x32_bf16 v[68:71], v[172:175], v[214:217], v[68:71]
	v_mfma_f32_16x16x32_bf16 v[64:67], v[180:183], v[214:217], v[64:67]
	s_barrier
	s_add_i32 s72, s64, s53
	s_mov_b32 m0, s72
	ds_read_b128 v[184:187], v171 offset:16384
	ds_read_b128 v[188:191], v171 offset:17408
	ds_read_b128 v[192:195], v171 offset:18432
	ds_read_b128 v[196:199], v171 offset:19456
	ds_read_b128 v[200:203], v171 offset:20480
	ds_read_b128 v[204:207], v171 offset:21504
	ds_read_b128 v[208:211], v171 offset:22528
	ds_read_b128 v[214:217], v171 offset:23552
	global_load_lds_dwordx4 v146, s[48:49]
	s_add_i32 m0, s72, 0x2000
	s_add_u32 s72, s48, 0x80000
	s_addc_u32 s73, s49, 0
	s_add_i32 s74, s65, s53
	global_load_lds_dwordx4 v150, s[48:49]
	s_mov_b32 m0, s74
	s_nop 0
	global_load_lds_dwordx4 v146, s[72:73]
	s_add_i32 m0, s74, 0x2000
	s_nop 0
	global_load_lds_dwordx4 v150, s[72:73]
	s_mov_b32 m0, s45
	s_nop 0
	global_load_lds_dwordx4 v144, s[50:51]
	s_mov_b32 m0, s54
	s_nop 0
	global_load_lds_dwordx4 v148, s[50:51]
	s_waitcnt vmcnt(8)
	s_waitcnt lgkmcnt(0)
	s_barrier
; #define PG8_STAGE(bufoff, gbase, voff) do { _Pragma("unroll") for (int _i = 0; _i < 2; ++_i) \
;         __builtin_amdgcn_global_load_lds((const unsigned*)((const char*)(gbase) + (voff)[_i]), (PG8_LAS unsigned*)(lds + (bufoff) + ldsw + _i * 8192), 16, 0, 0); } while (0)
; #define PG8_LDA(dst, b, h) do { _Pragma("unroll") for (int m = 0; m < 4; ++m) _Pragma("unroll") for (int k = 0; k < 2; ++k) dst[m][k] = *(const PG8_LAS bf16x8*)(lds + PG8_SA(b, h) + aoff + m * 2048 + k * 1024); } while (0)
; #define PG8_LDB(dst, b, h) do { _Pragma("unroll") for (int n = 0; n < 2; ++n) _Pragma("unroll") for (int k = 0; k < 2; ++k) dst[n][k] = *(const PG8_LAS bf16x8*)(lds + PG8_SB(b, h) + boff + n * 2048 + k * 1024); } while (0)
; #define PG8_MMA(ai, bj, At, Bt) do { __builtin_amdgcn_s_setprio(1); _Pragma("unroll") for (int m = 0; m < 4; ++m) _Pragma("unroll") for (int n = 0; n < 2; ++n) _Pragma("unroll") for (int k = 0; k < 2; ++k) \
;         acc[ai][bj][m][n] = __builtin_amdgcn_mfma_f32_16x16x32_bf16(Bt[n][k], At[m][k], acc[ai][bj][m][n], 0, 0, 0); __builtin_amdgcn_s_setprio(0); } while (0)
; #define PG8_WAIT_V(n) asm volatile("s_waitcnt vmcnt(" #n ")" ::: "memory")
; #define PG8_WAIT_L(n) asm volatile("s_waitcnt lgkmcnt(" #n ")" ::: "memory")
; #define PG8_BAR __builtin_amdgcn_s_barrier()
; #define PG8_SCHED __builtin_amdgcn_sched_barrier(0)
; template <class Epi, class Sched, bool ALIGN_EPI = false, bool SP2 = false>
; __device__ __forceinline__ void gemm_phase(PG8_LAS unsigned char* lds, const Gemm g, const Sched& S, const Epi& E) {
;     ...
;             PG8_WAIT_V(8); PG8_WAIT_L(0); PG8_BAR; PG8_MMA(1, 0, At, B0); PG8_MMA(1, 1, At, B1); PG8_BAR; PG8_SCHED;
;             PG8_LDB(B0, 1, 0); PG8_LDB(B1, 1, 1); PG8_SCHED; PG8_LDA(At, 1, 0); PG8_STAGE(PG8_SA(0, 1), a2 + hstep, voffA);
;             PG8_WAIT_V(8); PG8_WAIT_L(0); PG8_BAR; PG8_MMA(0, 0, At, B0); PG8_MMA(0, 1, At, B1); PG8_BAR; PG8_SCHED;
	v_mfma_f32_16x16x32_bf16 v[60:63], v[128:131], v[184:187], 0
	v_mfma_f32_16x16x32_bf16 v[56:59], v[136:139], v[184:187], 0
	v_mfma_f32_16x16x32_bf16 v[52:55], v[128:131], v[192:195], 0
	v_mfma_f32_16x16x32_bf16 v[48:51], v[136:139], v[192:195], 0
	v_mfma_f32_16x16x32_bf16 v[44:47], v[128:131], v[200:203], 0
	v_mfma_f32_16x16x32_bf16 v[32:35], v[136:139], v[200:203], 0
	v_mfma_f32_16x16x32_bf16 v[20:23], v[128:131], v[208:211], 0
	v_mfma_f32_16x16x32_bf16 v[8:11], v[136:139], v[208:211], 0
	v_mfma_f32_16x16x32_bf16 v[60:63], v[132:135], v[188:191], v[60:63]
	v_mfma_f32_16x16x32_bf16 v[56:59], v[140:143], v[188:191], v[56:59]
	v_mfma_f32_16x16x32_bf16 v[52:55], v[132:135], v[196:199], v[52:55]
	v_mfma_f32_16x16x32_bf16 v[48:51], v[140:143], v[196:199], v[48:51]
	v_mfma_f32_16x16x32_bf16 v[44:47], v[132:135], v[204:207], v[44:47]
	v_mfma_f32_16x16x32_bf16 v[32:35], v[140:143], v[204:207], v[32:35]
	v_mfma_f32_16x16x32_bf16 v[20:23], v[132:135], v[214:217], v[20:23]
	v_mfma_f32_16x16x32_bf16 v[8:11], v[140:143], v[214:217], v[8:11]
	v_mfma_f32_16x16x32_bf16 v[40:43], v[160:163], v[184:187], 0
	v_mfma_f32_16x16x32_bf16 v[36:39], v[176:179], v[184:187], 0
	v_mfma_f32_16x16x32_bf16 v[28:31], v[160:163], v[192:195], 0
	v_mfma_f32_16x16x32_bf16 v[24:27], v[176:179], v[192:195], 0
	v_mfma_f32_16x16x32_bf16 v[16:19], v[160:163], v[200:203], 0
	v_mfma_f32_16x16x32_bf16 v[12:15], v[176:179], v[200:203], 0
	v_mfma_f32_16x16x32_bf16 v[4:7], v[160:163], v[208:211], 0
	v_mfma_f32_16x16x32_bf16 v[0:3], v[176:179], v[208:211], 0
	v_mfma_f32_16x16x32_bf16 v[40:43], v[172:175], v[188:191], v[40:43]
	v_mfma_f32_16x16x32_bf16 v[36:39], v[180:183], v[188:191], v[36:39]
	v_mfma_f32_16x16x32_bf16 v[28:31], v[172:175], v[196:199], v[28:31]
	v_mfma_f32_16x16x32_bf16 v[24:27], v[180:183], v[196:199], v[24:27]
	v_mfma_f32_16x16x32_bf16 v[16:19], v[172:175], v[204:207], v[16:19]
	v_mfma_f32_16x16x32_bf16 v[12:15], v[180:183], v[204:207], v[12:15]
	v_mfma_f32_16x16x32_bf16 v[4:7], v[172:175], v[214:217], v[4:7]
	v_mfma_f32_16x16x32_bf16 v[0:3], v[180:183], v[214:217], v[0:3]
	s_barrier
	s_add_i32 s72, 0, 0x18000
	s_add_i32 s73, 0, 0x1c000
	v_add_u32_e32 v140, s72, v167
	v_add_u32_e32 v180, s73, v167
	ds_read_b128 v[128:131], v140
	ds_read_b128 v[132:135], v140 offset:1024
	ds_read_b128 v[136:139], v140 offset:2048
	ds_read_b128 v[140:143], v140 offset:3072
	ds_read_b128 v[160:163], v180
	ds_read_b128 v[172:175], v180 offset:1024
	ds_read_b128 v[176:179], v180 offset:2048
	ds_read_b128 v[180:183], v180 offset:3072
	s_add_u32 s84, s50, 0x80
	s_addc_u32 s85, s51, 0
	s_add_u32 s50, s50, 0x80000
	s_addc_u32 s51, s51, 0
	s_mov_b32 m0, s55
	ds_read_b128 v[184:187], v171 offset:32768
	ds_read_b128 v[188:191], v171 offset:33792
	ds_read_b128 v[192:195], v171 offset:34816
	ds_read_b128 v[196:199], v171 offset:35840
	ds_read_b128 v[200:203], v171 offset:36864
	ds_read_b128 v[204:207], v171 offset:37888
	ds_read_b128 v[208:211], v171 offset:38912
	ds_read_b128 v[214:217], v171 offset:39936
	global_load_lds_dwordx4 v144, s[50:51]
	s_mov_b32 m0, s56
	s_nop 0
	global_load_lds_dwordx4 v148, s[50:51]
	s_waitcnt vmcnt(8)
	s_waitcnt lgkmcnt(0)
	s_barrier
	v_mfma_f32_16x16x32_bf16 v[124:127], v[128:131], v[184:187], v[124:127]
	v_mfma_f32_16x16x32_bf16 v[120:123], v[136:139], v[184:187], v[120:123]
	v_mfma_f32_16x16x32_bf16 v[116:119], v[128:131], v[192:195], v[116:119]
	v_mfma_f32_16x16x32_bf16 v[112:115], v[136:139], v[192:195], v[112:115]
	v_mfma_f32_16x16x32_bf16 v[108:111], v[128:131], v[200:203], v[108:111]
	v_mfma_f32_16x16x32_bf16 v[96:99], v[136:139], v[200:203], v[96:99]
	v_mfma_f32_16x16x32_bf16 v[80:83], v[128:131], v[208:211], v[80:83]
	v_mfma_f32_16x16x32_bf16 v[72:75], v[136:139], v[208:211], v[72:75]
	v_mfma_f32_16x16x32_bf16 v[124:127], v[132:135], v[188:191], v[124:127]
	v_mfma_f32_16x16x32_bf16 v[120:123], v[140:143], v[188:191], v[120:123]
	v_mfma_f32_16x16x32_bf16 v[116:119], v[132:135], v[196:199], v[116:119]
	v_mfma_f32_16x16x32_bf16 v[112:115], v[140:143], v[196:199], v[112:115]
	v_mfma_f32_16x16x32_bf16 v[108:111], v[132:135], v[204:207], v[108:111]
	v_mfma_f32_16x16x32_bf16 v[96:99], v[140:143], v[204:207], v[96:99]
	v_mfma_f32_16x16x32_bf16 v[80:83], v[132:135], v[214:217], v[80:83]
	v_mfma_f32_16x16x32_bf16 v[72:75], v[140:143], v[214:217], v[72:75]
	v_mfma_f32_16x16x32_bf16 v[104:107], v[160:163], v[184:187], v[104:107]
	v_mfma_f32_16x16x32_bf16 v[100:103], v[176:179], v[184:187], v[100:103]
	v_mfma_f32_16x16x32_bf16 v[92:95], v[160:163], v[192:195], v[92:95]
	v_mfma_f32_16x16x32_bf16 v[88:91], v[176:179], v[192:195], v[88:91]
	v_mfma_f32_16x16x32_bf16 v[84:87], v[160:163], v[200:203], v[84:87]
	v_mfma_f32_16x16x32_bf16 v[76:79], v[176:179], v[200:203], v[76:79]
	v_mfma_f32_16x16x32_bf16 v[68:71], v[160:163], v[208:211], v[68:71]
	v_mfma_f32_16x16x32_bf16 v[64:67], v[176:179], v[208:211], v[64:67]
	v_mfma_f32_16x16x32_bf16 v[104:107], v[172:175], v[188:191], v[104:107]
	v_mfma_f32_16x16x32_bf16 v[100:103], v[180:183], v[188:191], v[100:103]
	v_mfma_f32_16x16x32_bf16 v[92:95], v[172:175], v[196:199], v[92:95]
	v_mfma_f32_16x16x32_bf16 v[88:91], v[180:183], v[196:199], v[88:91]
	v_mfma_f32_16x16x32_bf16 v[84:87], v[172:175], v[204:207], v[84:87]
	v_mfma_f32_16x16x32_bf16 v[76:79], v[180:183], v[204:207], v[76:79]
	v_mfma_f32_16x16x32_bf16 v[68:71], v[172:175], v[214:217], v[68:71]
	v_mfma_f32_16x16x32_bf16 v[64:67], v[180:183], v[214:217], v[64:67]
	s_barrier
; #define PG8_STAGE(bufoff, gbase, voff) do { _Pragma("unroll") for (int _i = 0; _i < 2; ++_i) \
;         __builtin_amdgcn_global_load_lds((const unsigned*)((const char*)(gbase) + (voff)[_i]), (PG8_LAS unsigned*)(lds + (bufoff) + ldsw + _i * 8192), 16, 0, 0); } while (0)
; #define PG8_LDA(dst, b, h) do { _Pragma("unroll") for (int m = 0; m < 4; ++m) _Pragma("unroll") for (int k = 0; k < 2; ++k) dst[m][k] = *(const PG8_LAS bf16x8*)(lds + PG8_SA(b, h) + aoff + m * 2048 + k * 1024); } while (0)
; #define PG8_MMA(ai, bj, At, Bt) do { __builtin_amdgcn_s_setprio(1); _Pragma("unroll") for (int m = 0; m < 4; ++m) _Pragma("unroll") for (int n = 0; n < 2; ++n) _Pragma("unroll") for (int k = 0; k < 2; ++k) \
;         acc[ai][bj][m][n] = __builtin_amdgcn_mfma_f32_16x16x32_bf16(Bt[n][k], At[m][k], acc[ai][bj][m][n], 0, 0, 0); __builtin_amdgcn_s_setprio(0); } while (0)
; #define PG8_WAIT_V(n) asm volatile("s_waitcnt vmcnt(" #n ")" ::: "memory")
; #define PG8_WAIT_L(n) asm volatile("s_waitcnt lgkmcnt(" #n ")" ::: "memory")
; #define PG8_BAR __builtin_amdgcn_s_barrier()
; #define PG8_SCHED __builtin_amdgcn_sched_barrier(0)
; template <class Epi, class Sched, bool ALIGN_EPI = false, bool SP2 = false>
; __device__ __forceinline__ void gemm_phase(PG8_LAS unsigned char* lds, const Gemm g, const Sched& S, const Epi& E) {
;     ...
;         for (int t = 0; t < nt; t += 2) {
;     ...
;             PG8_LDA(At, 1, 1); PG8_STAGE(PG8_SB(1, 0), b3, voffB); PG8_STAGE(PG8_SB(1, 1), b3 + hstep, voffB); PG8_STAGE(PG8_SA(1, 0), a3, voffA);
;             PG8_WAIT_V(8); PG8_WAIT_L(0); PG8_BAR; PG8_MMA(1, 0, At, B0); PG8_MMA(1, 1, At, B1); PG8_BAR; PG8_SCHED;
	s_add_i32 s50, s72, s53
	s_add_u32 s86, s48, 0x80
	s_addc_u32 s87, s49, 0
	s_mov_b32 m0, s50
	ds_read_b128 v[184:187], v171 offset:49152
	ds_read_b128 v[188:191], v171 offset:50176
	ds_read_b128 v[192:195], v171 offset:51200
	ds_read_b128 v[196:199], v171 offset:52224
	ds_read_b128 v[200:203], v171 offset:53248
	ds_read_b128 v[204:207], v171 offset:54272
	ds_read_b128 v[208:211], v171 offset:55296
	ds_read_b128 v[214:217], v171 offset:56320
	global_load_lds_dwordx4 v146, s[86:87]
	s_add_i32 m0, s50, 0x2000
	s_add_u32 s48, s48, 0x80080
	s_addc_u32 s49, s49, 0
	s_add_i32 s50, s73, s53
	global_load_lds_dwordx4 v150, s[86:87]
	s_mov_b32 m0, s50
	s_nop 0
	global_load_lds_dwordx4 v146, s[48:49]
	s_add_i32 m0, s50, 0x2000
	s_nop 0
	global_load_lds_dwordx4 v150, s[48:49]
	s_mov_b32 m0, s60
	s_nop 0
	global_load_lds_dwordx4 v144, s[84:85]
	s_mov_b32 m0, s61
	s_nop 0
	global_load_lds_dwordx4 v148, s[84:85]
	s_waitcnt vmcnt(8)
	s_waitcnt lgkmcnt(0)
	s_barrier
	v_mfma_f32_16x16x32_bf16 v[60:63], v[128:131], v[184:187], v[60:63]
	v_mfma_f32_16x16x32_bf16 v[56:59], v[136:139], v[184:187], v[56:59]
	v_mfma_f32_16x16x32_bf16 v[52:55], v[128:131], v[192:195], v[52:55]
	v_mfma_f32_16x16x32_bf16 v[48:51], v[136:139], v[192:195], v[48:51]
	v_mfma_f32_16x16x32_bf16 v[44:47], v[128:131], v[200:203], v[44:47]
	v_mfma_f32_16x16x32_bf16 v[32:35], v[136:139], v[200:203], v[32:35]
	v_mfma_f32_16x16x32_bf16 v[20:23], v[128:131], v[208:211], v[20:23]
	v_mfma_f32_16x16x32_bf16 v[8:11], v[136:139], v[208:211], v[8:11]
	v_mfma_f32_16x16x32_bf16 v[60:63], v[132:135], v[188:191], v[60:63]
	v_mfma_f32_16x16x32_bf16 v[56:59], v[140:143], v[188:191], v[56:59]
	v_mfma_f32_16x16x32_bf16 v[52:55], v[132:135], v[196:199], v[52:55]
	v_mfma_f32_16x16x32_bf16 v[48:51], v[140:143], v[196:199], v[48:51]
	v_mfma_f32_16x16x32_bf16 v[44:47], v[132:135], v[204:207], v[44:47]
	v_mfma_f32_16x16x32_bf16 v[32:35], v[140:143], v[204:207], v[32:35]
	v_mfma_f32_16x16x32_bf16 v[20:23], v[132:135], v[214:217], v[20:23]
	v_mfma_f32_16x16x32_bf16 v[8:11], v[140:143], v[214:217], v[8:11]
	v_mfma_f32_16x16x32_bf16 v[40:43], v[160:163], v[184:187], v[40:43]
	v_mfma_f32_16x16x32_bf16 v[36:39], v[176:179], v[184:187], v[36:39]
	v_mfma_f32_16x16x32_bf16 v[28:31], v[160:163], v[192:195], v[28:31]
	v_mfma_f32_16x16x32_bf16 v[24:27], v[176:179], v[192:195], v[24:27]
	v_mfma_f32_16x16x32_bf16 v[16:19], v[160:163], v[200:203], v[16:19]
	v_mfma_f32_16x16x32_bf16 v[12:15], v[176:179], v[200:203], v[12:15]
	v_mfma_f32_16x16x32_bf16 v[4:7], v[160:163], v[208:211], v[4:7]
	v_mfma_f32_16x16x32_bf16 v[0:3], v[176:179], v[208:211], v[0:3]
	v_mfma_f32_16x16x32_bf16 v[40:43], v[172:175], v[188:191], v[40:43]
	v_mfma_f32_16x16x32_bf16 v[36:39], v[180:183], v[188:191], v[36:39]
	v_mfma_f32_16x16x32_bf16 v[28:31], v[172:175], v[196:199], v[28:31]
	v_mfma_f32_16x16x32_bf16 v[24:27], v[180:183], v[196:199], v[24:27]
	v_mfma_f32_16x16x32_bf16 v[16:19], v[172:175], v[204:207], v[16:19]
	v_mfma_f32_16x16x32_bf16 v[12:15], v[180:183], v[204:207], v[12:15]
	v_mfma_f32_16x16x32_bf16 v[4:7], v[172:175], v[214:217], v[4:7]
	v_mfma_f32_16x16x32_bf16 v[0:3], v[180:183], v[214:217], v[0:3]
	s_barrier
	s_add_i32 s71, s71, 2
	s_add_u32 s46, s46, 0x100
	s_addc_u32 s47, s47, 0
	s_add_u32 s69, s69, 0x100
	s_addc_u32 s70, s70, 0
	s_cmp_gt_u32 s71, 29
	.p2align	6

; #define PG8_STAGE(bufoff, gbase, voff) do { _Pragma("unroll") for (int _i = 0; _i < 2; ++_i) \
;         __builtin_amdgcn_global_load_lds((const unsigned*)((const char*)(gbase) + (voff)[_i]), (PG8_LAS unsigned*)(lds + (bufoff) + ldsw + _i * 8192), 16, 0, 0); } while (0)
; #define PG8_LDA(dst, b, h) do { _Pragma("unroll") for (int m = 0; m < 4; ++m) _Pragma("unroll") for (int k = 0; k < 2; ++k) dst[m][k] = *(const PG8_LAS bf16x8*)(lds + PG8_SA(b, h) + aoff + m * 2048 + k * 1024); } while (0)
; #define PG8_LDB(dst, b, h) do { _Pragma("unroll") for (int n = 0; n < 2; ++n) _Pragma("unroll") for (int k = 0; k < 2; ++k) dst[n][k] = *(const PG8_LAS bf16x8*)(lds + PG8_SB(b, h) + boff + n * 2048 + k * 1024); } while (0)
; #define PG8_MMA(ai, bj, At, Bt) do { __builtin_amdgcn_s_setprio(1); _Pragma("unroll") for (int m = 0; m < 4; ++m) _Pragma("unroll") for (int n = 0; n < 2; ++n) _Pragma("unroll") for (int k = 0; k < 2; ++k) \
;         acc[ai][bj][m][n] = __builtin_amdgcn_mfma_f32_16x16x32_bf16(Bt[n][k], At[m][k], acc[ai][bj][m][n], 0, 0, 0); __builtin_amdgcn_s_setprio(0); } while (0)
; #define PG8_BAR __builtin_amdgcn_s_barrier()
; template <class Epi, class Sched, bool ALIGN_EPI = false, bool SP2 = false>
; __device__ __forceinline__ void gemm_phase(PG8_LAS unsigned char* lds, const Gemm g, const Sched& S, const Epi& E) {
;     ...
;         const bool has_next = S.next(ui + 1, nxt);
;         const char* nA = has_next ? (const char*)g.A + (size_t)nxt.pm * tstep : cA; const char* nB = has_next ? (const char*)g.Bt + (size_t)nxt.pn * tstep : cB;
;         for (int t = 0; t < nt; t += 2) {
;             const bool last = (t == nt - 2);
;             const char* a1 = cA + (size_t)(t + 1) * kstep;
;             const char* a2 = last ? nA : cA + (size_t)(t + 2) * kstep; const char* b2 = last ? nB : cB + (size_t)(t + 2) * kstep;
;             const char* a3 = a2 + kstep; const char* b3 = b2 + kstep;
;             if (last && has_next) S.a_ready(nxt);
;             if constexpr (SP2) {
;             PG8_LDB(B0, 0, 0); PG8_LDB(B1, 0, 1); PG8_SCHED; PG8_LDA(At, 0, 0); PG8_STAGE(PG8_SA(1, 1), a1 + hstep, voffA);
;             PG8_WAIT_V(8); PG8_WAIT_L(0); PG8_BAR; PG8_MMA(0, 0, At, B0); PG8_MMA(0, 1, At, B1); PG8_BAR; PG8_SCHED;
;             PG8_LDA(At, 0, 1); PG8_STAGE(PG8_SB(0, 0), b2, voffB); PG8_STAGE(PG8_SB(0, 1), b2 + hstep, voffB); PG8_STAGE(PG8_SA(0, 0), a2, voffA);
.LBB0_944:
	s_ashr_i32 s23, s22, 31
	v_cmp_lt_i64_e32 vcc, s[24:25], v[140:141]
	s_lshl_b64 s[24:25], s[22:23], 20
	s_add_u32 s24, s38, s24
	s_addc_u32 s25, s39, s25
	s_and_b64 s[26:27], vcc, exec
	s_cselect_b32 s23, s25, s31
	s_cselect_b32 s57, s24, s30
	s_ashr_i32 s15, s14, 31
	s_lshl_b64 s[26:27], s[14:15], 20
	s_add_u32 s26, s40, s26
	s_addc_u32 s27, s41, s27
	s_and_b64 s[36:37], vcc, exec
	s_cselect_b32 s15, s27, s35
	s_cselect_b32 s58, s26, s34
	s_add_u32 s30, s30, 0x80080
	s_addc_u32 s31, s31, 0
	s_add_u32 s59, s34, 0x100
	s_addc_u32 s60, s35, 0
	s_mov_b32 s61, -2
	ds_read_b128 v[152:155], v149
	ds_read_b128 v[156:159], v149 offset:1024
	ds_read_b128 v[160:163], v149 offset:2048
	ds_read_b128 v[164:167], v149 offset:3072
	ds_read_b128 v[168:171], v150
	ds_read_b128 v[172:175], v150 offset:1024
	ds_read_b128 v[176:179], v150 offset:2048
	ds_read_b128 v[180:183], v150 offset:3072
	s_add_u32 s34, s30, 0xfff80080
	s_addc_u32 s35, s31, -1
	s_cmp_eq_u32 s61, 28
	s_cselect_b32 s37, s23, s35
	s_cselect_b32 s36, s57, s34
	s_cselect_b32 s35, s15, s60
	s_cselect_b32 s34, s58, s59
	s_add_i32 m0, s29, 0xc000
	ds_read_b128 v[184:187], v151
	ds_read_b128 v[188:191], v151 offset:1024
	ds_read_b128 v[192:195], v151 offset:2048
	ds_read_b128 v[196:199], v151 offset:3072
	ds_read_b128 v[200:203], v151 offset:4096
	ds_read_b128 v[204:207], v151 offset:5120
	ds_read_b128 v[208:211], v151 offset:6144
	ds_read_b128 v[212:215], v151 offset:7168
	global_load_lds_dwordx4 v136, s[30:31]
	s_add_i32 m0, s29, 0xe000
	s_nop 0
	global_load_lds_dwordx4 v138, s[30:31]
	s_waitcnt vmcnt(8)
	s_waitcnt lgkmcnt(0)
	s_barrier
	v_mfma_f32_16x16x32_bf16 v[124:127], v[152:155], v[184:187], 0
	v_mfma_f32_16x16x32_bf16 v[120:123], v[160:163], v[184:187], 0
	v_mfma_f32_16x16x32_bf16 v[108:111], v[152:155], v[192:195], 0
	v_mfma_f32_16x16x32_bf16 v[104:107], v[160:163], v[192:195], 0
	v_mfma_f32_16x16x32_bf16 v[92:95], v[152:155], v[200:203], 0
	v_mfma_f32_16x16x32_bf16 v[88:91], v[160:163], v[200:203], 0
	v_mfma_f32_16x16x32_bf16 v[76:79], v[152:155], v[208:211], 0
	v_mfma_f32_16x16x32_bf16 v[72:75], v[160:163], v[208:211], 0
	v_mfma_f32_16x16x32_bf16 v[124:127], v[156:159], v[188:191], v[124:127]
	v_mfma_f32_16x16x32_bf16 v[120:123], v[164:167], v[188:191], v[120:123]
	v_mfma_f32_16x16x32_bf16 v[108:111], v[156:159], v[196:199], v[108:111]
	v_mfma_f32_16x16x32_bf16 v[104:107], v[164:167], v[196:199], v[104:107]
	v_mfma_f32_16x16x32_bf16 v[92:95], v[156:159], v[204:207], v[92:95]
	v_mfma_f32_16x16x32_bf16 v[88:91], v[164:167], v[204:207], v[88:91]
	v_mfma_f32_16x16x32_bf16 v[76:79], v[156:159], v[212:215], v[76:79]
	v_mfma_f32_16x16x32_bf16 v[72:75], v[164:167], v[212:215], v[72:75]
	v_mfma_f32_16x16x32_bf16 v[116:119], v[168:171], v[184:187], 0
	v_mfma_f32_16x16x32_bf16 v[112:115], v[176:179], v[184:187], 0
	v_mfma_f32_16x16x32_bf16 v[100:103], v[168:171], v[192:195], 0
	v_mfma_f32_16x16x32_bf16 v[96:99], v[176:179], v[192:195], 0
	v_mfma_f32_16x16x32_bf16 v[84:87], v[168:171], v[200:203], 0
	v_mfma_f32_16x16x32_bf16 v[80:83], v[176:179], v[200:203], 0
	v_mfma_f32_16x16x32_bf16 v[68:71], v[168:171], v[208:211], 0
	v_mfma_f32_16x16x32_bf16 v[64:67], v[176:179], v[208:211], 0
	v_mfma_f32_16x16x32_bf16 v[116:119], v[172:175], v[188:191], v[116:119]
	v_mfma_f32_16x16x32_bf16 v[112:115], v[180:183], v[188:191], v[112:115]
	v_mfma_f32_16x16x32_bf16 v[100:103], v[172:175], v[196:199], v[100:103]
	v_mfma_f32_16x16x32_bf16 v[96:99], v[180:183], v[196:199], v[96:99]
	v_mfma_f32_16x16x32_bf16 v[84:87], v[172:175], v[204:207], v[84:87]
	v_mfma_f32_16x16x32_bf16 v[80:83], v[180:183], v[204:207], v[80:83]
	v_mfma_f32_16x16x32_bf16 v[68:71], v[172:175], v[212:215], v[68:71]
	v_mfma_f32_16x16x32_bf16 v[64:67], v[180:183], v[212:215], v[64:67]
	s_barrier
	s_add_i32 s62, s53, s42
	s_mov_b32 m0, s62
	ds_read_b128 v[184:187], v151 offset:16384
	ds_read_b128 v[188:191], v151 offset:17408
	ds_read_b128 v[192:195], v151 offset:18432
	ds_read_b128 v[196:199], v151 offset:19456
	ds_read_b128 v[200:203], v151 offset:20480
	ds_read_b128 v[204:207], v151 offset:21504
	ds_read_b128 v[208:211], v151 offset:22528
	ds_read_b128 v[212:215], v151 offset:23552
	global_load_lds_dwordx4 v132, s[34:35]
	s_add_i32 m0, s62, 0x2000
	s_add_u32 s62, s34, 0x80000
	s_addc_u32 s63, s35, 0
	s_add_i32 s64, s54, s42
	global_load_lds_dwordx4 v128, s[34:35]
	s_mov_b32 m0, s64
	s_nop 0
	global_load_lds_dwordx4 v132, s[62:63]
	s_add_i32 m0, s64, 0x2000
	s_nop 0
	global_load_lds_dwordx4 v128, s[62:63]
	s_mov_b32 m0, s29
	s_nop 0
	global_load_lds_dwordx4 v134, s[36:37]
	s_mov_b32 m0, s45
	s_nop 0
	global_load_lds_dwordx4 v130, s[36:37]
	s_waitcnt vmcnt(8)
	s_waitcnt lgkmcnt(0)
	s_barrier
; #define PG8_STAGE(bufoff, gbase, voff) do { _Pragma("unroll") for (int _i = 0; _i < 2; ++_i) \
;         __builtin_amdgcn_global_load_lds((const unsigned*)((const char*)(gbase) + (voff)[_i]), (PG8_LAS unsigned*)(lds + (bufoff) + ldsw + _i * 8192), 16, 0, 0); } while (0)
; #define PG8_LDA(dst, b, h) do { _Pragma("unroll") for (int m = 0; m < 4; ++m) _Pragma("unroll") for (int k = 0; k < 2; ++k) dst[m][k] = *(const PG8_LAS bf16x8*)(lds + PG8_SA(b, h) + aoff + m * 2048 + k * 1024); } while (0)
; #define PG8_LDB(dst, b, h) do { _Pragma("unroll") for (int n = 0; n < 2; ++n) _Pragma("unroll") for (int k = 0; k < 2; ++k) dst[n][k] = *(const PG8_LAS bf16x8*)(lds + PG8_SB(b, h) + boff + n * 2048 + k * 1024); } while (0)
; #define PG8_MMA(ai, bj, At, Bt) do { __builtin_amdgcn_s_setprio(1); _Pragma("unroll") for (int m = 0; m < 4; ++m) _Pragma("unroll") for (int n = 0; n < 2; ++n) _Pragma("unroll") for (int k = 0; k < 2; ++k) \
;         acc[ai][bj][m][n] = __builtin_amdgcn_mfma_f32_16x16x32_bf16(Bt[n][k], At[m][k], acc[ai][bj][m][n], 0, 0, 0); __builtin_amdgcn_s_setprio(0); } while (0)
; #define PG8_WAIT_V(n) asm volatile("s_waitcnt vmcnt(" #n ")" ::: "memory")
; #define PG8_WAIT_L(n) asm volatile("s_waitcnt lgkmcnt(" #n ")" ::: "memory")
; #define PG8_BAR __builtin_amdgcn_s_barrier()
; #define PG8_SCHED __builtin_amdgcn_sched_barrier(0)
; template <class Epi, class Sched, bool ALIGN_EPI = false, bool SP2 = false>
; __device__ __forceinline__ void gemm_phase(PG8_LAS unsigned char* lds, const Gemm g, const Sched& S, const Epi& E) {
;     ...
;             PG8_WAIT_V(8); PG8_WAIT_L(0); PG8_BAR; PG8_MMA(1, 0, At, B0); PG8_MMA(1, 1, At, B1); PG8_BAR; PG8_SCHED;
;             PG8_LDB(B0, 1, 0); PG8_LDB(B1, 1, 1); PG8_SCHED; PG8_LDA(At, 1, 0); PG8_STAGE(PG8_SA(0, 1), a2 + hstep, voffA);
;             PG8_WAIT_V(8); PG8_WAIT_L(0); PG8_BAR; PG8_MMA(0, 0, At, B0); PG8_MMA(0, 1, At, B1); PG8_BAR; PG8_SCHED;
	v_mfma_f32_16x16x32_bf16 v[60:63], v[152:155], v[184:187], 0
	v_mfma_f32_16x16x32_bf16 v[56:59], v[160:163], v[184:187], 0
	v_mfma_f32_16x16x32_bf16 v[44:47], v[152:155], v[192:195], 0
	v_mfma_f32_16x16x32_bf16 v[40:43], v[160:163], v[192:195], 0
	v_mfma_f32_16x16x32_bf16 v[28:31], v[152:155], v[200:203], 0
	v_mfma_f32_16x16x32_bf16 v[24:27], v[160:163], v[200:203], 0
	v_mfma_f32_16x16x32_bf16 v[12:15], v[152:155], v[208:211], 0
	v_mfma_f32_16x16x32_bf16 v[8:11], v[160:163], v[208:211], 0
	v_mfma_f32_16x16x32_bf16 v[60:63], v[156:159], v[188:191], v[60:63]
	v_mfma_f32_16x16x32_bf16 v[56:59], v[164:167], v[188:191], v[56:59]
	v_mfma_f32_16x16x32_bf16 v[44:47], v[156:159], v[196:199], v[44:47]
	v_mfma_f32_16x16x32_bf16 v[40:43], v[164:167], v[196:199], v[40:43]
	v_mfma_f32_16x16x32_bf16 v[28:31], v[156:159], v[204:207], v[28:31]
	v_mfma_f32_16x16x32_bf16 v[24:27], v[164:167], v[204:207], v[24:27]
	v_mfma_f32_16x16x32_bf16 v[12:15], v[156:159], v[212:215], v[12:15]
	v_mfma_f32_16x16x32_bf16 v[8:11], v[164:167], v[212:215], v[8:11]
	v_mfma_f32_16x16x32_bf16 v[52:55], v[168:171], v[184:187], 0
	v_mfma_f32_16x16x32_bf16 v[48:51], v[176:179], v[184:187], 0
	v_mfma_f32_16x16x32_bf16 v[36:39], v[168:171], v[192:195], 0
	v_mfma_f32_16x16x32_bf16 v[32:35], v[176:179], v[192:195], 0
	v_mfma_f32_16x16x32_bf16 v[20:23], v[168:171], v[200:203], 0
	v_mfma_f32_16x16x32_bf16 v[16:19], v[176:179], v[200:203], 0
	v_mfma_f32_16x16x32_bf16 v[4:7], v[168:171], v[208:211], 0
	v_mfma_f32_16x16x32_bf16 v[0:3], v[176:179], v[208:211], 0
	v_mfma_f32_16x16x32_bf16 v[52:55], v[172:175], v[188:191], v[52:55]
	v_mfma_f32_16x16x32_bf16 v[48:51], v[180:183], v[188:191], v[48:51]
	v_mfma_f32_16x16x32_bf16 v[36:39], v[172:175], v[196:199], v[36:39]
	v_mfma_f32_16x16x32_bf16 v[32:35], v[180:183], v[196:199], v[32:35]
	v_mfma_f32_16x16x32_bf16 v[20:23], v[172:175], v[204:207], v[20:23]
	v_mfma_f32_16x16x32_bf16 v[16:19], v[180:183], v[204:207], v[16:19]
	v_mfma_f32_16x16x32_bf16 v[4:7], v[172:175], v[212:215], v[4:7]
	v_mfma_f32_16x16x32_bf16 v[0:3], v[180:183], v[212:215], v[0:3]
	s_barrier
	s_add_i32 s62, 0, 0x18000
	s_add_i32 s63, 0, 0x1c000
	v_add_u32_e32 v164, s62, v147
	v_add_u32_e32 v180, s63, v147
	ds_read_b128 v[152:155], v164
	ds_read_b128 v[156:159], v164 offset:1024
	ds_read_b128 v[160:163], v164 offset:2048
	ds_read_b128 v[164:167], v164 offset:3072
	ds_read_b128 v[168:171], v180
	ds_read_b128 v[172:175], v180 offset:1024
	ds_read_b128 v[176:179], v180 offset:2048
	ds_read_b128 v[180:183], v180 offset:3072
	s_add_u32 s84, s36, 0x80
	s_addc_u32 s85, s37, 0
	s_add_u32 s36, s36, 0x80000
	s_addc_u32 s37, s37, 0
	s_mov_b32 m0, s46
	ds_read_b128 v[184:187], v151 offset:32768
	ds_read_b128 v[188:191], v151 offset:33792
	ds_read_b128 v[192:195], v151 offset:34816
	ds_read_b128 v[196:199], v151 offset:35840
	ds_read_b128 v[200:203], v151 offset:36864
	ds_read_b128 v[204:207], v151 offset:37888
	ds_read_b128 v[208:211], v151 offset:38912
	ds_read_b128 v[212:215], v151 offset:39936
	global_load_lds_dwordx4 v134, s[36:37]
	s_mov_b32 m0, s47
	s_nop 0
	global_load_lds_dwordx4 v130, s[36:37]
	s_waitcnt vmcnt(8)
	s_waitcnt lgkmcnt(0)
	s_barrier
	v_mfma_f32_16x16x32_bf16 v[124:127], v[152:155], v[184:187], v[124:127]
	v_mfma_f32_16x16x32_bf16 v[120:123], v[160:163], v[184:187], v[120:123]
	v_mfma_f32_16x16x32_bf16 v[108:111], v[152:155], v[192:195], v[108:111]
	v_mfma_f32_16x16x32_bf16 v[104:107], v[160:163], v[192:195], v[104:107]
	v_mfma_f32_16x16x32_bf16 v[92:95], v[152:155], v[200:203], v[92:95]
	v_mfma_f32_16x16x32_bf16 v[88:91], v[160:163], v[200:203], v[88:91]
	v_mfma_f32_16x16x32_bf16 v[76:79], v[152:155], v[208:211], v[76:79]
	v_mfma_f32_16x16x32_bf16 v[72:75], v[160:163], v[208:211], v[72:75]
	v_mfma_f32_16x16x32_bf16 v[124:127], v[156:159], v[188:191], v[124:127]
	v_mfma_f32_16x16x32_bf16 v[120:123], v[164:167], v[188:191], v[120:123]
	v_mfma_f32_16x16x32_bf16 v[108:111], v[156:159], v[196:199], v[108:111]
	v_mfma_f32_16x16x32_bf16 v[104:107], v[164:167], v[196:199], v[104:107]
	v_mfma_f32_16x16x32_bf16 v[92:95], v[156:159], v[204:207], v[92:95]
	v_mfma_f32_16x16x32_bf16 v[88:91], v[164:167], v[204:207], v[88:91]
	v_mfma_f32_16x16x32_bf16 v[76:79], v[156:159], v[212:215], v[76:79]
	v_mfma_f32_16x16x32_bf16 v[72:75], v[164:167], v[212:215], v[72:75]
	v_mfma_f32_16x16x32_bf16 v[116:119], v[168:171], v[184:187], v[116:119]
	v_mfma_f32_16x16x32_bf16 v[112:115], v[176:179], v[184:187], v[112:115]
	v_mfma_f32_16x16x32_bf16 v[100:103], v[168:171], v[192:195], v[100:103]
	v_mfma_f32_16x16x32_bf16 v[96:99], v[176:179], v[192:195], v[96:99]
	v_mfma_f32_16x16x32_bf16 v[84:87], v[168:171], v[200:203], v[84:87]
	v_mfma_f32_16x16x32_bf16 v[80:83], v[176:179], v[200:203], v[80:83]
	v_mfma_f32_16x16x32_bf16 v[68:71], v[168:171], v[208:211], v[68:71]
	v_mfma_f32_16x16x32_bf16 v[64:67], v[176:179], v[208:211], v[64:67]
	v_mfma_f32_16x16x32_bf16 v[116:119], v[172:175], v[188:191], v[116:119]
	v_mfma_f32_16x16x32_bf16 v[112:115], v[180:183], v[188:191], v[112:115]
	v_mfma_f32_16x16x32_bf16 v[100:103], v[172:175], v[196:199], v[100:103]
	v_mfma_f32_16x16x32_bf16 v[96:99], v[180:183], v[196:199], v[96:99]
	v_mfma_f32_16x16x32_bf16 v[84:87], v[172:175], v[204:207], v[84:87]
	v_mfma_f32_16x16x32_bf16 v[80:83], v[180:183], v[204:207], v[80:83]
	v_mfma_f32_16x16x32_bf16 v[68:71], v[172:175], v[212:215], v[68:71]
	v_mfma_f32_16x16x32_bf16 v[64:67], v[180:183], v[212:215], v[64:67]
	s_barrier
; #define PG8_STAGE(bufoff, gbase, voff) do { _Pragma("unroll") for (int _i = 0; _i < 2; ++_i) \
;         __builtin_amdgcn_global_load_lds((const unsigned*)((const char*)(gbase) + (voff)[_i]), (PG8_LAS unsigned*)(lds + (bufoff) + ldsw + _i * 8192), 16, 0, 0); } while (0)
; #define PG8_LDA(dst, b, h) do { _Pragma("unroll") for (int m = 0; m < 4; ++m) _Pragma("unroll") for (int k = 0; k < 2; ++k) dst[m][k] = *(const PG8_LAS bf16x8*)(lds + PG8_SA(b, h) + aoff + m * 2048 + k * 1024); } while (0)
; #define PG8_MMA(ai, bj, At, Bt) do { __builtin_amdgcn_s_setprio(1); _Pragma("unroll") for (int m = 0; m < 4; ++m) _Pragma("unroll") for (int n = 0; n < 2; ++n) _Pragma("unroll") for (int k = 0; k < 2; ++k) \
;         acc[ai][bj][m][n] = __builtin_amdgcn_mfma_f32_16x16x32_bf16(Bt[n][k], At[m][k], acc[ai][bj][m][n], 0, 0, 0); __builtin_amdgcn_s_setprio(0); } while (0)
; #define PG8_WAIT_V(n) asm volatile("s_waitcnt vmcnt(" #n ")" ::: "memory")
; #define PG8_WAIT_L(n) asm volatile("s_waitcnt lgkmcnt(" #n ")" ::: "memory")
; #define PG8_BAR __builtin_amdgcn_s_barrier()
; #define PG8_SCHED __builtin_amdgcn_sched_barrier(0)
; template <class Epi, class Sched, bool ALIGN_EPI = false, bool SP2 = false>
; __device__ __forceinline__ void gemm_phase(PG8_LAS unsigned char* lds, const Gemm g, const Sched& S, const Epi& E) {
;     ...
;         for (int t = 0; t < nt; t += 2) {
;     ...
;             PG8_LDA(At, 1, 1); PG8_STAGE(PG8_SB(1, 0), b3, voffB); PG8_STAGE(PG8_SB(1, 1), b3 + hstep, voffB); PG8_STAGE(PG8_SA(1, 0), a3, voffA);
;             PG8_WAIT_V(8); PG8_WAIT_L(0); PG8_BAR; PG8_MMA(1, 0, At, B0); PG8_MMA(1, 1, At, B1); PG8_BAR; PG8_SCHED;
	s_add_i32 s36, s62, s42
	s_add_u32 s86, s34, 0x80
	s_addc_u32 s87, s35, 0
	s_mov_b32 m0, s36
	ds_read_b128 v[184:187], v151 offset:49152
	ds_read_b128 v[188:191], v151 offset:50176
	ds_read_b128 v[192:195], v151 offset:51200
	ds_read_b128 v[196:199], v151 offset:52224
	ds_read_b128 v[200:203], v151 offset:53248
	ds_read_b128 v[204:207], v151 offset:54272
	ds_read_b128 v[208:211], v151 offset:55296
	ds_read_b128 v[212:215], v151 offset:56320
	global_load_lds_dwordx4 v132, s[86:87]
	s_add_i32 m0, s36, 0x2000
	s_add_u32 s34, s34, 0x80080
	s_addc_u32 s35, s35, 0
	s_add_i32 s36, s63, s42
	global_load_lds_dwordx4 v128, s[86:87]
	s_mov_b32 m0, s36
	s_nop 0
	global_load_lds_dwordx4 v132, s[34:35]
	s_add_i32 m0, s36, 0x2000
	s_nop 0
	global_load_lds_dwordx4 v128, s[34:35]
	s_mov_b32 m0, s49
	s_nop 0
	global_load_lds_dwordx4 v134, s[84:85]
	s_mov_b32 m0, s50
	s_nop 0
	global_load_lds_dwordx4 v130, s[84:85]
	s_waitcnt vmcnt(8)
	s_waitcnt lgkmcnt(0)
	s_barrier
	v_mfma_f32_16x16x32_bf16 v[60:63], v[152:155], v[184:187], v[60:63]
	v_mfma_f32_16x16x32_bf16 v[56:59], v[160:163], v[184:187], v[56:59]
	v_mfma_f32_16x16x32_bf16 v[44:47], v[152:155], v[192:195], v[44:47]
	v_mfma_f32_16x16x32_bf16 v[40:43], v[160:163], v[192:195], v[40:43]
	v_mfma_f32_16x16x32_bf16 v[28:31], v[152:155], v[200:203], v[28:31]
	v_mfma_f32_16x16x32_bf16 v[24:27], v[160:163], v[200:203], v[24:27]
	v_mfma_f32_16x16x32_bf16 v[12:15], v[152:155], v[208:211], v[12:15]
	v_mfma_f32_16x16x32_bf16 v[8:11], v[160:163], v[208:211], v[8:11]
	v_mfma_f32_16x16x32_bf16 v[60:63], v[156:159], v[188:191], v[60:63]
	v_mfma_f32_16x16x32_bf16 v[56:59], v[164:167], v[188:191], v[56:59]
	v_mfma_f32_16x16x32_bf16 v[44:47], v[156:159], v[196:199], v[44:47]
	v_mfma_f32_16x16x32_bf16 v[40:43], v[164:167], v[196:199], v[40:43]
	v_mfma_f32_16x16x32_bf16 v[28:31], v[156:159], v[204:207], v[28:31]
	v_mfma_f32_16x16x32_bf16 v[24:27], v[164:167], v[204:207], v[24:27]
	v_mfma_f32_16x16x32_bf16 v[12:15], v[156:159], v[212:215], v[12:15]
	v_mfma_f32_16x16x32_bf16 v[8:11], v[164:167], v[212:215], v[8:11]
	v_mfma_f32_16x16x32_bf16 v[52:55], v[168:171], v[184:187], v[52:55]
	v_mfma_f32_16x16x32_bf16 v[48:51], v[176:179], v[184:187], v[48:51]
	v_mfma_f32_16x16x32_bf16 v[36:39], v[168:171], v[192:195], v[36:39]
	v_mfma_f32_16x16x32_bf16 v[32:35], v[176:179], v[192:195], v[32:35]
	v_mfma_f32_16x16x32_bf16 v[20:23], v[168:171], v[200:203], v[20:23]
	v_mfma_f32_16x16x32_bf16 v[16:19], v[176:179], v[200:203], v[16:19]
	v_mfma_f32_16x16x32_bf16 v[4:7], v[168:171], v[208:211], v[4:7]
	v_mfma_f32_16x16x32_bf16 v[0:3], v[176:179], v[208:211], v[0:3]
	v_mfma_f32_16x16x32_bf16 v[52:55], v[172:175], v[188:191], v[52:55]
	v_mfma_f32_16x16x32_bf16 v[48:51], v[180:183], v[188:191], v[48:51]
	v_mfma_f32_16x16x32_bf16 v[36:39], v[172:175], v[196:199], v[36:39]
	v_mfma_f32_16x16x32_bf16 v[32:35], v[180:183], v[196:199], v[32:35]
	v_mfma_f32_16x16x32_bf16 v[20:23], v[172:175], v[204:207], v[20:23]
	v_mfma_f32_16x16x32_bf16 v[16:19], v[180:183], v[204:207], v[16:19]
	v_mfma_f32_16x16x32_bf16 v[4:7], v[172:175], v[212:215], v[4:7]
	v_mfma_f32_16x16x32_bf16 v[0:3], v[180:183], v[212:215], v[0:3]
	s_barrier
	s_add_i32 s61, s61, 2
	s_add_u32 s30, s30, 0x100
	s_addc_u32 s31, s31, 0
	s_add_u32 s59, s59, 0x100
	s_addc_u32 s60, s60, 0
	s_cmp_gt_u32 s61, 29
	.p2align	6

; #define PG8_STAGE(bufoff, gbase, voff) do { _Pragma("unroll") for (int _i = 0; _i < 2; ++_i) \
;         __builtin_amdgcn_global_load_lds((const unsigned*)((const char*)(gbase) + (voff)[_i]), (PG8_LAS unsigned*)(lds + (bufoff) + ldsw + _i * 8192), 16, 0, 0); } while (0)
; #define PG8_LDA(dst, b, h) do { _Pragma("unroll") for (int m = 0; m < 4; ++m) _Pragma("unroll") for (int k = 0; k < 2; ++k) dst[m][k] = *(const PG8_LAS bf16x8*)(lds + PG8_SA(b, h) + aoff + m * 2048 + k * 1024); } while (0)
; #define PG8_LDB(dst, b, h) do { _Pragma("unroll") for (int n = 0; n < 2; ++n) _Pragma("unroll") for (int k = 0; k < 2; ++k) dst[n][k] = *(const PG8_LAS bf16x8*)(lds + PG8_SB(b, h) + boff + n * 2048 + k * 1024); } while (0)
; #define PG8_WAIT_V(n) asm volatile("s_waitcnt vmcnt(" #n ")" ::: "memory")
; #define PG8_WAIT_L(n) asm volatile("s_waitcnt lgkmcnt(" #n ")" ::: "memory")
; #define PG8_BAR __builtin_amdgcn_s_barrier()
; #define PG8_SCHED __builtin_amdgcn_sched_barrier(0)
; template <class Epi, class Sched, bool ALIGN_EPI = false, bool SP2 = false>
; __device__ __forceinline__ void gemm_phase(PG8_LAS unsigned char* lds, const Gemm g, const Sched& S, const Epi& E) {
;     ...
;         const bool has_next = S.next(ui + 1, nxt);
;         const char* nA = has_next ? (const char*)g.A + (size_t)nxt.pm * tstep : cA; const char* nB = has_next ? (const char*)g.Bt + (size_t)nxt.pn * tstep : cB;
;         for (int t = 0; t < nt; t += 2) {
;             const bool last = (t == nt - 2);
;             const char* a1 = cA + (size_t)(t + 1) * kstep;
;             const char* a2 = last ? nA : cA + (size_t)(t + 2) * kstep; const char* b2 = last ? nB : cB + (size_t)(t + 2) * kstep;
;             const char* a3 = a2 + kstep; const char* b3 = b2 + kstep;
;             if (last && has_next) S.a_ready(nxt);
;             if constexpr (SP2) {
;             PG8_LDB(B0, 0, 0); PG8_LDB(B1, 0, 1); PG8_SCHED; PG8_LDA(At, 0, 0); PG8_STAGE(PG8_SA(1, 1), a1 + hstep, voffA);
;             PG8_WAIT_V(8); PG8_WAIT_L(0); PG8_BAR; PG8_MMA(0, 0, At, B0); PG8_MMA(0, 1, At, B1); PG8_BAR; PG8_SCHED;
;             PG8_LDA(At, 0, 1); PG8_STAGE(PG8_SB(0, 0), b2, voffB); PG8_STAGE(PG8_SB(0, 1), b2 + hstep, voffB); PG8_STAGE(PG8_SA(0, 0), a2, voffA);
;             PG8_WAIT_V(8); PG8_WAIT_L(0); PG8_BAR; PG8_MMA(1, 0, At, B0); PG8_MMA(1, 1, At, B1); PG8_BAR; PG8_SCHED;
.LBB0_1020:
	s_add_u32 s54, s26, 0x100
	s_addc_u32 s55, s27, 0
	s_mov_b32 s56, -2
	ds_read_b128 v[144:147], v169
	ds_read_b128 v[148:151], v169 offset:1024
	ds_read_b128 v[152:155], v169 offset:2048
	ds_read_b128 v[156:159], v169 offset:3072
	ds_read_b128 v[160:163], v170
	ds_read_b128 v[172:175], v170 offset:1024
	ds_read_b128 v[176:179], v170 offset:2048
	ds_read_b128 v[180:183], v170 offset:3072
	s_add_u32 s26, s24, 0x100
	s_addc_u32 s27, s25, 0
	s_cmpk_eq_i32 s56, 0x54
	s_cselect_b32 s31, s5, s27
	s_cselect_b32 s30, s4, s26
	s_cselect_b32 s29, s7, s55
	s_cselect_b32 s28, s6, s54
	s_add_i32 m0, s38, 0xc000
	ds_read_b128 v[184:187], v171
	ds_read_b128 v[188:191], v171 offset:1024
	ds_read_b128 v[192:195], v171 offset:2048
	ds_read_b128 v[196:199], v171 offset:3072
	ds_read_b128 v[200:203], v171 offset:4096
	ds_read_b128 v[204:207], v171 offset:5120
	ds_read_b128 v[208:211], v171 offset:6144
	ds_read_b128 v[212:215], v171 offset:7168
	global_load_lds_dwordx4 v136, s[24:25]
	s_add_i32 m0, s38, 0xe000
	s_nop 0
	global_load_lds_dwordx4 v138, s[24:25]
	s_waitcnt vmcnt(8)
	s_waitcnt lgkmcnt(0)
	s_barrier
	v_mfma_f32_16x16x32_bf16 v[124:127], v[144:147], v[184:187], 0
	v_mfma_f32_16x16x32_bf16 v[120:123], v[152:155], v[184:187], 0
	v_mfma_f32_16x16x32_bf16 v[116:119], v[144:147], v[192:195], 0
	v_mfma_f32_16x16x32_bf16 v[112:115], v[152:155], v[192:195], 0
	v_mfma_f32_16x16x32_bf16 v[108:111], v[144:147], v[200:203], 0
	v_mfma_f32_16x16x32_bf16 v[96:99], v[152:155], v[200:203], 0
	v_mfma_f32_16x16x32_bf16 v[84:87], v[144:147], v[208:211], 0
	v_mfma_f32_16x16x32_bf16 v[76:79], v[152:155], v[208:211], 0
	v_mfma_f32_16x16x32_bf16 v[124:127], v[148:151], v[188:191], v[124:127]
	v_mfma_f32_16x16x32_bf16 v[120:123], v[156:159], v[188:191], v[120:123]
	v_mfma_f32_16x16x32_bf16 v[116:119], v[148:151], v[196:199], v[116:119]
	v_mfma_f32_16x16x32_bf16 v[112:115], v[156:159], v[196:199], v[112:115]
	v_mfma_f32_16x16x32_bf16 v[108:111], v[148:151], v[204:207], v[108:111]
	v_mfma_f32_16x16x32_bf16 v[96:99], v[156:159], v[204:207], v[96:99]
	v_mfma_f32_16x16x32_bf16 v[84:87], v[148:151], v[212:215], v[84:87]
	v_mfma_f32_16x16x32_bf16 v[76:79], v[156:159], v[212:215], v[76:79]
	v_mfma_f32_16x16x32_bf16 v[104:107], v[160:163], v[184:187], 0
	v_mfma_f32_16x16x32_bf16 v[100:103], v[176:179], v[184:187], 0
	v_mfma_f32_16x16x32_bf16 v[92:95], v[160:163], v[192:195], 0
	v_mfma_f32_16x16x32_bf16 v[88:91], v[176:179], v[192:195], 0
	v_mfma_f32_16x16x32_bf16 v[80:83], v[160:163], v[200:203], 0
	v_mfma_f32_16x16x32_bf16 v[72:75], v[176:179], v[200:203], 0
	v_mfma_f32_16x16x32_bf16 v[68:71], v[160:163], v[208:211], 0
	v_mfma_f32_16x16x32_bf16 v[64:67], v[176:179], v[208:211], 0
	v_mfma_f32_16x16x32_bf16 v[104:107], v[172:175], v[188:191], v[104:107]
	v_mfma_f32_16x16x32_bf16 v[100:103], v[180:183], v[188:191], v[100:103]
	v_mfma_f32_16x16x32_bf16 v[92:95], v[172:175], v[196:199], v[92:95]
	v_mfma_f32_16x16x32_bf16 v[88:91], v[180:183], v[196:199], v[88:91]
	v_mfma_f32_16x16x32_bf16 v[80:83], v[172:175], v[204:207], v[80:83]
	v_mfma_f32_16x16x32_bf16 v[72:75], v[180:183], v[204:207], v[72:75]
	v_mfma_f32_16x16x32_bf16 v[68:71], v[172:175], v[212:215], v[68:71]
	v_mfma_f32_16x16x32_bf16 v[64:67], v[180:183], v[212:215], v[64:67]
	s_barrier
	s_add_i32 s24, s48, s37
	s_mov_b32 m0, s24
	ds_read_b128 v[184:187], v171 offset:16384
	ds_read_b128 v[188:191], v171 offset:17408
	ds_read_b128 v[192:195], v171 offset:18432
	ds_read_b128 v[196:199], v171 offset:19456
	ds_read_b128 v[200:203], v171 offset:20480
	ds_read_b128 v[204:207], v171 offset:21504
	ds_read_b128 v[208:211], v171 offset:22528
	ds_read_b128 v[212:215], v171 offset:23552
	global_load_lds_dwordx4 v130, s[28:29]
	s_add_i32 m0, s24, 0x2000
	s_add_u32 s24, s28, 0x160000
	s_addc_u32 s25, s29, 0
	s_add_i32 s57, s49, s37
	global_load_lds_dwordx4 v134, s[28:29]
	s_mov_b32 m0, s57
	s_nop 0
	global_load_lds_dwordx4 v130, s[24:25]
	s_add_i32 m0, s57, 0x2000
	s_nop 0
	global_load_lds_dwordx4 v134, s[24:25]
	s_mov_b32 m0, s38
	s_nop 0
	global_load_lds_dwordx4 v128, s[30:31]
	s_mov_b32 m0, s39
	s_nop 0
	global_load_lds_dwordx4 v132, s[30:31]
	s_waitcnt vmcnt(8)
	s_waitcnt lgkmcnt(0)
	s_barrier
	v_mfma_f32_16x16x32_bf16 v[60:63], v[144:147], v[184:187], 0
	v_mfma_f32_16x16x32_bf16 v[56:59], v[152:155], v[184:187], 0
	v_mfma_f32_16x16x32_bf16 v[52:55], v[144:147], v[192:195], 0
	v_mfma_f32_16x16x32_bf16 v[48:51], v[152:155], v[192:195], 0
	v_mfma_f32_16x16x32_bf16 v[44:47], v[144:147], v[200:203], 0
	v_mfma_f32_16x16x32_bf16 v[32:35], v[152:155], v[200:203], 0
	v_mfma_f32_16x16x32_bf16 v[20:23], v[144:147], v[208:211], 0
	v_mfma_f32_16x16x32_bf16 v[12:15], v[152:155], v[208:211], 0
	v_mfma_f32_16x16x32_bf16 v[60:63], v[148:151], v[188:191], v[60:63]
	v_mfma_f32_16x16x32_bf16 v[56:59], v[156:159], v[188:191], v[56:59]
	v_mfma_f32_16x16x32_bf16 v[52:55], v[148:151], v[196:199], v[52:55]
	v_mfma_f32_16x16x32_bf16 v[48:51], v[156:159], v[196:199], v[48:51]
	v_mfma_f32_16x16x32_bf16 v[44:47], v[148:151], v[204:207], v[44:47]
	v_mfma_f32_16x16x32_bf16 v[32:35], v[156:159], v[204:207], v[32:35]
	v_mfma_f32_16x16x32_bf16 v[20:23], v[148:151], v[212:215], v[20:23]
	v_mfma_f32_16x16x32_bf16 v[12:15], v[156:159], v[212:215], v[12:15]
	v_mfma_f32_16x16x32_bf16 v[40:43], v[160:163], v[184:187], 0
	v_mfma_f32_16x16x32_bf16 v[36:39], v[176:179], v[184:187], 0
	v_mfma_f32_16x16x32_bf16 v[28:31], v[160:163], v[192:195], 0
	v_mfma_f32_16x16x32_bf16 v[24:27], v[176:179], v[192:195], 0
	v_mfma_f32_16x16x32_bf16 v[16:19], v[160:163], v[200:203], 0
	v_mfma_f32_16x16x32_bf16 v[8:11], v[176:179], v[200:203], 0
	v_mfma_f32_16x16x32_bf16 v[4:7], v[160:163], v[208:211], 0
	v_mfma_f32_16x16x32_bf16 v[0:3], v[176:179], v[208:211], 0
	v_mfma_f32_16x16x32_bf16 v[40:43], v[172:175], v[188:191], v[40:43]
	v_mfma_f32_16x16x32_bf16 v[36:39], v[180:183], v[188:191], v[36:39]
	v_mfma_f32_16x16x32_bf16 v[28:31], v[172:175], v[196:199], v[28:31]
	v_mfma_f32_16x16x32_bf16 v[24:27], v[180:183], v[196:199], v[24:27]
	v_mfma_f32_16x16x32_bf16 v[16:19], v[172:175], v[204:207], v[16:19]
	v_mfma_f32_16x16x32_bf16 v[8:11], v[180:183], v[204:207], v[8:11]
	v_mfma_f32_16x16x32_bf16 v[4:7], v[172:175], v[212:215], v[4:7]
	v_mfma_f32_16x16x32_bf16 v[0:3], v[180:183], v[212:215], v[0:3]
	s_barrier
; #define PG8_STAGE(bufoff, gbase, voff) do { _Pragma("unroll") for (int _i = 0; _i < 2; ++_i) \
;         __builtin_amdgcn_global_load_lds((const unsigned*)((const char*)(gbase) + (voff)[_i]), (PG8_LAS unsigned*)(lds + (bufoff) + ldsw + _i * 8192), 16, 0, 0); } while (0)
; #define PG8_LDA(dst, b, h) do { _Pragma("unroll") for (int m = 0; m < 4; ++m) _Pragma("unroll") for (int k = 0; k < 2; ++k) dst[m][k] = *(const PG8_LAS bf16x8*)(lds + PG8_SA(b, h) + aoff + m * 2048 + k * 1024); } while (0)
; #define PG8_LDB(dst, b, h) do { _Pragma("unroll") for (int n = 0; n < 2; ++n) _Pragma("unroll") for (int k = 0; k < 2; ++k) dst[n][k] = *(const PG8_LAS bf16x8*)(lds + PG8_SB(b, h) + boff + n * 2048 + k * 1024); } while (0)
; #define PG8_MMA(ai, bj, At, Bt) do { __builtin_amdgcn_s_setprio(1); _Pragma("unroll") for (int m = 0; m < 4; ++m) _Pragma("unroll") for (int n = 0; n < 2; ++n) _Pragma("unroll") for (int k = 0; k < 2; ++k) \
;         acc[ai][bj][m][n] = __builtin_amdgcn_mfma_f32_16x16x32_bf16(Bt[n][k], At[m][k], acc[ai][bj][m][n], 0, 0, 0); __builtin_amdgcn_s_setprio(0); } while (0)
; #define PG8_WAIT_V(n) asm volatile("s_waitcnt vmcnt(" #n ")" ::: "memory")
; #define PG8_WAIT_L(n) asm volatile("s_waitcnt lgkmcnt(" #n ")" ::: "memory")
; #define PG8_BAR __builtin_amdgcn_s_barrier()
; #define PG8_SCHED __builtin_amdgcn_sched_barrier(0)
; template <class Epi, class Sched, bool ALIGN_EPI = false, bool SP2 = false>
; __device__ __forceinline__ void gemm_phase(PG8_LAS unsigned char* lds, const Gemm g, const Sched& S, const Epi& E) {
;     ...
;             PG8_LDB(B0, 1, 0); PG8_LDB(B1, 1, 1); PG8_SCHED; PG8_LDA(At, 1, 0); PG8_STAGE(PG8_SA(0, 1), a2 + hstep, voffA);
;             PG8_WAIT_V(8); PG8_WAIT_L(0); PG8_BAR; PG8_MMA(0, 0, At, B0); PG8_MMA(0, 1, At, B1); PG8_BAR; PG8_SCHED;
;             PG8_LDA(At, 1, 1); PG8_STAGE(PG8_SB(1, 0), b3, voffB); PG8_STAGE(PG8_SB(1, 1), b3 + hstep, voffB); PG8_STAGE(PG8_SA(1, 0), a3, voffA);
;             PG8_WAIT_V(8); PG8_WAIT_L(0); PG8_BAR; PG8_MMA(1, 0, At, B0); PG8_MMA(1, 1, At, B1); PG8_BAR; PG8_SCHED;
	s_add_i32 s57, 0, 0x18000
	s_add_i32 s58, 0, 0x1c000
	v_add_u32_e32 v156, s57, v167
	v_add_u32_e32 v180, s58, v167
	ds_read_b128 v[144:147], v156
	ds_read_b128 v[148:151], v156 offset:1024
	ds_read_b128 v[152:155], v156 offset:2048
	ds_read_b128 v[156:159], v156 offset:3072
	ds_read_b128 v[160:163], v180
	ds_read_b128 v[172:175], v180 offset:1024
	ds_read_b128 v[176:179], v180 offset:2048
	ds_read_b128 v[180:183], v180 offset:3072
	s_add_u32 s24, s30, 0x160000
	s_addc_u32 s25, s31, 0
	s_mov_b32 m0, s40
	ds_read_b128 v[184:187], v171 offset:32768
	ds_read_b128 v[188:191], v171 offset:33792
	ds_read_b128 v[192:195], v171 offset:34816
	ds_read_b128 v[196:199], v171 offset:35840
	ds_read_b128 v[200:203], v171 offset:36864
	ds_read_b128 v[204:207], v171 offset:37888
	ds_read_b128 v[208:211], v171 offset:38912
	ds_read_b128 v[212:215], v171 offset:39936
	global_load_lds_dwordx4 v128, s[24:25]
	s_mov_b32 m0, s41
	s_nop 0
	global_load_lds_dwordx4 v132, s[24:25]
	s_waitcnt vmcnt(8)
	s_waitcnt lgkmcnt(0)
	s_barrier
	v_mfma_f32_16x16x32_bf16 v[124:127], v[144:147], v[184:187], v[124:127]
	v_mfma_f32_16x16x32_bf16 v[120:123], v[152:155], v[184:187], v[120:123]
	v_mfma_f32_16x16x32_bf16 v[116:119], v[144:147], v[192:195], v[116:119]
	v_mfma_f32_16x16x32_bf16 v[112:115], v[152:155], v[192:195], v[112:115]
	v_mfma_f32_16x16x32_bf16 v[108:111], v[144:147], v[200:203], v[108:111]
	v_mfma_f32_16x16x32_bf16 v[96:99], v[152:155], v[200:203], v[96:99]
	v_mfma_f32_16x16x32_bf16 v[84:87], v[144:147], v[208:211], v[84:87]
	v_mfma_f32_16x16x32_bf16 v[76:79], v[152:155], v[208:211], v[76:79]
	v_mfma_f32_16x16x32_bf16 v[124:127], v[148:151], v[188:191], v[124:127]
	v_mfma_f32_16x16x32_bf16 v[120:123], v[156:159], v[188:191], v[120:123]
	v_mfma_f32_16x16x32_bf16 v[116:119], v[148:151], v[196:199], v[116:119]
	v_mfma_f32_16x16x32_bf16 v[112:115], v[156:159], v[196:199], v[112:115]
	v_mfma_f32_16x16x32_bf16 v[108:111], v[148:151], v[204:207], v[108:111]
	v_mfma_f32_16x16x32_bf16 v[96:99], v[156:159], v[204:207], v[96:99]
	v_mfma_f32_16x16x32_bf16 v[84:87], v[148:151], v[212:215], v[84:87]
	v_mfma_f32_16x16x32_bf16 v[76:79], v[156:159], v[212:215], v[76:79]
	v_mfma_f32_16x16x32_bf16 v[104:107], v[160:163], v[184:187], v[104:107]
	v_mfma_f32_16x16x32_bf16 v[100:103], v[176:179], v[184:187], v[100:103]
	v_mfma_f32_16x16x32_bf16 v[92:95], v[160:163], v[192:195], v[92:95]
	v_mfma_f32_16x16x32_bf16 v[88:91], v[176:179], v[192:195], v[88:91]
	v_mfma_f32_16x16x32_bf16 v[80:83], v[160:163], v[200:203], v[80:83]
	v_mfma_f32_16x16x32_bf16 v[72:75], v[176:179], v[200:203], v[72:75]
	v_mfma_f32_16x16x32_bf16 v[68:71], v[160:163], v[208:211], v[68:71]
	v_mfma_f32_16x16x32_bf16 v[64:67], v[176:179], v[208:211], v[64:67]
	v_mfma_f32_16x16x32_bf16 v[104:107], v[172:175], v[188:191], v[104:107]
	v_mfma_f32_16x16x32_bf16 v[100:103], v[180:183], v[188:191], v[100:103]
	v_mfma_f32_16x16x32_bf16 v[92:95], v[172:175], v[196:199], v[92:95]
	v_mfma_f32_16x16x32_bf16 v[88:91], v[180:183], v[196:199], v[88:91]
	v_mfma_f32_16x16x32_bf16 v[80:83], v[172:175], v[204:207], v[80:83]
	v_mfma_f32_16x16x32_bf16 v[72:75], v[180:183], v[204:207], v[72:75]
	v_mfma_f32_16x16x32_bf16 v[68:71], v[172:175], v[212:215], v[68:71]
	v_mfma_f32_16x16x32_bf16 v[64:67], v[180:183], v[212:215], v[64:67]
	s_barrier
	s_add_i32 s24, s57, s37
	s_add_u32 s86, s28, 0x80
	s_addc_u32 s87, s29, 0
	s_mov_b32 m0, s24
	ds_read_b128 v[184:187], v171 offset:49152
	ds_read_b128 v[188:191], v171 offset:50176
	ds_read_b128 v[192:195], v171 offset:51200
	ds_read_b128 v[196:199], v171 offset:52224
	ds_read_b128 v[200:203], v171 offset:53248
	ds_read_b128 v[204:207], v171 offset:54272
	ds_read_b128 v[208:211], v171 offset:55296
	ds_read_b128 v[212:215], v171 offset:56320
	global_load_lds_dwordx4 v130, s[86:87]
	s_add_i32 m0, s24, 0x2000
	s_add_u32 s24, s28, 0x160080
	s_addc_u32 s25, s29, 0
	s_add_i32 s28, s58, s37
	global_load_lds_dwordx4 v134, s[86:87]
	s_mov_b32 m0, s28
	s_nop 0
	global_load_lds_dwordx4 v130, s[24:25]
	s_add_i32 m0, s28, 0x2000
	s_nop 0
	global_load_lds_dwordx4 v134, s[24:25]
	s_add_u32 s84, s30, 0x80
	s_addc_u32 s85, s31, 0
	s_mov_b32 m0, s45
	s_nop 0
	global_load_lds_dwordx4 v128, s[84:85]
	s_mov_b32 m0, s46
	s_nop 0
	global_load_lds_dwordx4 v132, s[84:85]
	s_waitcnt vmcnt(8)
	s_waitcnt lgkmcnt(0)
	s_barrier
	v_mfma_f32_16x16x32_bf16 v[60:63], v[144:147], v[184:187], v[60:63]
	v_mfma_f32_16x16x32_bf16 v[56:59], v[152:155], v[184:187], v[56:59]
	v_mfma_f32_16x16x32_bf16 v[52:55], v[144:147], v[192:195], v[52:55]
	v_mfma_f32_16x16x32_bf16 v[48:51], v[152:155], v[192:195], v[48:51]
	v_mfma_f32_16x16x32_bf16 v[44:47], v[144:147], v[200:203], v[44:47]
	v_mfma_f32_16x16x32_bf16 v[32:35], v[152:155], v[200:203], v[32:35]
	v_mfma_f32_16x16x32_bf16 v[20:23], v[144:147], v[208:211], v[20:23]
	v_mfma_f32_16x16x32_bf16 v[12:15], v[152:155], v[208:211], v[12:15]
	v_mfma_f32_16x16x32_bf16 v[60:63], v[148:151], v[188:191], v[60:63]
	v_mfma_f32_16x16x32_bf16 v[56:59], v[156:159], v[188:191], v[56:59]
	v_mfma_f32_16x16x32_bf16 v[52:55], v[148:151], v[196:199], v[52:55]
	v_mfma_f32_16x16x32_bf16 v[48:51], v[156:159], v[196:199], v[48:51]
	v_mfma_f32_16x16x32_bf16 v[44:47], v[148:151], v[204:207], v[44:47]
	v_mfma_f32_16x16x32_bf16 v[32:35], v[156:159], v[204:207], v[32:35]
	v_mfma_f32_16x16x32_bf16 v[20:23], v[148:151], v[212:215], v[20:23]
	v_mfma_f32_16x16x32_bf16 v[12:15], v[156:159], v[212:215], v[12:15]
	v_mfma_f32_16x16x32_bf16 v[40:43], v[160:163], v[184:187], v[40:43]
	v_mfma_f32_16x16x32_bf16 v[36:39], v[176:179], v[184:187], v[36:39]
	v_mfma_f32_16x16x32_bf16 v[28:31], v[160:163], v[192:195], v[28:31]
	v_mfma_f32_16x16x32_bf16 v[24:27], v[176:179], v[192:195], v[24:27]
	v_mfma_f32_16x16x32_bf16 v[16:19], v[160:163], v[200:203], v[16:19]
	v_mfma_f32_16x16x32_bf16 v[8:11], v[176:179], v[200:203], v[8:11]
	v_mfma_f32_16x16x32_bf16 v[4:7], v[160:163], v[208:211], v[4:7]
	v_mfma_f32_16x16x32_bf16 v[0:3], v[176:179], v[208:211], v[0:3]
	v_mfma_f32_16x16x32_bf16 v[40:43], v[172:175], v[188:191], v[40:43]
	v_mfma_f32_16x16x32_bf16 v[36:39], v[180:183], v[188:191], v[36:39]
	v_mfma_f32_16x16x32_bf16 v[28:31], v[172:175], v[196:199], v[28:31]
	v_mfma_f32_16x16x32_bf16 v[24:27], v[180:183], v[196:199], v[24:27]
	v_mfma_f32_16x16x32_bf16 v[16:19], v[172:175], v[204:207], v[16:19]
	v_mfma_f32_16x16x32_bf16 v[8:11], v[180:183], v[204:207], v[8:11]
	v_mfma_f32_16x16x32_bf16 v[4:7], v[172:175], v[212:215], v[4:7]
	v_mfma_f32_16x16x32_bf16 v[0:3], v[180:183], v[212:215], v[0:3]
	s_barrier
	s_add_i32 s56, s56, 2
	s_add_u32 s54, s54, 0x100
	s_addc_u32 s55, s55, 0
	s_cmpk_gt_u32 s56, 0x55
	s_mov_b64 s[24:25], s[26:27]
	.p2align	6
